# GEMM template A/B: the mid-segment s_setprio 0/1 flip pair inside each 32-MFMA segment removed (48 pairs), rest unchanged
# baseline (speedup 1.0000x reference)
; #define PG8_BAR __builtin_amdgcn_s_barrier()
; template <class Epi, class Sched>
; __device__ __forceinline__ void gemm_phase(LAS unsigned char* lds, const int K, const int lda, const int ldb, const Sched& S, const Epi& E) {
;     ...
;     Unit cur, nxt; int ui = 0;
;     if (!S.next(0, cur)) return;
;     f32x4 acc[2][2][4][2];
; #pragma unroll
;     for (int a = 0; a < 2; ++a)
; #pragma unroll
;         for (int b = 0; b < 2; ++b)
; #pragma unroll
;             for (int m = 0; m < 4; ++m)
; #pragma unroll
;                 for (int n = 0; n < 2; ++n) acc[a][b][m][n] = (f32x4){0.f, 0.f, 0.f, 0.f};
;     bf16x8 At[4][2], B0[2][2], B1[2][2];
;     const char* cA = S.aptr(cur); const char* cB = S.bptr(cur);
;     PG8_STAGE(PG8_SB(0, 0), cB, voffB); PG8_STAGE(PG8_SB(0, 1), cB + hB, voffB); PG8_STAGE(PG8_SA(0, 0), cA, voffA); PG8_STAGE(PG8_SA(0, 1), cA + hA, voffA);
;     if (wr == 1) PG8_BAR;
;     PG8_WAIT_V(2); PG8_BAR;
;     PG8_STAGE(PG8_SB(1, 0), cB + kstep, voffB); PG8_STAGE(PG8_SA(1, 0), cA + kstep, voffA); PG8_STAGE(PG8_SB(1, 1), cB + hB + kstep, voffB);
;     PG8_WAIT_V(6); PG8_BAR;
;     for (;;) {
;         const bool has_next = S.next(ui + 1, nxt);
;         const char* nA = has_next ? S.aptr(nxt) : cA; const char* nB = has_next ? S.bptr(nxt) : cB;
;         for (int t = 0; t < nt; t += 2) {
;             const bool last = (t == nt - 2);
;             const char* a1 = cA + (size_t)(t + 1) * kstep;
;             const char* a2 = last ? nA : cA + (size_t)(t + 2) * kstep; const char* b2 = last ? nB : cB + (size_t)(t + 2) * kstep;
;             const char* a3 = a2 + kstep; const char* b3 = b2 + kstep;
;             PG8_LDB(B0, 0, 0); PG8_LDB(B1, 0, 1); PG8_SCHED; PG8_LDA(At, 0, 0); PG8_STAGE(PG8_SA(1, 1), a1 + hA, voffA);
;             PG8_WAIT_V(8); PG8_WAIT_L(0); PG8_BAR; PG8_MMA(0, 0, At, B0); PG8_MMA(0, 1, At, B1); PG8_BAR; PG8_SCHED;
;             PG8_LDA(At, 0, 1); PG8_STAGE(PG8_SB(0, 0), b2, voffB); PG8_STAGE(PG8_SB(0, 1), b2 + hB, voffB); PG8_STAGE(PG8_SA(0, 0), a2, voffA);
;             PG8_WAIT_V(8); PG8_WAIT_L(0); PG8_BAR; PG8_MMA(1, 0, At, B0); PG8_MMA(1, 1, At, B1); PG8_BAR; PG8_SCHED;
;             PG8_LDB(B0, 1, 0); PG8_LDB(B1, 1, 1); PG8_SCHED; PG8_LDA(At, 1, 0); PG8_STAGE(PG8_SA(0, 1), a2 + hA, voffA);
;             PG8_WAIT_V(8); PG8_WAIT_L(0); PG8_BAR; PG8_MMA(0, 0, At, B0); PG8_MMA(0, 1, At, B1); PG8_BAR; PG8_SCHED;
.LBB0_209:
	ds_read_b128 v[174:177], v188
	ds_read_b128 v[178:181], v147
	ds_read_b128 v[190:193], v188 offset:2048
	ds_read_b128 v[194:197], v147 offset:2048
	ds_read_b128 v[198:201], v189
	ds_read_b128 v[202:205], v149
	ds_read_b128 v[206:209], v189 offset:2048
	ds_read_b128 v[210:213], v149 offset:2048
	s_add_u32 s49, s54, 0xfff80080
	s_addc_u32 s56, s55, -1
	s_cmp_eq_u32 s47, 28
	s_cselect_b32 s59, s7, s56
	s_cselect_b32 s58, s18, s49
	s_cselect_b32 s57, s19, s45
	s_cselect_b32 s56, s20, s43
	v_lshl_add_u64 v[182:183], s[54:55], 0, v[140:141]
	s_add_i32 m0, s1, 0xc000
	ds_read_b128 v[214:217], v163
	ds_read_b128 v[218:221], v145
	ds_read_b128 v[222:225], v163 offset:2048
	ds_read_b128 v[226:229], v145 offset:2048
	ds_read_b128 v[230:233], v163 offset:4096
	ds_read_b128 v[236:239], v145 offset:4096
	ds_read_b128 v[240:243], v163 offset:6144
	ds_read_b128 v[244:247], v145 offset:6144
	global_load_lds_dwordx4 v[182:183], off
	v_lshl_add_u64 v[182:183], s[54:55], 0, v[138:139]
	s_add_i32 m0, s1, 0xe000
	s_nop 0
	global_load_lds_dwordx4 v[182:183], off
	s_waitcnt vmcnt(8)
	s_waitcnt lgkmcnt(0)
	s_barrier
	s_setprio 1
	s_waitcnt lgkmcnt(0)
	v_mfma_f32_16x16x32_bf16 v[124:127], v[214:217], v[174:177], v[124:127]
	v_mfma_f32_16x16x32_bf16 v[120:123], v[214:217], v[190:193], v[120:123]
	v_mfma_f32_16x16x32_bf16 v[108:111], v[222:225], v[174:177], v[108:111]
	v_mfma_f32_16x16x32_bf16 v[104:107], v[222:225], v[190:193], v[104:107]
	v_mfma_f32_16x16x32_bf16 v[92:95], v[230:233], v[174:177], v[92:95]
	v_mfma_f32_16x16x32_bf16 v[88:91], v[230:233], v[190:193], v[88:91]
	v_mfma_f32_16x16x32_bf16 v[76:79], v[240:243], v[174:177], v[76:79]
	v_mfma_f32_16x16x32_bf16 v[72:75], v[240:243], v[190:193], v[72:75]
	v_mfma_f32_16x16x32_bf16 v[124:127], v[218:221], v[178:181], v[124:127]
	v_mfma_f32_16x16x32_bf16 v[120:123], v[218:221], v[194:197], v[120:123]
	v_mfma_f32_16x16x32_bf16 v[108:111], v[226:229], v[178:181], v[108:111]
	v_mfma_f32_16x16x32_bf16 v[104:107], v[226:229], v[194:197], v[104:107]
	v_mfma_f32_16x16x32_bf16 v[92:95], v[236:239], v[178:181], v[92:95]
	v_mfma_f32_16x16x32_bf16 v[88:91], v[236:239], v[194:197], v[88:91]
	v_mfma_f32_16x16x32_bf16 v[76:79], v[244:247], v[178:181], v[76:79]
	v_mfma_f32_16x16x32_bf16 v[72:75], v[244:247], v[194:197], v[72:75]
	v_mfma_f32_16x16x32_bf16 v[116:119], v[214:217], v[198:201], v[116:119]
	v_mfma_f32_16x16x32_bf16 v[112:115], v[214:217], v[206:209], v[112:115]
	v_mfma_f32_16x16x32_bf16 v[100:103], v[222:225], v[198:201], v[100:103]
	v_mfma_f32_16x16x32_bf16 v[96:99], v[222:225], v[206:209], v[96:99]
	v_mfma_f32_16x16x32_bf16 v[84:87], v[230:233], v[198:201], v[84:87]
	v_mfma_f32_16x16x32_bf16 v[80:83], v[230:233], v[206:209], v[80:83]
	v_mfma_f32_16x16x32_bf16 v[68:71], v[240:243], v[198:201], v[68:71]
	v_mfma_f32_16x16x32_bf16 v[64:67], v[240:243], v[206:209], v[64:67]
	v_mfma_f32_16x16x32_bf16 v[116:119], v[218:221], v[202:205], v[116:119]
	v_mfma_f32_16x16x32_bf16 v[112:115], v[218:221], v[210:213], v[112:115]
	v_mfma_f32_16x16x32_bf16 v[100:103], v[226:229], v[202:205], v[100:103]
	v_mfma_f32_16x16x32_bf16 v[96:99], v[226:229], v[210:213], v[96:99]
	v_mfma_f32_16x16x32_bf16 v[84:87], v[236:239], v[202:205], v[84:87]
	v_mfma_f32_16x16x32_bf16 v[80:83], v[236:239], v[210:213], v[80:83]
	v_mfma_f32_16x16x32_bf16 v[68:71], v[244:247], v[202:205], v[68:71]
	v_mfma_f32_16x16x32_bf16 v[64:67], v[244:247], v[210:213], v[64:67]
	s_setprio 0
	s_barrier
	s_add_i32 s49, s68, s2
	v_lshl_add_u64 v[182:183], s[56:57], 0, v[132:133]
	s_mov_b32 m0, s49
	ds_read_b128 v[214:217], v163 offset:16384
	ds_read_b128 v[218:221], v145 offset:16384
	ds_read_b128 v[222:225], v163 offset:18432
	ds_read_b128 v[226:229], v145 offset:18432
	ds_read_b128 v[230:233], v163 offset:20480
	ds_read_b128 v[236:239], v145 offset:20480
	ds_read_b128 v[240:243], v163 offset:22528
	ds_read_b128 v[244:247], v145 offset:22528
	global_load_lds_dwordx4 v[182:183], off
	s_add_i32 m0, s49, 0x2000
	s_add_u32 s60, s56, 0x80000
	v_lshl_add_u64 v[248:249], s[56:57], 0, v[128:129]
	s_addc_u32 s61, s57, 0
	s_add_i32 s49, s69, s2
	global_load_lds_dwordx4 v[248:249], off
	v_lshl_add_u64 v[250:251], s[60:61], 0, v[132:133]
	s_mov_b32 m0, s49
	v_lshl_add_u64 v[252:253], s[58:59], 0, v[130:131]
	global_load_lds_dwordx4 v[250:251], off
	v_lshl_add_u64 v[250:251], s[60:61], 0, v[128:129]
	s_add_i32 m0, s49, 0x2000
	s_nop 0
	global_load_lds_dwordx4 v[250:251], off
	v_lshl_add_u64 v[250:251], s[58:59], 0, v[134:135]
	s_mov_b32 m0, s1
	s_nop 0
	global_load_lds_dwordx4 v[250:251], off
	s_mov_b32 m0, s17
	s_nop 0
	global_load_lds_dwordx4 v[252:253], off
	s_waitcnt vmcnt(8)
	s_waitcnt lgkmcnt(0)
	s_barrier
; #define PG8_BAR __builtin_amdgcn_s_barrier()
; template <class Epi, class Sched>
; __device__ __forceinline__ void gemm_phase(LAS unsigned char* lds, const int K, const int lda, const int ldb, const Sched& S, const Epi& E) {
;     ...
;     Unit cur, nxt; int ui = 0;
;     if (!S.next(0, cur)) return;
;     f32x4 acc[2][2][4][2];
; #pragma unroll
;     for (int a = 0; a < 2; ++a)
; #pragma unroll
;         for (int b = 0; b < 2; ++b)
; #pragma unroll
;             for (int m = 0; m < 4; ++m)
; #pragma unroll
;                 for (int n = 0; n < 2; ++n) acc[a][b][m][n] = (f32x4){0.f, 0.f, 0.f, 0.f};
;     bf16x8 At[4][2], B0[2][2], B1[2][2];
;     const char* cA = S.aptr(cur); const char* cB = S.bptr(cur);
;     PG8_STAGE(PG8_SB(0, 0), cB, voffB); PG8_STAGE(PG8_SB(0, 1), cB + hB, voffB); PG8_STAGE(PG8_SA(0, 0), cA, voffA); PG8_STAGE(PG8_SA(0, 1), cA + hA, voffA);
;     if (wr == 1) PG8_BAR;
;     PG8_WAIT_V(2); PG8_BAR;
;     PG8_STAGE(PG8_SB(1, 0), cB + kstep, voffB); PG8_STAGE(PG8_SA(1, 0), cA + kstep, voffA); PG8_STAGE(PG8_SB(1, 1), cB + hB + kstep, voffB);
;     PG8_WAIT_V(6); PG8_BAR;
;     for (;;) {
;         const bool has_next = S.next(ui + 1, nxt);
;         const char* nA = has_next ? S.aptr(nxt) : cA; const char* nB = has_next ? S.bptr(nxt) : cB;
;         for (int t = 0; t < nt; t += 2) {
;             const bool last = (t == nt - 2);
;             const char* a1 = cA + (size_t)(t + 1) * kstep;
;             const char* a2 = last ? nA : cA + (size_t)(t + 2) * kstep; const char* b2 = last ? nB : cB + (size_t)(t + 2) * kstep;
;             const char* a3 = a2 + kstep; const char* b3 = b2 + kstep;
;             PG8_LDB(B0, 0, 0); PG8_LDB(B1, 0, 1); PG8_SCHED; PG8_LDA(At, 0, 0); PG8_STAGE(PG8_SA(1, 1), a1 + hA, voffA);
;             PG8_WAIT_V(8); PG8_WAIT_L(0); PG8_BAR; PG8_MMA(0, 0, At, B0); PG8_MMA(0, 1, At, B1); PG8_BAR; PG8_SCHED;
;             PG8_LDA(At, 0, 1); PG8_STAGE(PG8_SB(0, 0), b2, voffB); PG8_STAGE(PG8_SB(0, 1), b2 + hB, voffB); PG8_STAGE(PG8_SA(0, 0), a2, voffA);
;             PG8_WAIT_V(8); PG8_WAIT_L(0); PG8_BAR; PG8_MMA(1, 0, At, B0); PG8_MMA(1, 1, At, B1); PG8_BAR; PG8_SCHED;
;             PG8_LDB(B0, 1, 0); PG8_LDB(B1, 1, 1); PG8_SCHED; PG8_LDA(At, 1, 0); PG8_STAGE(PG8_SA(0, 1), a2 + hA, voffA);
;             PG8_WAIT_V(8); PG8_WAIT_L(0); PG8_BAR; PG8_MMA(0, 0, At, B0); PG8_MMA(0, 1, At, B1); PG8_BAR; PG8_SCHED;
	s_setprio 1
	s_waitcnt lgkmcnt(0)
	v_mfma_f32_16x16x32_bf16 v[60:63], v[214:217], v[174:177], v[60:63]
	v_mfma_f32_16x16x32_bf16 v[56:59], v[214:217], v[190:193], v[56:59]
	v_mfma_f32_16x16x32_bf16 v[44:47], v[222:225], v[174:177], v[44:47]
	v_mfma_f32_16x16x32_bf16 v[40:43], v[222:225], v[190:193], v[40:43]
	v_mfma_f32_16x16x32_bf16 v[28:31], v[230:233], v[174:177], v[28:31]
	v_mfma_f32_16x16x32_bf16 v[24:27], v[230:233], v[190:193], v[24:27]
	v_mfma_f32_16x16x32_bf16 v[12:15], v[240:243], v[174:177], v[12:15]
	v_mfma_f32_16x16x32_bf16 v[8:11], v[240:243], v[190:193], v[8:11]
	v_mfma_f32_16x16x32_bf16 v[60:63], v[218:221], v[178:181], v[60:63]
	v_mfma_f32_16x16x32_bf16 v[56:59], v[218:221], v[194:197], v[56:59]
	v_mfma_f32_16x16x32_bf16 v[44:47], v[226:229], v[178:181], v[44:47]
	v_mfma_f32_16x16x32_bf16 v[40:43], v[226:229], v[194:197], v[40:43]
	v_mfma_f32_16x16x32_bf16 v[28:31], v[236:239], v[178:181], v[28:31]
	v_mfma_f32_16x16x32_bf16 v[24:27], v[236:239], v[194:197], v[24:27]
	v_mfma_f32_16x16x32_bf16 v[12:15], v[244:247], v[178:181], v[12:15]
	v_mfma_f32_16x16x32_bf16 v[8:11], v[244:247], v[194:197], v[8:11]
	v_mfma_f32_16x16x32_bf16 v[52:55], v[214:217], v[198:201], v[52:55]
	v_mfma_f32_16x16x32_bf16 v[48:51], v[214:217], v[206:209], v[48:51]
	v_mfma_f32_16x16x32_bf16 v[36:39], v[222:225], v[198:201], v[36:39]
	v_mfma_f32_16x16x32_bf16 v[32:35], v[222:225], v[206:209], v[32:35]
	v_mfma_f32_16x16x32_bf16 v[20:23], v[230:233], v[198:201], v[20:23]
	v_mfma_f32_16x16x32_bf16 v[16:19], v[230:233], v[206:209], v[16:19]
	v_mfma_f32_16x16x32_bf16 v[4:7], v[240:243], v[198:201], v[4:7]
	v_mfma_f32_16x16x32_bf16 v[0:3], v[240:243], v[206:209], v[0:3]
	v_mfma_f32_16x16x32_bf16 v[52:55], v[218:221], v[202:205], v[52:55]
	v_mfma_f32_16x16x32_bf16 v[48:51], v[218:221], v[210:213], v[48:51]
	v_mfma_f32_16x16x32_bf16 v[36:39], v[226:229], v[202:205], v[36:39]
	v_mfma_f32_16x16x32_bf16 v[32:35], v[226:229], v[210:213], v[32:35]
	v_mfma_f32_16x16x32_bf16 v[20:23], v[236:239], v[202:205], v[20:23]
	v_mfma_f32_16x16x32_bf16 v[16:19], v[236:239], v[210:213], v[16:19]
	v_mfma_f32_16x16x32_bf16 v[4:7], v[244:247], v[202:205], v[4:7]
	v_mfma_f32_16x16x32_bf16 v[0:3], v[244:247], v[210:213], v[0:3]
	s_setprio 0
	s_barrier
	s_add_i32 s49, 0, 0x18000
	v_add_u32_e32 v143, s49, v161
	v_add_u32_e32 v158, s49, v151
	s_add_i32 s60, 0, 0x1c000
	ds_read_b128 v[174:177], v143
	ds_read_b128 v[178:181], v158
	ds_read_b128 v[190:193], v143 offset:2048
	ds_read_b128 v[194:197], v158 offset:2048
	v_add_u32_e32 v143, 0x19000, v161
	v_add_u32_e32 v158, 0x19000, v151
	ds_read_b128 v[198:201], v143
	ds_read_b128 v[202:205], v158
	ds_read_b128 v[206:209], v143 offset:2048
	ds_read_b128 v[210:213], v158 offset:2048
	s_add_u32 s58, s58, 0x80000
	s_addc_u32 s59, s59, 0
	s_mov_b32 m0, s29
	v_lshl_add_u64 v[234:235], s[58:59], 0, v[134:135]
	ds_read_b128 v[214:217], v163 offset:32768
	ds_read_b128 v[218:221], v145 offset:32768
	ds_read_b128 v[222:225], v163 offset:34816
	ds_read_b128 v[226:229], v145 offset:34816
	ds_read_b128 v[230:233], v163 offset:36864
	ds_read_b128 v[236:239], v145 offset:36864
	ds_read_b128 v[240:243], v163 offset:38912
	ds_read_b128 v[244:247], v145 offset:38912
	global_load_lds_dwordx4 v[234:235], off
	v_lshl_add_u64 v[234:235], s[58:59], 0, v[130:131]
	s_mov_b32 m0, s34
	s_nop 0
	global_load_lds_dwordx4 v[234:235], off
	s_waitcnt vmcnt(8)
	s_waitcnt lgkmcnt(0)
	s_barrier
	s_setprio 1
	s_waitcnt lgkmcnt(0)
	v_mfma_f32_16x16x32_bf16 v[124:127], v[214:217], v[174:177], v[124:127]
	v_mfma_f32_16x16x32_bf16 v[120:123], v[214:217], v[190:193], v[120:123]
	v_mfma_f32_16x16x32_bf16 v[108:111], v[222:225], v[174:177], v[108:111]
	v_mfma_f32_16x16x32_bf16 v[104:107], v[222:225], v[190:193], v[104:107]
	v_mfma_f32_16x16x32_bf16 v[92:95], v[230:233], v[174:177], v[92:95]
	v_mfma_f32_16x16x32_bf16 v[88:91], v[230:233], v[190:193], v[88:91]
	v_mfma_f32_16x16x32_bf16 v[76:79], v[240:243], v[174:177], v[76:79]
	v_mfma_f32_16x16x32_bf16 v[72:75], v[240:243], v[190:193], v[72:75]
	v_mfma_f32_16x16x32_bf16 v[124:127], v[218:221], v[178:181], v[124:127]
	v_mfma_f32_16x16x32_bf16 v[120:123], v[218:221], v[194:197], v[120:123]
	v_mfma_f32_16x16x32_bf16 v[108:111], v[226:229], v[178:181], v[108:111]
	v_mfma_f32_16x16x32_bf16 v[104:107], v[226:229], v[194:197], v[104:107]
	v_mfma_f32_16x16x32_bf16 v[92:95], v[236:239], v[178:181], v[92:95]
	v_mfma_f32_16x16x32_bf16 v[88:91], v[236:239], v[194:197], v[88:91]
	v_mfma_f32_16x16x32_bf16 v[76:79], v[244:247], v[178:181], v[76:79]
	v_mfma_f32_16x16x32_bf16 v[72:75], v[244:247], v[194:197], v[72:75]
	v_mfma_f32_16x16x32_bf16 v[116:119], v[214:217], v[198:201], v[116:119]
	v_mfma_f32_16x16x32_bf16 v[112:115], v[214:217], v[206:209], v[112:115]
	v_mfma_f32_16x16x32_bf16 v[100:103], v[222:225], v[198:201], v[100:103]
	v_mfma_f32_16x16x32_bf16 v[96:99], v[222:225], v[206:209], v[96:99]
	v_mfma_f32_16x16x32_bf16 v[84:87], v[230:233], v[198:201], v[84:87]
	v_mfma_f32_16x16x32_bf16 v[80:83], v[230:233], v[206:209], v[80:83]
	v_mfma_f32_16x16x32_bf16 v[68:71], v[240:243], v[198:201], v[68:71]
	v_mfma_f32_16x16x32_bf16 v[64:67], v[240:243], v[206:209], v[64:67]
	v_mfma_f32_16x16x32_bf16 v[116:119], v[218:221], v[202:205], v[116:119]
	v_mfma_f32_16x16x32_bf16 v[112:115], v[218:221], v[210:213], v[112:115]
	v_mfma_f32_16x16x32_bf16 v[100:103], v[226:229], v[202:205], v[100:103]
	v_mfma_f32_16x16x32_bf16 v[96:99], v[226:229], v[210:213], v[96:99]
	v_mfma_f32_16x16x32_bf16 v[84:87], v[236:239], v[202:205], v[84:87]
	v_mfma_f32_16x16x32_bf16 v[80:83], v[236:239], v[210:213], v[80:83]
	v_mfma_f32_16x16x32_bf16 v[68:71], v[244:247], v[202:205], v[68:71]
	v_mfma_f32_16x16x32_bf16 v[64:67], v[244:247], v[210:213], v[64:67]
	s_setprio 0
	s_barrier
; #define PG8_STAGE(bufoff, gbase, voff) do { _Pragma("unroll") for (int _i = 0; _i < 2; ++_i) \
;         __builtin_amdgcn_global_load_lds((const unsigned*)((const char*)(gbase) + (voff)[_i]), (LAS unsigned*)(lds + (bufoff) + ldsw + _i * 8192), 16, 0, 0); } while (0)
; #define PG8_LDA(dst, b, h) do { _Pragma("unroll") for (int m = 0; m < 4; ++m) _Pragma("unroll") for (int k = 0; k < 2; ++k) dst[m][k] = *(const LAS bf16x8*)(lds + PG8_SA(b, h) + aoff + m * 2048 + k * 1024); } while (0)
; #define PG8_LDB(dst, b, h) do { _Pragma("unroll") for (int n = 0; n < 2; ++n) _Pragma("unroll") for (int k = 0; k < 2; ++k) dst[n][k] = *(const LAS bf16x8*)(lds + PG8_SB(b, h) + boff + n * 2048 + k * 1024); } while (0)
; #define PG8_WAIT_V(n) asm volatile("s_waitcnt vmcnt(" #n ")" ::: "memory")
; template <class Epi, class Sched>
; __device__ __forceinline__ void gemm_phase(LAS unsigned char* lds, const int K, const int lda, const int ldb, const Sched& S, const Epi& E) {
;     ...
;         for (int t = 0; t < nt; t += 2) {
;             const bool last = (t == nt - 2);
;             const char* a1 = cA + (size_t)(t + 1) * kstep;
;             const char* a2 = last ? nA : cA + (size_t)(t + 2) * kstep; const char* b2 = last ? nB : cB + (size_t)(t + 2) * kstep;
;             const char* a3 = a2 + kstep; const char* b3 = b2 + kstep;
;             PG8_LDB(B0, 0, 0); PG8_LDB(B1, 0, 1); PG8_SCHED; PG8_LDA(At, 0, 0); PG8_STAGE(PG8_SA(1, 1), a1 + hA, voffA);
;             PG8_WAIT_V(8); PG8_WAIT_L(0); PG8_BAR; PG8_MMA(0, 0, At, B0); PG8_MMA(0, 1, At, B1); PG8_BAR; PG8_SCHED;
;             PG8_LDA(At, 0, 1); PG8_STAGE(PG8_SB(0, 0), b2, voffB); PG8_STAGE(PG8_SB(0, 1), b2 + hB, voffB); PG8_STAGE(PG8_SA(0, 0), a2, voffA);
;             PG8_WAIT_V(8); PG8_WAIT_L(0); PG8_BAR; PG8_MMA(1, 0, At, B0); PG8_MMA(1, 1, At, B1); PG8_BAR; PG8_SCHED;
;             PG8_LDB(B0, 1, 0); PG8_LDB(B1, 1, 1); PG8_SCHED; PG8_LDA(At, 1, 0); PG8_STAGE(PG8_SA(0, 1), a2 + hA, voffA);
;             PG8_WAIT_V(8); PG8_WAIT_L(0); PG8_BAR; PG8_MMA(0, 0, At, B0); PG8_MMA(0, 1, At, B1); PG8_BAR; PG8_SCHED;
;             PG8_LDA(At, 1, 1); PG8_STAGE(PG8_SB(1, 0), b3, voffB); PG8_STAGE(PG8_SB(1, 1), b3 + hB, voffB); PG8_STAGE(PG8_SA(1, 0), a3, voffA);
;             PG8_WAIT_V(8); PG8_WAIT_L(0); PG8_BAR; PG8_MMA(1, 0, At, B0); PG8_MMA(1, 1, At, B1); PG8_BAR; PG8_SCHED;
;         }
;         if (wr == 0) PG8_BAR;
	s_add_i32 s49, s49, s2
	v_lshl_add_u64 v[182:183], v[182:183], 0, s[22:23]
	s_mov_b32 m0, s49
	ds_read_b128 v[214:217], v163 offset:49152
	ds_read_b128 v[218:221], v145 offset:49152
	ds_read_b128 v[222:225], v163 offset:51200
	ds_read_b128 v[226:229], v145 offset:51200
	ds_read_b128 v[230:233], v163 offset:53248
	ds_read_b128 v[236:239], v145 offset:53248
	ds_read_b128 v[240:243], v163 offset:55296
	ds_read_b128 v[244:247], v145 offset:55296
	global_load_lds_dwordx4 v[182:183], off
	s_add_i32 m0, s49, 0x2000
	s_add_u32 s56, s56, 0x80080
	v_lshl_add_u64 v[182:183], v[248:249], 0, s[22:23]
	s_addc_u32 s57, s57, 0
	s_add_i32 s49, s60, s2
	global_load_lds_dwordx4 v[182:183], off
	v_lshl_add_u64 v[182:183], s[56:57], 0, v[132:133]
	s_mov_b32 m0, s49
	s_nop 0
	global_load_lds_dwordx4 v[182:183], off
	v_lshl_add_u64 v[182:183], s[56:57], 0, v[128:129]
	s_add_i32 m0, s49, 0x2000
	s_nop 0
	global_load_lds_dwordx4 v[182:183], off
	v_lshl_add_u64 v[182:183], v[250:251], 0, s[22:23]
	s_mov_b32 m0, s38
	s_nop 0
	global_load_lds_dwordx4 v[182:183], off
	v_lshl_add_u64 v[182:183], v[252:253], 0, s[22:23]
	s_mov_b32 m0, s39
	s_nop 0
	global_load_lds_dwordx4 v[182:183], off
	s_waitcnt vmcnt(8)
	s_waitcnt lgkmcnt(0)
	s_barrier
	s_setprio 1
	s_waitcnt lgkmcnt(0)
	v_mfma_f32_16x16x32_bf16 v[60:63], v[214:217], v[174:177], v[60:63]
	v_mfma_f32_16x16x32_bf16 v[56:59], v[214:217], v[190:193], v[56:59]
	v_mfma_f32_16x16x32_bf16 v[44:47], v[222:225], v[174:177], v[44:47]
	v_mfma_f32_16x16x32_bf16 v[40:43], v[222:225], v[190:193], v[40:43]
	v_mfma_f32_16x16x32_bf16 v[28:31], v[230:233], v[174:177], v[28:31]
	v_mfma_f32_16x16x32_bf16 v[24:27], v[230:233], v[190:193], v[24:27]
	v_mfma_f32_16x16x32_bf16 v[12:15], v[240:243], v[174:177], v[12:15]
	v_mfma_f32_16x16x32_bf16 v[8:11], v[240:243], v[190:193], v[8:11]
	v_mfma_f32_16x16x32_bf16 v[60:63], v[218:221], v[178:181], v[60:63]
	v_mfma_f32_16x16x32_bf16 v[56:59], v[218:221], v[194:197], v[56:59]
	v_mfma_f32_16x16x32_bf16 v[44:47], v[226:229], v[178:181], v[44:47]
	v_mfma_f32_16x16x32_bf16 v[40:43], v[226:229], v[194:197], v[40:43]
	v_mfma_f32_16x16x32_bf16 v[28:31], v[236:239], v[178:181], v[28:31]
	v_mfma_f32_16x16x32_bf16 v[24:27], v[236:239], v[194:197], v[24:27]
	v_mfma_f32_16x16x32_bf16 v[12:15], v[244:247], v[178:181], v[12:15]
	v_mfma_f32_16x16x32_bf16 v[8:11], v[244:247], v[194:197], v[8:11]
	v_mfma_f32_16x16x32_bf16 v[52:55], v[214:217], v[198:201], v[52:55]
	v_mfma_f32_16x16x32_bf16 v[48:51], v[214:217], v[206:209], v[48:51]
	v_mfma_f32_16x16x32_bf16 v[36:39], v[222:225], v[198:201], v[36:39]
	v_mfma_f32_16x16x32_bf16 v[32:35], v[222:225], v[206:209], v[32:35]
	v_mfma_f32_16x16x32_bf16 v[20:23], v[230:233], v[198:201], v[20:23]
	v_mfma_f32_16x16x32_bf16 v[16:19], v[230:233], v[206:209], v[16:19]
	v_mfma_f32_16x16x32_bf16 v[4:7], v[240:243], v[198:201], v[4:7]
	v_mfma_f32_16x16x32_bf16 v[0:3], v[240:243], v[206:209], v[0:3]
	v_mfma_f32_16x16x32_bf16 v[52:55], v[218:221], v[202:205], v[52:55]
	v_mfma_f32_16x16x32_bf16 v[48:51], v[218:221], v[210:213], v[48:51]
	v_mfma_f32_16x16x32_bf16 v[36:39], v[226:229], v[202:205], v[36:39]
	v_mfma_f32_16x16x32_bf16 v[32:35], v[226:229], v[210:213], v[32:35]
	v_mfma_f32_16x16x32_bf16 v[20:23], v[236:239], v[202:205], v[20:23]
	v_mfma_f32_16x16x32_bf16 v[16:19], v[236:239], v[210:213], v[16:19]
	v_mfma_f32_16x16x32_bf16 v[4:7], v[244:247], v[202:205], v[4:7]
	v_mfma_f32_16x16x32_bf16 v[0:3], v[244:247], v[210:213], v[0:3]
	s_setprio 0
	s_barrier
	s_add_i32 s47, s47, 2
	s_add_u32 s43, s43, 0x100
	s_addc_u32 s45, s45, 0
	s_add_u32 s54, s54, 0x100
	s_addc_u32 s55, s55, 0
	s_cmp_gt_u32 s47, 29
	s_cbranch_scc0 .LBB0_209
	s_and_b64 vcc, exec, s[24:25]
	s_cbranch_vccz .LBB0_212
	s_barrier

; #define PG8_BAR __builtin_amdgcn_s_barrier()
; template <class Epi, class Sched>
; __device__ __forceinline__ void gemm_phase(LAS unsigned char* lds, const int K, const int lda, const int ldb, const Sched& S, const Epi& E) {
;     ...
;     Unit cur, nxt; int ui = 0;
;     if (!S.next(0, cur)) return;
;     f32x4 acc[2][2][4][2];
; #pragma unroll
;     for (int a = 0; a < 2; ++a)
; #pragma unroll
;         for (int b = 0; b < 2; ++b)
; #pragma unroll
;             for (int m = 0; m < 4; ++m)
; #pragma unroll
;                 for (int n = 0; n < 2; ++n) acc[a][b][m][n] = (f32x4){0.f, 0.f, 0.f, 0.f};
;     bf16x8 At[4][2], B0[2][2], B1[2][2];
;     const char* cA = S.aptr(cur); const char* cB = S.bptr(cur);
;     PG8_STAGE(PG8_SB(0, 0), cB, voffB); PG8_STAGE(PG8_SB(0, 1), cB + hB, voffB); PG8_STAGE(PG8_SA(0, 0), cA, voffA); PG8_STAGE(PG8_SA(0, 1), cA + hA, voffA);
;     if (wr == 1) PG8_BAR;
;     PG8_WAIT_V(2); PG8_BAR;
;     PG8_STAGE(PG8_SB(1, 0), cB + kstep, voffB); PG8_STAGE(PG8_SA(1, 0), cA + kstep, voffA); PG8_STAGE(PG8_SB(1, 1), cB + hB + kstep, voffB);
;     PG8_WAIT_V(6); PG8_BAR;
;     for (;;) {
;         const bool has_next = S.next(ui + 1, nxt);
;         const char* nA = has_next ? S.aptr(nxt) : cA; const char* nB = has_next ? S.bptr(nxt) : cB;
;         for (int t = 0; t < nt; t += 2) {
;             const bool last = (t == nt - 2);
;             const char* a1 = cA + (size_t)(t + 1) * kstep;
;             const char* a2 = last ? nA : cA + (size_t)(t + 2) * kstep; const char* b2 = last ? nB : cB + (size_t)(t + 2) * kstep;
;             const char* a3 = a2 + kstep; const char* b3 = b2 + kstep;
;             PG8_LDB(B0, 0, 0); PG8_LDB(B1, 0, 1); PG8_SCHED; PG8_LDA(At, 0, 0); PG8_STAGE(PG8_SA(1, 1), a1 + hA, voffA);
;             PG8_WAIT_V(8); PG8_WAIT_L(0); PG8_BAR; PG8_MMA(0, 0, At, B0); PG8_MMA(0, 1, At, B1); PG8_BAR; PG8_SCHED;
;             PG8_LDA(At, 0, 1); PG8_STAGE(PG8_SB(0, 0), b2, voffB); PG8_STAGE(PG8_SB(0, 1), b2 + hB, voffB); PG8_STAGE(PG8_SA(0, 0), a2, voffA);
;             PG8_WAIT_V(8); PG8_WAIT_L(0); PG8_BAR; PG8_MMA(1, 0, At, B0); PG8_MMA(1, 1, At, B1); PG8_BAR; PG8_SCHED;
;             PG8_LDB(B0, 1, 0); PG8_LDB(B1, 1, 1); PG8_SCHED; PG8_LDA(At, 1, 0); PG8_STAGE(PG8_SA(0, 1), a2 + hA, voffA);
;             PG8_WAIT_V(8); PG8_WAIT_L(0); PG8_BAR; PG8_MMA(0, 0, At, B0); PG8_MMA(0, 1, At, B1); PG8_BAR; PG8_SCHED;
.LBB0_427:
	ds_read_b128 v[156:159], v151
	ds_read_b128 v[160:163], v151 offset:1024
	ds_read_b128 v[164:167], v151 offset:2048
	ds_read_b128 v[168:171], v151 offset:3072
	ds_read_b128 v[172:175], v152
	ds_read_b128 v[176:179], v152 offset:1024
	ds_read_b128 v[180:183], v152 offset:2048
	ds_read_b128 v[184:187], v152 offset:3072
	s_add_u32 s60, s8, 0xfff00080
	s_addc_u32 s61, s9, -1
	s_cmp_eq_u32 s78, 28
	s_cselect_b32 s63, s51, s61
	s_cselect_b32 s62, s50, s60
	s_cselect_b32 s61, s57, s59
	s_cselect_b32 s60, s56, s55
	v_lshl_add_u64 v[146:147], s[8:9], 0, v[140:141]
	s_add_i32 m0, s21, 0xc000
	ds_read_b128 v[188:191], v153
	ds_read_b128 v[192:195], v153 offset:1024
	ds_read_b128 v[196:199], v153 offset:2048
	ds_read_b128 v[200:203], v153 offset:3072
	ds_read_b128 v[204:207], v153 offset:4096
	ds_read_b128 v[208:211], v153 offset:5120
	ds_read_b128 v[212:215], v153 offset:6144
	ds_read_b128 v[216:219], v153 offset:7168
	global_load_lds_dwordx4 v[146:147], off
	v_lshl_add_u64 v[146:147], s[8:9], 0, v[138:139]
	s_add_i32 m0, s21, 0xe000
	s_nop 0
	global_load_lds_dwordx4 v[146:147], off
	s_waitcnt vmcnt(8)
	s_waitcnt lgkmcnt(0)
	s_barrier
	s_setprio 1
	s_waitcnt lgkmcnt(0)
	v_mfma_f32_16x16x32_bf16 v[124:127], v[156:159], v[188:191], v[124:127]
	v_mfma_f32_16x16x32_bf16 v[120:123], v[164:167], v[188:191], v[120:123]
	v_mfma_f32_16x16x32_bf16 v[108:111], v[156:159], v[196:199], v[108:111]
	v_mfma_f32_16x16x32_bf16 v[104:107], v[164:167], v[196:199], v[104:107]
	v_mfma_f32_16x16x32_bf16 v[92:95], v[156:159], v[204:207], v[92:95]
	v_mfma_f32_16x16x32_bf16 v[88:91], v[164:167], v[204:207], v[88:91]
	v_mfma_f32_16x16x32_bf16 v[76:79], v[156:159], v[212:215], v[76:79]
	v_mfma_f32_16x16x32_bf16 v[72:75], v[164:167], v[212:215], v[72:75]
	v_mfma_f32_16x16x32_bf16 v[124:127], v[160:163], v[192:195], v[124:127]
	v_mfma_f32_16x16x32_bf16 v[120:123], v[168:171], v[192:195], v[120:123]
	v_mfma_f32_16x16x32_bf16 v[108:111], v[160:163], v[200:203], v[108:111]
	v_mfma_f32_16x16x32_bf16 v[104:107], v[168:171], v[200:203], v[104:107]
	v_mfma_f32_16x16x32_bf16 v[92:95], v[160:163], v[208:211], v[92:95]
	v_mfma_f32_16x16x32_bf16 v[88:91], v[168:171], v[208:211], v[88:91]
	v_mfma_f32_16x16x32_bf16 v[76:79], v[160:163], v[216:219], v[76:79]
	v_mfma_f32_16x16x32_bf16 v[72:75], v[168:171], v[216:219], v[72:75]
	v_mfma_f32_16x16x32_bf16 v[116:119], v[172:175], v[188:191], v[116:119]
	v_mfma_f32_16x16x32_bf16 v[112:115], v[180:183], v[188:191], v[112:115]
	v_mfma_f32_16x16x32_bf16 v[100:103], v[172:175], v[196:199], v[100:103]
	v_mfma_f32_16x16x32_bf16 v[96:99], v[180:183], v[196:199], v[96:99]
	v_mfma_f32_16x16x32_bf16 v[84:87], v[172:175], v[204:207], v[84:87]
	v_mfma_f32_16x16x32_bf16 v[80:83], v[180:183], v[204:207], v[80:83]
	v_mfma_f32_16x16x32_bf16 v[68:71], v[172:175], v[212:215], v[68:71]
	v_mfma_f32_16x16x32_bf16 v[64:67], v[180:183], v[212:215], v[64:67]
	v_mfma_f32_16x16x32_bf16 v[116:119], v[176:179], v[192:195], v[116:119]
	v_mfma_f32_16x16x32_bf16 v[112:115], v[184:187], v[192:195], v[112:115]
	v_mfma_f32_16x16x32_bf16 v[100:103], v[176:179], v[200:203], v[100:103]
	v_mfma_f32_16x16x32_bf16 v[96:99], v[184:187], v[200:203], v[96:99]
	v_mfma_f32_16x16x32_bf16 v[84:87], v[176:179], v[208:211], v[84:87]
	v_mfma_f32_16x16x32_bf16 v[80:83], v[184:187], v[208:211], v[80:83]
	v_mfma_f32_16x16x32_bf16 v[68:71], v[176:179], v[216:219], v[68:71]
	v_mfma_f32_16x16x32_bf16 v[64:67], v[184:187], v[216:219], v[64:67]
	s_setprio 0
	s_barrier
	s_add_i32 s79, s0, s25
	v_lshl_add_u64 v[146:147], s[60:61], 0, v[132:133]
	s_mov_b32 m0, s79
	ds_read_b128 v[188:191], v153 offset:16384
	ds_read_b128 v[192:195], v153 offset:17408
	ds_read_b128 v[196:199], v153 offset:18432
	ds_read_b128 v[200:203], v153 offset:19456
	ds_read_b128 v[204:207], v153 offset:20480
	ds_read_b128 v[208:211], v153 offset:21504
	ds_read_b128 v[212:215], v153 offset:22528
	ds_read_b128 v[216:219], v153 offset:23552
	global_load_lds_dwordx4 v[146:147], off
	s_add_i32 m0, s79, 0x2000
	s_add_u32 s80, s60, 0x400000
	v_lshl_add_u64 v[220:221], s[60:61], 0, v[128:129]
	s_addc_u32 s81, s61, 0
	s_add_i32 s79, s64, s25
	global_load_lds_dwordx4 v[220:221], off
	v_lshl_add_u64 v[222:223], s[80:81], 0, v[132:133]
	s_mov_b32 m0, s79
	v_lshl_add_u64 v[224:225], s[62:63], 0, v[130:131]
	global_load_lds_dwordx4 v[222:223], off
	v_lshl_add_u64 v[222:223], s[80:81], 0, v[128:129]
	s_add_i32 m0, s79, 0x2000
	s_nop 0
	global_load_lds_dwordx4 v[222:223], off
	v_lshl_add_u64 v[222:223], s[62:63], 0, v[134:135]
	s_mov_b32 m0, s21
	s_nop 0
	global_load_lds_dwordx4 v[222:223], off
	s_mov_b32 m0, s22
	s_nop 0
	global_load_lds_dwordx4 v[224:225], off
	s_waitcnt vmcnt(8)
	s_waitcnt lgkmcnt(0)
	s_barrier
; #define PG8_BAR __builtin_amdgcn_s_barrier()
; template <class Epi, class Sched>
; __device__ __forceinline__ void gemm_phase(LAS unsigned char* lds, const int K, const int lda, const int ldb, const Sched& S, const Epi& E) {
;     ...
;     Unit cur, nxt; int ui = 0;
;     if (!S.next(0, cur)) return;
;     f32x4 acc[2][2][4][2];
; #pragma unroll
;     for (int a = 0; a < 2; ++a)
; #pragma unroll
;         for (int b = 0; b < 2; ++b)
; #pragma unroll
;             for (int m = 0; m < 4; ++m)
; #pragma unroll
;                 for (int n = 0; n < 2; ++n) acc[a][b][m][n] = (f32x4){0.f, 0.f, 0.f, 0.f};
;     bf16x8 At[4][2], B0[2][2], B1[2][2];
;     const char* cA = S.aptr(cur); const char* cB = S.bptr(cur);
;     PG8_STAGE(PG8_SB(0, 0), cB, voffB); PG8_STAGE(PG8_SB(0, 1), cB + hB, voffB); PG8_STAGE(PG8_SA(0, 0), cA, voffA); PG8_STAGE(PG8_SA(0, 1), cA + hA, voffA);
;     if (wr == 1) PG8_BAR;
;     PG8_WAIT_V(2); PG8_BAR;
;     PG8_STAGE(PG8_SB(1, 0), cB + kstep, voffB); PG8_STAGE(PG8_SA(1, 0), cA + kstep, voffA); PG8_STAGE(PG8_SB(1, 1), cB + hB + kstep, voffB);
;     PG8_WAIT_V(6); PG8_BAR;
;     for (;;) {
;         const bool has_next = S.next(ui + 1, nxt);
;         const char* nA = has_next ? S.aptr(nxt) : cA; const char* nB = has_next ? S.bptr(nxt) : cB;
;         for (int t = 0; t < nt; t += 2) {
;             const bool last = (t == nt - 2);
;             const char* a1 = cA + (size_t)(t + 1) * kstep;
;             const char* a2 = last ? nA : cA + (size_t)(t + 2) * kstep; const char* b2 = last ? nB : cB + (size_t)(t + 2) * kstep;
;             const char* a3 = a2 + kstep; const char* b3 = b2 + kstep;
;             PG8_LDB(B0, 0, 0); PG8_LDB(B1, 0, 1); PG8_SCHED; PG8_LDA(At, 0, 0); PG8_STAGE(PG8_SA(1, 1), a1 + hA, voffA);
;             PG8_WAIT_V(8); PG8_WAIT_L(0); PG8_BAR; PG8_MMA(0, 0, At, B0); PG8_MMA(0, 1, At, B1); PG8_BAR; PG8_SCHED;
;             PG8_LDA(At, 0, 1); PG8_STAGE(PG8_SB(0, 0), b2, voffB); PG8_STAGE(PG8_SB(0, 1), b2 + hB, voffB); PG8_STAGE(PG8_SA(0, 0), a2, voffA);
;             PG8_WAIT_V(8); PG8_WAIT_L(0); PG8_BAR; PG8_MMA(1, 0, At, B0); PG8_MMA(1, 1, At, B1); PG8_BAR; PG8_SCHED;
;             PG8_LDB(B0, 1, 0); PG8_LDB(B1, 1, 1); PG8_SCHED; PG8_LDA(At, 1, 0); PG8_STAGE(PG8_SA(0, 1), a2 + hA, voffA);
;             PG8_WAIT_V(8); PG8_WAIT_L(0); PG8_BAR; PG8_MMA(0, 0, At, B0); PG8_MMA(0, 1, At, B1); PG8_BAR; PG8_SCHED;
	s_setprio 1
	s_waitcnt lgkmcnt(0)
	v_mfma_f32_16x16x32_bf16 v[60:63], v[156:159], v[188:191], v[60:63]
	v_mfma_f32_16x16x32_bf16 v[56:59], v[164:167], v[188:191], v[56:59]
	v_mfma_f32_16x16x32_bf16 v[44:47], v[156:159], v[196:199], v[44:47]
	v_mfma_f32_16x16x32_bf16 v[40:43], v[164:167], v[196:199], v[40:43]
	v_mfma_f32_16x16x32_bf16 v[28:31], v[156:159], v[204:207], v[28:31]
	v_mfma_f32_16x16x32_bf16 v[24:27], v[164:167], v[204:207], v[24:27]
	v_mfma_f32_16x16x32_bf16 v[12:15], v[156:159], v[212:215], v[12:15]
	v_mfma_f32_16x16x32_bf16 v[8:11], v[164:167], v[212:215], v[8:11]
	v_mfma_f32_16x16x32_bf16 v[60:63], v[160:163], v[192:195], v[60:63]
	v_mfma_f32_16x16x32_bf16 v[56:59], v[168:171], v[192:195], v[56:59]
	v_mfma_f32_16x16x32_bf16 v[44:47], v[160:163], v[200:203], v[44:47]
	v_mfma_f32_16x16x32_bf16 v[40:43], v[168:171], v[200:203], v[40:43]
	v_mfma_f32_16x16x32_bf16 v[28:31], v[160:163], v[208:211], v[28:31]
	v_mfma_f32_16x16x32_bf16 v[24:27], v[168:171], v[208:211], v[24:27]
	v_mfma_f32_16x16x32_bf16 v[12:15], v[160:163], v[216:219], v[12:15]
	v_mfma_f32_16x16x32_bf16 v[8:11], v[168:171], v[216:219], v[8:11]
	v_mfma_f32_16x16x32_bf16 v[52:55], v[172:175], v[188:191], v[52:55]
	v_mfma_f32_16x16x32_bf16 v[48:51], v[180:183], v[188:191], v[48:51]
	v_mfma_f32_16x16x32_bf16 v[36:39], v[172:175], v[196:199], v[36:39]
	v_mfma_f32_16x16x32_bf16 v[32:35], v[180:183], v[196:199], v[32:35]
	v_mfma_f32_16x16x32_bf16 v[20:23], v[172:175], v[204:207], v[20:23]
	v_mfma_f32_16x16x32_bf16 v[16:19], v[180:183], v[204:207], v[16:19]
	v_mfma_f32_16x16x32_bf16 v[4:7], v[172:175], v[212:215], v[4:7]
	v_mfma_f32_16x16x32_bf16 v[0:3], v[180:183], v[212:215], v[0:3]
	v_mfma_f32_16x16x32_bf16 v[52:55], v[176:179], v[192:195], v[52:55]
	v_mfma_f32_16x16x32_bf16 v[48:51], v[184:187], v[192:195], v[48:51]
	v_mfma_f32_16x16x32_bf16 v[36:39], v[176:179], v[200:203], v[36:39]
	v_mfma_f32_16x16x32_bf16 v[32:35], v[184:187], v[200:203], v[32:35]
	v_mfma_f32_16x16x32_bf16 v[20:23], v[176:179], v[208:211], v[20:23]
	v_mfma_f32_16x16x32_bf16 v[16:19], v[184:187], v[208:211], v[16:19]
	v_mfma_f32_16x16x32_bf16 v[4:7], v[176:179], v[216:219], v[4:7]
	v_mfma_f32_16x16x32_bf16 v[0:3], v[184:187], v[216:219], v[0:3]
	s_setprio 0
	s_barrier
	s_add_i32 s79, 0, 0x18000
	v_add_u32_e32 v136, s79, v149
	s_add_i32 s80, 0, 0x1c000
	ds_read_b128 v[156:159], v136
	ds_read_b128 v[160:163], v136 offset:1024
	ds_read_b128 v[164:167], v136 offset:2048
	ds_read_b128 v[168:171], v136 offset:3072
	v_add_u32_e32 v136, s80, v149
	ds_read_b128 v[172:175], v136
	ds_read_b128 v[176:179], v136 offset:1024
	ds_read_b128 v[180:183], v136 offset:2048
	ds_read_b128 v[184:187], v136 offset:3072
	s_add_u32 s62, s62, 0x100000
	s_addc_u32 s63, s63, 0
	s_mov_b32 m0, s28
	v_lshl_add_u64 v[226:227], s[62:63], 0, v[134:135]
	ds_read_b128 v[188:191], v153 offset:32768
	ds_read_b128 v[192:195], v153 offset:33792
	ds_read_b128 v[196:199], v153 offset:34816
	ds_read_b128 v[200:203], v153 offset:35840
	ds_read_b128 v[204:207], v153 offset:36864
	ds_read_b128 v[208:211], v153 offset:37888
	ds_read_b128 v[212:215], v153 offset:38912
	ds_read_b128 v[216:219], v153 offset:39936
	global_load_lds_dwordx4 v[226:227], off
	v_lshl_add_u64 v[226:227], s[62:63], 0, v[130:131]
	s_mov_b32 m0, s29
	s_nop 0
	global_load_lds_dwordx4 v[226:227], off
	s_waitcnt vmcnt(8)
	s_waitcnt lgkmcnt(0)
	s_barrier
	s_setprio 1
	s_waitcnt lgkmcnt(0)
	v_mfma_f32_16x16x32_bf16 v[124:127], v[156:159], v[188:191], v[124:127]
	v_mfma_f32_16x16x32_bf16 v[120:123], v[164:167], v[188:191], v[120:123]
	v_mfma_f32_16x16x32_bf16 v[108:111], v[156:159], v[196:199], v[108:111]
	v_mfma_f32_16x16x32_bf16 v[104:107], v[164:167], v[196:199], v[104:107]
	v_mfma_f32_16x16x32_bf16 v[92:95], v[156:159], v[204:207], v[92:95]
	v_mfma_f32_16x16x32_bf16 v[88:91], v[164:167], v[204:207], v[88:91]
	v_mfma_f32_16x16x32_bf16 v[76:79], v[156:159], v[212:215], v[76:79]
	v_mfma_f32_16x16x32_bf16 v[72:75], v[164:167], v[212:215], v[72:75]
	v_mfma_f32_16x16x32_bf16 v[124:127], v[160:163], v[192:195], v[124:127]
	v_mfma_f32_16x16x32_bf16 v[120:123], v[168:171], v[192:195], v[120:123]
	v_mfma_f32_16x16x32_bf16 v[108:111], v[160:163], v[200:203], v[108:111]
	v_mfma_f32_16x16x32_bf16 v[104:107], v[168:171], v[200:203], v[104:107]
	v_mfma_f32_16x16x32_bf16 v[92:95], v[160:163], v[208:211], v[92:95]
	v_mfma_f32_16x16x32_bf16 v[88:91], v[168:171], v[208:211], v[88:91]
	v_mfma_f32_16x16x32_bf16 v[76:79], v[160:163], v[216:219], v[76:79]
	v_mfma_f32_16x16x32_bf16 v[72:75], v[168:171], v[216:219], v[72:75]
	v_mfma_f32_16x16x32_bf16 v[116:119], v[172:175], v[188:191], v[116:119]
	v_mfma_f32_16x16x32_bf16 v[112:115], v[180:183], v[188:191], v[112:115]
	v_mfma_f32_16x16x32_bf16 v[100:103], v[172:175], v[196:199], v[100:103]
	v_mfma_f32_16x16x32_bf16 v[96:99], v[180:183], v[196:199], v[96:99]
	v_mfma_f32_16x16x32_bf16 v[84:87], v[172:175], v[204:207], v[84:87]
	v_mfma_f32_16x16x32_bf16 v[80:83], v[180:183], v[204:207], v[80:83]
	v_mfma_f32_16x16x32_bf16 v[68:71], v[172:175], v[212:215], v[68:71]
	v_mfma_f32_16x16x32_bf16 v[64:67], v[180:183], v[212:215], v[64:67]
	v_mfma_f32_16x16x32_bf16 v[116:119], v[176:179], v[192:195], v[116:119]
	v_mfma_f32_16x16x32_bf16 v[112:115], v[184:187], v[192:195], v[112:115]
	v_mfma_f32_16x16x32_bf16 v[100:103], v[176:179], v[200:203], v[100:103]
	v_mfma_f32_16x16x32_bf16 v[96:99], v[184:187], v[200:203], v[96:99]
	v_mfma_f32_16x16x32_bf16 v[84:87], v[176:179], v[208:211], v[84:87]
	v_mfma_f32_16x16x32_bf16 v[80:83], v[184:187], v[208:211], v[80:83]
	v_mfma_f32_16x16x32_bf16 v[68:71], v[176:179], v[216:219], v[68:71]
	v_mfma_f32_16x16x32_bf16 v[64:67], v[184:187], v[216:219], v[64:67]
	s_setprio 0
	s_barrier
; #define PG8_STAGE(bufoff, gbase, voff) do { _Pragma("unroll") for (int _i = 0; _i < 2; ++_i) \
;         __builtin_amdgcn_global_load_lds((const unsigned*)((const char*)(gbase) + (voff)[_i]), (LAS unsigned*)(lds + (bufoff) + ldsw + _i * 8192), 16, 0, 0); } while (0)
; #define PG8_LDA(dst, b, h) do { _Pragma("unroll") for (int m = 0; m < 4; ++m) _Pragma("unroll") for (int k = 0; k < 2; ++k) dst[m][k] = *(const LAS bf16x8*)(lds + PG8_SA(b, h) + aoff + m * 2048 + k * 1024); } while (0)
; #define PG8_LDB(dst, b, h) do { _Pragma("unroll") for (int n = 0; n < 2; ++n) _Pragma("unroll") for (int k = 0; k < 2; ++k) dst[n][k] = *(const LAS bf16x8*)(lds + PG8_SB(b, h) + boff + n * 2048 + k * 1024); } while (0)
; #define PG8_WAIT_V(n) asm volatile("s_waitcnt vmcnt(" #n ")" ::: "memory")
; template <class Epi, class Sched>
; __device__ __forceinline__ void gemm_phase(LAS unsigned char* lds, const int K, const int lda, const int ldb, const Sched& S, const Epi& E) {
;     ...
;         for (int t = 0; t < nt; t += 2) {
;             const bool last = (t == nt - 2);
;             const char* a1 = cA + (size_t)(t + 1) * kstep;
;             const char* a2 = last ? nA : cA + (size_t)(t + 2) * kstep; const char* b2 = last ? nB : cB + (size_t)(t + 2) * kstep;
;             const char* a3 = a2 + kstep; const char* b3 = b2 + kstep;
;             PG8_LDB(B0, 0, 0); PG8_LDB(B1, 0, 1); PG8_SCHED; PG8_LDA(At, 0, 0); PG8_STAGE(PG8_SA(1, 1), a1 + hA, voffA);
;             PG8_WAIT_V(8); PG8_WAIT_L(0); PG8_BAR; PG8_MMA(0, 0, At, B0); PG8_MMA(0, 1, At, B1); PG8_BAR; PG8_SCHED;
;             PG8_LDA(At, 0, 1); PG8_STAGE(PG8_SB(0, 0), b2, voffB); PG8_STAGE(PG8_SB(0, 1), b2 + hB, voffB); PG8_STAGE(PG8_SA(0, 0), a2, voffA);
;             PG8_WAIT_V(8); PG8_WAIT_L(0); PG8_BAR; PG8_MMA(1, 0, At, B0); PG8_MMA(1, 1, At, B1); PG8_BAR; PG8_SCHED;
;             PG8_LDB(B0, 1, 0); PG8_LDB(B1, 1, 1); PG8_SCHED; PG8_LDA(At, 1, 0); PG8_STAGE(PG8_SA(0, 1), a2 + hA, voffA);
;             PG8_WAIT_V(8); PG8_WAIT_L(0); PG8_BAR; PG8_MMA(0, 0, At, B0); PG8_MMA(0, 1, At, B1); PG8_BAR; PG8_SCHED;
;             PG8_LDA(At, 1, 1); PG8_STAGE(PG8_SB(1, 0), b3, voffB); PG8_STAGE(PG8_SB(1, 1), b3 + hB, voffB); PG8_STAGE(PG8_SA(1, 0), a3, voffA);
;             PG8_WAIT_V(8); PG8_WAIT_L(0); PG8_BAR; PG8_MMA(1, 0, At, B0); PG8_MMA(1, 1, At, B1); PG8_BAR; PG8_SCHED;
;         }
;         if (wr == 0) PG8_BAR;
	s_add_i32 s62, s79, s25
	v_lshl_add_u64 v[146:147], v[146:147], 0, s[46:47]
	s_mov_b32 m0, s62
	ds_read_b128 v[188:191], v153 offset:49152
	ds_read_b128 v[192:195], v153 offset:50176
	ds_read_b128 v[196:199], v153 offset:51200
	ds_read_b128 v[200:203], v153 offset:52224
	ds_read_b128 v[204:207], v153 offset:53248
	ds_read_b128 v[208:211], v153 offset:54272
	ds_read_b128 v[212:215], v153 offset:55296
	ds_read_b128 v[216:219], v153 offset:56320
	global_load_lds_dwordx4 v[146:147], off
	s_add_i32 m0, s62, 0x2000
	s_add_u32 s60, s60, 0x400080
	v_lshl_add_u64 v[146:147], v[220:221], 0, s[46:47]
	s_addc_u32 s61, s61, 0
	s_add_i32 s62, s80, s25
	global_load_lds_dwordx4 v[146:147], off
	v_lshl_add_u64 v[146:147], s[60:61], 0, v[132:133]
	s_mov_b32 m0, s62
	s_nop 0
	global_load_lds_dwordx4 v[146:147], off
	v_lshl_add_u64 v[146:147], s[60:61], 0, v[128:129]
	s_add_i32 m0, s62, 0x2000
	s_nop 0
	global_load_lds_dwordx4 v[146:147], off
	v_lshl_add_u64 v[146:147], v[222:223], 0, s[46:47]
	s_mov_b32 m0, s35
	s_nop 0
	global_load_lds_dwordx4 v[146:147], off
	v_lshl_add_u64 v[146:147], v[224:225], 0, s[46:47]
	s_mov_b32 m0, s38
	s_nop 0
	global_load_lds_dwordx4 v[146:147], off
	s_waitcnt vmcnt(8)
	s_waitcnt lgkmcnt(0)
	s_barrier
	s_setprio 1
	s_waitcnt lgkmcnt(0)
	v_mfma_f32_16x16x32_bf16 v[60:63], v[156:159], v[188:191], v[60:63]
	v_mfma_f32_16x16x32_bf16 v[56:59], v[164:167], v[188:191], v[56:59]
	v_mfma_f32_16x16x32_bf16 v[44:47], v[156:159], v[196:199], v[44:47]
	v_mfma_f32_16x16x32_bf16 v[40:43], v[164:167], v[196:199], v[40:43]
	v_mfma_f32_16x16x32_bf16 v[28:31], v[156:159], v[204:207], v[28:31]
	v_mfma_f32_16x16x32_bf16 v[24:27], v[164:167], v[204:207], v[24:27]
	v_mfma_f32_16x16x32_bf16 v[12:15], v[156:159], v[212:215], v[12:15]
	v_mfma_f32_16x16x32_bf16 v[8:11], v[164:167], v[212:215], v[8:11]
	v_mfma_f32_16x16x32_bf16 v[60:63], v[160:163], v[192:195], v[60:63]
	v_mfma_f32_16x16x32_bf16 v[56:59], v[168:171], v[192:195], v[56:59]
	v_mfma_f32_16x16x32_bf16 v[44:47], v[160:163], v[200:203], v[44:47]
	v_mfma_f32_16x16x32_bf16 v[40:43], v[168:171], v[200:203], v[40:43]
	v_mfma_f32_16x16x32_bf16 v[28:31], v[160:163], v[208:211], v[28:31]
	v_mfma_f32_16x16x32_bf16 v[24:27], v[168:171], v[208:211], v[24:27]
	v_mfma_f32_16x16x32_bf16 v[12:15], v[160:163], v[216:219], v[12:15]
	v_mfma_f32_16x16x32_bf16 v[8:11], v[168:171], v[216:219], v[8:11]
	v_mfma_f32_16x16x32_bf16 v[52:55], v[172:175], v[188:191], v[52:55]
	v_mfma_f32_16x16x32_bf16 v[48:51], v[180:183], v[188:191], v[48:51]
	v_mfma_f32_16x16x32_bf16 v[36:39], v[172:175], v[196:199], v[36:39]
	v_mfma_f32_16x16x32_bf16 v[32:35], v[180:183], v[196:199], v[32:35]
	v_mfma_f32_16x16x32_bf16 v[20:23], v[172:175], v[204:207], v[20:23]
	v_mfma_f32_16x16x32_bf16 v[16:19], v[180:183], v[204:207], v[16:19]
	v_mfma_f32_16x16x32_bf16 v[4:7], v[172:175], v[212:215], v[4:7]
	v_mfma_f32_16x16x32_bf16 v[0:3], v[180:183], v[212:215], v[0:3]
	v_mfma_f32_16x16x32_bf16 v[52:55], v[176:179], v[192:195], v[52:55]
	v_mfma_f32_16x16x32_bf16 v[48:51], v[184:187], v[192:195], v[48:51]
	v_mfma_f32_16x16x32_bf16 v[36:39], v[176:179], v[200:203], v[36:39]
	v_mfma_f32_16x16x32_bf16 v[32:35], v[184:187], v[200:203], v[32:35]
	v_mfma_f32_16x16x32_bf16 v[20:23], v[176:179], v[208:211], v[20:23]
	v_mfma_f32_16x16x32_bf16 v[16:19], v[184:187], v[208:211], v[16:19]
	v_mfma_f32_16x16x32_bf16 v[4:7], v[176:179], v[216:219], v[4:7]
	v_mfma_f32_16x16x32_bf16 v[0:3], v[184:187], v[216:219], v[0:3]
	s_setprio 0
	s_barrier
	s_add_i32 s78, s78, 2
	s_add_u32 s55, s55, 0x100
	s_addc_u32 s59, s59, 0
	s_add_u32 s8, s8, 0x100
	s_addc_u32 s9, s9, 0
	s_cmp_gt_u32 s78, 29
	s_cbranch_scc0 .LBB0_427
	s_and_b64 vcc, exec, s[48:49]
	s_cbranch_vccz .LBB0_430
	s_barrier

; #define PG8_STAGE(bufoff, gbase, voff) do { _Pragma("unroll") for (int _i = 0; _i < 2; ++_i) \
;         __builtin_amdgcn_global_load_lds((const unsigned*)((const char*)(gbase) + (voff)[_i]), (LAS unsigned*)(lds + (bufoff) + ldsw + _i * 8192), 16, 0, 0); } while (0)
; #define PG8_LDA(dst, b, h) do { _Pragma("unroll") for (int m = 0; m < 4; ++m) _Pragma("unroll") for (int k = 0; k < 2; ++k) dst[m][k] = *(const LAS bf16x8*)(lds + PG8_SA(b, h) + aoff + m * 2048 + k * 1024); } while (0)
; #define PG8_LDB(dst, b, h) do { _Pragma("unroll") for (int n = 0; n < 2; ++n) _Pragma("unroll") for (int k = 0; k < 2; ++k) dst[n][k] = *(const LAS bf16x8*)(lds + PG8_SB(b, h) + boff + n * 2048 + k * 1024); } while (0)
; #define PG8_MMA(ai, bj, At, Bt) do { __builtin_amdgcn_s_setprio(1); _Pragma("unroll") for (int m = 0; m < 4; ++m) _Pragma("unroll") for (int n = 0; n < 2; ++n) _Pragma("unroll") for (int k = 0; k < 2; ++k) \
;         acc[ai][bj][m][n] = __builtin_amdgcn_mfma_f32_16x16x32_bf16(Bt[n][k], At[m][k], acc[ai][bj][m][n], 0, 0, 0); __builtin_amdgcn_s_setprio(0); } while (0)
; #define PG8_WAIT_V(n) asm volatile("s_waitcnt vmcnt(" #n ")" ::: "memory")
; #define PG8_WAIT_L(n) asm volatile("s_waitcnt lgkmcnt(" #n ")" ::: "memory")
; #define PG8_BAR __builtin_amdgcn_s_barrier()
; #define PG8_SCHED __builtin_amdgcn_sched_barrier(0)
; template <class Epi, class Sched>
; __device__ __forceinline__ void gemm_phase(LAS unsigned char* lds, const int K, const int lda, const int ldb, const Sched& S, const Epi& E) {
;     ...
;         for (int t = 0; t < nt; t += 2) {
;             const bool last = (t == nt - 2);
;             const char* a1 = cA + (size_t)(t + 1) * kstep;
;             const char* a2 = last ? nA : cA + (size_t)(t + 2) * kstep; const char* b2 = last ? nB : cB + (size_t)(t + 2) * kstep;
;             const char* a3 = a2 + kstep; const char* b3 = b2 + kstep;
;             PG8_LDB(B0, 0, 0); PG8_LDB(B1, 0, 1); PG8_SCHED; PG8_LDA(At, 0, 0); PG8_STAGE(PG8_SA(1, 1), a1 + hA, voffA);
;             PG8_WAIT_V(8); PG8_WAIT_L(0); PG8_BAR; PG8_MMA(0, 0, At, B0); PG8_MMA(0, 1, At, B1); PG8_BAR; PG8_SCHED;
;             PG8_LDA(At, 0, 1); PG8_STAGE(PG8_SB(0, 0), b2, voffB); PG8_STAGE(PG8_SB(0, 1), b2 + hB, voffB); PG8_STAGE(PG8_SA(0, 0), a2, voffA);
;             PG8_WAIT_V(8); PG8_WAIT_L(0); PG8_BAR; PG8_MMA(1, 0, At, B0); PG8_MMA(1, 1, At, B1); PG8_BAR; PG8_SCHED;
.LBB0_477:
	ds_read_b128 v[156:159], v151
	ds_read_b128 v[160:163], v151 offset:1024
	ds_read_b128 v[164:167], v151 offset:2048
	ds_read_b128 v[168:171], v151 offset:3072
	ds_read_b128 v[172:175], v152
	ds_read_b128 v[176:179], v152 offset:1024
	ds_read_b128 v[180:183], v152 offset:2048
	ds_read_b128 v[184:187], v152 offset:3072
	s_add_u32 s60, s8, 0xffe00080
	s_addc_u32 s61, s9, -1
	s_cmp_eq_u32 s63, 12
	s_cselect_b32 s65, s53, s61
	s_cselect_b32 s64, s52, s60
	s_cselect_b32 s61, s59, s57
	s_cselect_b32 s60, s58, s19
	v_lshl_add_u64 v[146:147], s[8:9], 0, v[140:141]
	s_add_i32 m0, s1, 0xc000
	ds_read_b128 v[188:191], v153
	ds_read_b128 v[192:195], v153 offset:1024
	ds_read_b128 v[196:199], v153 offset:2048
	ds_read_b128 v[200:203], v153 offset:3072
	ds_read_b128 v[204:207], v153 offset:4096
	ds_read_b128 v[208:211], v153 offset:5120
	ds_read_b128 v[212:215], v153 offset:6144
	ds_read_b128 v[216:219], v153 offset:7168
	global_load_lds_dwordx4 v[146:147], off
	v_lshl_add_u64 v[146:147], s[8:9], 0, v[138:139]
	s_add_i32 m0, s1, 0xe000
	s_nop 0
	global_load_lds_dwordx4 v[146:147], off
	s_waitcnt vmcnt(8)
	s_waitcnt lgkmcnt(0)
	s_barrier
	s_setprio 1
	s_waitcnt lgkmcnt(0)
	v_mfma_f32_16x16x32_bf16 v[124:127], v[156:159], v[188:191], v[124:127]
	v_mfma_f32_16x16x32_bf16 v[120:123], v[164:167], v[188:191], v[120:123]
	v_mfma_f32_16x16x32_bf16 v[108:111], v[156:159], v[196:199], v[108:111]
	v_mfma_f32_16x16x32_bf16 v[104:107], v[164:167], v[196:199], v[104:107]
	v_mfma_f32_16x16x32_bf16 v[92:95], v[156:159], v[204:207], v[92:95]
	v_mfma_f32_16x16x32_bf16 v[88:91], v[164:167], v[204:207], v[88:91]
	v_mfma_f32_16x16x32_bf16 v[76:79], v[156:159], v[212:215], v[76:79]
	v_mfma_f32_16x16x32_bf16 v[72:75], v[164:167], v[212:215], v[72:75]
	v_mfma_f32_16x16x32_bf16 v[124:127], v[160:163], v[192:195], v[124:127]
	v_mfma_f32_16x16x32_bf16 v[120:123], v[168:171], v[192:195], v[120:123]
	v_mfma_f32_16x16x32_bf16 v[108:111], v[160:163], v[200:203], v[108:111]
	v_mfma_f32_16x16x32_bf16 v[104:107], v[168:171], v[200:203], v[104:107]
	v_mfma_f32_16x16x32_bf16 v[92:95], v[160:163], v[208:211], v[92:95]
	v_mfma_f32_16x16x32_bf16 v[88:91], v[168:171], v[208:211], v[88:91]
	v_mfma_f32_16x16x32_bf16 v[76:79], v[160:163], v[216:219], v[76:79]
	v_mfma_f32_16x16x32_bf16 v[72:75], v[168:171], v[216:219], v[72:75]
	v_mfma_f32_16x16x32_bf16 v[116:119], v[172:175], v[188:191], v[116:119]
	v_mfma_f32_16x16x32_bf16 v[112:115], v[180:183], v[188:191], v[112:115]
	v_mfma_f32_16x16x32_bf16 v[100:103], v[172:175], v[196:199], v[100:103]
	v_mfma_f32_16x16x32_bf16 v[96:99], v[180:183], v[196:199], v[96:99]
	v_mfma_f32_16x16x32_bf16 v[84:87], v[172:175], v[204:207], v[84:87]
	v_mfma_f32_16x16x32_bf16 v[80:83], v[180:183], v[204:207], v[80:83]
	v_mfma_f32_16x16x32_bf16 v[68:71], v[172:175], v[212:215], v[68:71]
	v_mfma_f32_16x16x32_bf16 v[64:67], v[180:183], v[212:215], v[64:67]
	v_mfma_f32_16x16x32_bf16 v[116:119], v[176:179], v[192:195], v[116:119]
	v_mfma_f32_16x16x32_bf16 v[112:115], v[184:187], v[192:195], v[112:115]
	v_mfma_f32_16x16x32_bf16 v[100:103], v[176:179], v[200:203], v[100:103]
	v_mfma_f32_16x16x32_bf16 v[96:99], v[184:187], v[200:203], v[96:99]
	v_mfma_f32_16x16x32_bf16 v[84:87], v[176:179], v[208:211], v[84:87]
	v_mfma_f32_16x16x32_bf16 v[80:83], v[184:187], v[208:211], v[80:83]
	v_mfma_f32_16x16x32_bf16 v[68:71], v[176:179], v[216:219], v[68:71]
	v_mfma_f32_16x16x32_bf16 v[64:67], v[184:187], v[216:219], v[64:67]
	s_setprio 0
	s_barrier
	s_add_i32 s72, s41, s25
	v_lshl_add_u64 v[146:147], s[60:61], 0, v[132:133]
	s_mov_b32 m0, s72
	ds_read_b128 v[188:191], v153 offset:16384
	ds_read_b128 v[192:195], v153 offset:17408
	ds_read_b128 v[196:199], v153 offset:18432
	ds_read_b128 v[200:203], v153 offset:19456
	ds_read_b128 v[204:207], v153 offset:20480
	ds_read_b128 v[208:211], v153 offset:21504
	ds_read_b128 v[212:215], v153 offset:22528
	ds_read_b128 v[216:219], v153 offset:23552
	global_load_lds_dwordx4 v[146:147], off
	s_add_i32 m0, s72, 0x2000
	s_add_u32 s72, s60, 0x400000
	v_lshl_add_u64 v[220:221], s[60:61], 0, v[128:129]
	s_addc_u32 s73, s61, 0
	s_add_i32 s74, s66, s25
	global_load_lds_dwordx4 v[220:221], off
	v_lshl_add_u64 v[222:223], s[72:73], 0, v[132:133]
	s_mov_b32 m0, s74
	v_lshl_add_u64 v[224:225], s[64:65], 0, v[130:131]
	global_load_lds_dwordx4 v[222:223], off
	v_lshl_add_u64 v[222:223], s[72:73], 0, v[128:129]
	s_add_i32 m0, s74, 0x2000
	s_nop 0
	global_load_lds_dwordx4 v[222:223], off
	v_lshl_add_u64 v[222:223], s[64:65], 0, v[134:135]
	s_mov_b32 m0, s1
	s_nop 0
	global_load_lds_dwordx4 v[222:223], off
	s_mov_b32 m0, s23
	s_nop 0
	global_load_lds_dwordx4 v[224:225], off
	s_waitcnt vmcnt(8)
	s_waitcnt lgkmcnt(0)
	s_barrier
; #define PG8_STAGE(bufoff, gbase, voff) do { _Pragma("unroll") for (int _i = 0; _i < 2; ++_i) \
;         __builtin_amdgcn_global_load_lds((const unsigned*)((const char*)(gbase) + (voff)[_i]), (LAS unsigned*)(lds + (bufoff) + ldsw + _i * 8192), 16, 0, 0); } while (0)
; #define PG8_LDA(dst, b, h) do { _Pragma("unroll") for (int m = 0; m < 4; ++m) _Pragma("unroll") for (int k = 0; k < 2; ++k) dst[m][k] = *(const LAS bf16x8*)(lds + PG8_SA(b, h) + aoff + m * 2048 + k * 1024); } while (0)
; #define PG8_LDB(dst, b, h) do { _Pragma("unroll") for (int n = 0; n < 2; ++n) _Pragma("unroll") for (int k = 0; k < 2; ++k) dst[n][k] = *(const LAS bf16x8*)(lds + PG8_SB(b, h) + boff + n * 2048 + k * 1024); } while (0)
; #define PG8_MMA(ai, bj, At, Bt) do { __builtin_amdgcn_s_setprio(1); _Pragma("unroll") for (int m = 0; m < 4; ++m) _Pragma("unroll") for (int n = 0; n < 2; ++n) _Pragma("unroll") for (int k = 0; k < 2; ++k) \
;         acc[ai][bj][m][n] = __builtin_amdgcn_mfma_f32_16x16x32_bf16(Bt[n][k], At[m][k], acc[ai][bj][m][n], 0, 0, 0); __builtin_amdgcn_s_setprio(0); } while (0)
; #define PG8_WAIT_V(n) asm volatile("s_waitcnt vmcnt(" #n ")" ::: "memory")
; #define PG8_WAIT_L(n) asm volatile("s_waitcnt lgkmcnt(" #n ")" ::: "memory")
; #define PG8_BAR __builtin_amdgcn_s_barrier()
; #define PG8_SCHED __builtin_amdgcn_sched_barrier(0)
; template <class Epi, class Sched>
; __device__ __forceinline__ void gemm_phase(LAS unsigned char* lds, const int K, const int lda, const int ldb, const Sched& S, const Epi& E) {
;     ...
;             PG8_WAIT_V(8); PG8_WAIT_L(0); PG8_BAR; PG8_MMA(1, 0, At, B0); PG8_MMA(1, 1, At, B1); PG8_BAR; PG8_SCHED;
;             PG8_LDB(B0, 1, 0); PG8_LDB(B1, 1, 1); PG8_SCHED; PG8_LDA(At, 1, 0); PG8_STAGE(PG8_SA(0, 1), a2 + hA, voffA);
;             PG8_WAIT_V(8); PG8_WAIT_L(0); PG8_BAR; PG8_MMA(0, 0, At, B0); PG8_MMA(0, 1, At, B1); PG8_BAR; PG8_SCHED;
	s_setprio 1
	s_waitcnt lgkmcnt(0)
	v_mfma_f32_16x16x32_bf16 v[60:63], v[156:159], v[188:191], v[60:63]
	v_mfma_f32_16x16x32_bf16 v[56:59], v[164:167], v[188:191], v[56:59]
	v_mfma_f32_16x16x32_bf16 v[44:47], v[156:159], v[196:199], v[44:47]
	v_mfma_f32_16x16x32_bf16 v[40:43], v[164:167], v[196:199], v[40:43]
	v_mfma_f32_16x16x32_bf16 v[28:31], v[156:159], v[204:207], v[28:31]
	v_mfma_f32_16x16x32_bf16 v[24:27], v[164:167], v[204:207], v[24:27]
	v_mfma_f32_16x16x32_bf16 v[12:15], v[156:159], v[212:215], v[12:15]
	v_mfma_f32_16x16x32_bf16 v[8:11], v[164:167], v[212:215], v[8:11]
	v_mfma_f32_16x16x32_bf16 v[60:63], v[160:163], v[192:195], v[60:63]
	v_mfma_f32_16x16x32_bf16 v[56:59], v[168:171], v[192:195], v[56:59]
	v_mfma_f32_16x16x32_bf16 v[44:47], v[160:163], v[200:203], v[44:47]
	v_mfma_f32_16x16x32_bf16 v[40:43], v[168:171], v[200:203], v[40:43]
	v_mfma_f32_16x16x32_bf16 v[28:31], v[160:163], v[208:211], v[28:31]
	v_mfma_f32_16x16x32_bf16 v[24:27], v[168:171], v[208:211], v[24:27]
	v_mfma_f32_16x16x32_bf16 v[12:15], v[160:163], v[216:219], v[12:15]
	v_mfma_f32_16x16x32_bf16 v[8:11], v[168:171], v[216:219], v[8:11]
	v_mfma_f32_16x16x32_bf16 v[52:55], v[172:175], v[188:191], v[52:55]
	v_mfma_f32_16x16x32_bf16 v[48:51], v[180:183], v[188:191], v[48:51]
	v_mfma_f32_16x16x32_bf16 v[36:39], v[172:175], v[196:199], v[36:39]
	v_mfma_f32_16x16x32_bf16 v[32:35], v[180:183], v[196:199], v[32:35]
	v_mfma_f32_16x16x32_bf16 v[20:23], v[172:175], v[204:207], v[20:23]
	v_mfma_f32_16x16x32_bf16 v[16:19], v[180:183], v[204:207], v[16:19]
	v_mfma_f32_16x16x32_bf16 v[4:7], v[172:175], v[212:215], v[4:7]
	v_mfma_f32_16x16x32_bf16 v[0:3], v[180:183], v[212:215], v[0:3]
	v_mfma_f32_16x16x32_bf16 v[52:55], v[176:179], v[192:195], v[52:55]
	v_mfma_f32_16x16x32_bf16 v[48:51], v[184:187], v[192:195], v[48:51]
	v_mfma_f32_16x16x32_bf16 v[36:39], v[176:179], v[200:203], v[36:39]
	v_mfma_f32_16x16x32_bf16 v[32:35], v[184:187], v[200:203], v[32:35]
	v_mfma_f32_16x16x32_bf16 v[20:23], v[176:179], v[208:211], v[20:23]
	v_mfma_f32_16x16x32_bf16 v[16:19], v[184:187], v[208:211], v[16:19]
	v_mfma_f32_16x16x32_bf16 v[4:7], v[176:179], v[216:219], v[4:7]
	v_mfma_f32_16x16x32_bf16 v[0:3], v[184:187], v[216:219], v[0:3]
	s_setprio 0
	s_barrier
	s_add_i32 s72, 0, 0x18000
	v_add_u32_e32 v136, s72, v149
	s_add_i32 s73, 0, 0x1c000
	ds_read_b128 v[156:159], v136
	ds_read_b128 v[160:163], v136 offset:1024
	ds_read_b128 v[164:167], v136 offset:2048
	ds_read_b128 v[168:171], v136 offset:3072
	v_add_u32_e32 v136, s73, v149
	ds_read_b128 v[172:175], v136
	ds_read_b128 v[176:179], v136 offset:1024
	ds_read_b128 v[180:183], v136 offset:2048
	ds_read_b128 v[184:187], v136 offset:3072
	s_add_u32 s64, s64, 0x200000
	s_addc_u32 s65, s65, 0
	s_mov_b32 m0, s26
	v_lshl_add_u64 v[226:227], s[64:65], 0, v[134:135]
	ds_read_b128 v[188:191], v153 offset:32768
	ds_read_b128 v[192:195], v153 offset:33792
	ds_read_b128 v[196:199], v153 offset:34816
	ds_read_b128 v[200:203], v153 offset:35840
	ds_read_b128 v[204:207], v153 offset:36864
	ds_read_b128 v[208:211], v153 offset:37888
	ds_read_b128 v[212:215], v153 offset:38912
	ds_read_b128 v[216:219], v153 offset:39936
	global_load_lds_dwordx4 v[226:227], off
	v_lshl_add_u64 v[226:227], s[64:65], 0, v[130:131]
	s_mov_b32 m0, s27
	s_nop 0
	global_load_lds_dwordx4 v[226:227], off
	s_waitcnt vmcnt(8)
	s_waitcnt lgkmcnt(0)
	s_barrier
	s_setprio 1
	s_waitcnt lgkmcnt(0)
	v_mfma_f32_16x16x32_bf16 v[124:127], v[156:159], v[188:191], v[124:127]
	v_mfma_f32_16x16x32_bf16 v[120:123], v[164:167], v[188:191], v[120:123]
	v_mfma_f32_16x16x32_bf16 v[108:111], v[156:159], v[196:199], v[108:111]
	v_mfma_f32_16x16x32_bf16 v[104:107], v[164:167], v[196:199], v[104:107]
	v_mfma_f32_16x16x32_bf16 v[92:95], v[156:159], v[204:207], v[92:95]
	v_mfma_f32_16x16x32_bf16 v[88:91], v[164:167], v[204:207], v[88:91]
	v_mfma_f32_16x16x32_bf16 v[76:79], v[156:159], v[212:215], v[76:79]
	v_mfma_f32_16x16x32_bf16 v[72:75], v[164:167], v[212:215], v[72:75]
	v_mfma_f32_16x16x32_bf16 v[124:127], v[160:163], v[192:195], v[124:127]
	v_mfma_f32_16x16x32_bf16 v[120:123], v[168:171], v[192:195], v[120:123]
	v_mfma_f32_16x16x32_bf16 v[108:111], v[160:163], v[200:203], v[108:111]
	v_mfma_f32_16x16x32_bf16 v[104:107], v[168:171], v[200:203], v[104:107]
	v_mfma_f32_16x16x32_bf16 v[92:95], v[160:163], v[208:211], v[92:95]
	v_mfma_f32_16x16x32_bf16 v[88:91], v[168:171], v[208:211], v[88:91]
	v_mfma_f32_16x16x32_bf16 v[76:79], v[160:163], v[216:219], v[76:79]
	v_mfma_f32_16x16x32_bf16 v[72:75], v[168:171], v[216:219], v[72:75]
	v_mfma_f32_16x16x32_bf16 v[116:119], v[172:175], v[188:191], v[116:119]
	v_mfma_f32_16x16x32_bf16 v[112:115], v[180:183], v[188:191], v[112:115]
	v_mfma_f32_16x16x32_bf16 v[100:103], v[172:175], v[196:199], v[100:103]
	v_mfma_f32_16x16x32_bf16 v[96:99], v[180:183], v[196:199], v[96:99]
	v_mfma_f32_16x16x32_bf16 v[84:87], v[172:175], v[204:207], v[84:87]
	v_mfma_f32_16x16x32_bf16 v[80:83], v[180:183], v[204:207], v[80:83]
	v_mfma_f32_16x16x32_bf16 v[68:71], v[172:175], v[212:215], v[68:71]
	v_mfma_f32_16x16x32_bf16 v[64:67], v[180:183], v[212:215], v[64:67]
	v_mfma_f32_16x16x32_bf16 v[116:119], v[176:179], v[192:195], v[116:119]
	v_mfma_f32_16x16x32_bf16 v[112:115], v[184:187], v[192:195], v[112:115]
	v_mfma_f32_16x16x32_bf16 v[100:103], v[176:179], v[200:203], v[100:103]
	v_mfma_f32_16x16x32_bf16 v[96:99], v[184:187], v[200:203], v[96:99]
	v_mfma_f32_16x16x32_bf16 v[84:87], v[176:179], v[208:211], v[84:87]
	v_mfma_f32_16x16x32_bf16 v[80:83], v[184:187], v[208:211], v[80:83]
	v_mfma_f32_16x16x32_bf16 v[68:71], v[176:179], v[216:219], v[68:71]
	v_mfma_f32_16x16x32_bf16 v[64:67], v[184:187], v[216:219], v[64:67]
	s_setprio 0
	s_barrier
; #define PG8_STAGE(bufoff, gbase, voff) do { _Pragma("unroll") for (int _i = 0; _i < 2; ++_i) \
;         __builtin_amdgcn_global_load_lds((const unsigned*)((const char*)(gbase) + (voff)[_i]), (LAS unsigned*)(lds + (bufoff) + ldsw + _i * 8192), 16, 0, 0); } while (0)
; #define PG8_LDA(dst, b, h) do { _Pragma("unroll") for (int m = 0; m < 4; ++m) _Pragma("unroll") for (int k = 0; k < 2; ++k) dst[m][k] = *(const LAS bf16x8*)(lds + PG8_SA(b, h) + aoff + m * 2048 + k * 1024); } while (0)
; #define PG8_MMA(ai, bj, At, Bt) do { __builtin_amdgcn_s_setprio(1); _Pragma("unroll") for (int m = 0; m < 4; ++m) _Pragma("unroll") for (int n = 0; n < 2; ++n) _Pragma("unroll") for (int k = 0; k < 2; ++k) \
;         acc[ai][bj][m][n] = __builtin_amdgcn_mfma_f32_16x16x32_bf16(Bt[n][k], At[m][k], acc[ai][bj][m][n], 0, 0, 0); __builtin_amdgcn_s_setprio(0); } while (0)
; #define PG8_WAIT_V(n) asm volatile("s_waitcnt vmcnt(" #n ")" ::: "memory")
; #define PG8_WAIT_L(n) asm volatile("s_waitcnt lgkmcnt(" #n ")" ::: "memory")
; #define PG8_BAR __builtin_amdgcn_s_barrier()
; #define PG8_SCHED __builtin_amdgcn_sched_barrier(0)
; template <class Epi, class Sched>
; __device__ __forceinline__ void gemm_phase(LAS unsigned char* lds, const int K, const int lda, const int ldb, const Sched& S, const Epi& E) {
;     ...
;             PG8_LDA(At, 1, 1); PG8_STAGE(PG8_SB(1, 0), b3, voffB); PG8_STAGE(PG8_SB(1, 1), b3 + hB, voffB); PG8_STAGE(PG8_SA(1, 0), a3, voffA);
;             PG8_WAIT_V(8); PG8_WAIT_L(0); PG8_BAR; PG8_MMA(1, 0, At, B0); PG8_MMA(1, 1, At, B1); PG8_BAR; PG8_SCHED;
;         }
;         if (wr == 0) PG8_BAR;
	s_add_i32 s64, s72, s25
	v_lshl_add_u64 v[146:147], v[146:147], 0, s[48:49]
	s_mov_b32 m0, s64
	ds_read_b128 v[188:191], v153 offset:49152
	ds_read_b128 v[192:195], v153 offset:50176
	ds_read_b128 v[196:199], v153 offset:51200
	ds_read_b128 v[200:203], v153 offset:52224
	ds_read_b128 v[204:207], v153 offset:53248
	ds_read_b128 v[208:211], v153 offset:54272
	ds_read_b128 v[212:215], v153 offset:55296
	ds_read_b128 v[216:219], v153 offset:56320
	global_load_lds_dwordx4 v[146:147], off
	s_add_i32 m0, s64, 0x2000
	s_add_u32 s60, s60, 0x400080
	v_lshl_add_u64 v[146:147], v[220:221], 0, s[48:49]
	s_addc_u32 s61, s61, 0
	s_add_i32 s64, s73, s25
	global_load_lds_dwordx4 v[146:147], off
	v_lshl_add_u64 v[146:147], s[60:61], 0, v[132:133]
	s_mov_b32 m0, s64
	s_nop 0
	global_load_lds_dwordx4 v[146:147], off
	v_lshl_add_u64 v[146:147], s[60:61], 0, v[128:129]
	s_add_i32 m0, s64, 0x2000
	s_nop 0
	global_load_lds_dwordx4 v[146:147], off
	v_lshl_add_u64 v[146:147], v[222:223], 0, s[48:49]
	s_mov_b32 m0, s34
	s_nop 0
	global_load_lds_dwordx4 v[146:147], off
	v_lshl_add_u64 v[146:147], v[224:225], 0, s[48:49]
	s_mov_b32 m0, s35
	s_nop 0
	global_load_lds_dwordx4 v[146:147], off
	s_waitcnt vmcnt(8)
	s_waitcnt lgkmcnt(0)
	s_barrier
	s_setprio 1
	s_waitcnt lgkmcnt(0)
	v_mfma_f32_16x16x32_bf16 v[60:63], v[156:159], v[188:191], v[60:63]
	v_mfma_f32_16x16x32_bf16 v[56:59], v[164:167], v[188:191], v[56:59]
	v_mfma_f32_16x16x32_bf16 v[44:47], v[156:159], v[196:199], v[44:47]
	v_mfma_f32_16x16x32_bf16 v[40:43], v[164:167], v[196:199], v[40:43]
	v_mfma_f32_16x16x32_bf16 v[28:31], v[156:159], v[204:207], v[28:31]
	v_mfma_f32_16x16x32_bf16 v[24:27], v[164:167], v[204:207], v[24:27]
	v_mfma_f32_16x16x32_bf16 v[12:15], v[156:159], v[212:215], v[12:15]
	v_mfma_f32_16x16x32_bf16 v[8:11], v[164:167], v[212:215], v[8:11]
	v_mfma_f32_16x16x32_bf16 v[60:63], v[160:163], v[192:195], v[60:63]
	v_mfma_f32_16x16x32_bf16 v[56:59], v[168:171], v[192:195], v[56:59]
	v_mfma_f32_16x16x32_bf16 v[44:47], v[160:163], v[200:203], v[44:47]
	v_mfma_f32_16x16x32_bf16 v[40:43], v[168:171], v[200:203], v[40:43]
	v_mfma_f32_16x16x32_bf16 v[28:31], v[160:163], v[208:211], v[28:31]
	v_mfma_f32_16x16x32_bf16 v[24:27], v[168:171], v[208:211], v[24:27]
	v_mfma_f32_16x16x32_bf16 v[12:15], v[160:163], v[216:219], v[12:15]
	v_mfma_f32_16x16x32_bf16 v[8:11], v[168:171], v[216:219], v[8:11]
	v_mfma_f32_16x16x32_bf16 v[52:55], v[172:175], v[188:191], v[52:55]
	v_mfma_f32_16x16x32_bf16 v[48:51], v[180:183], v[188:191], v[48:51]
	v_mfma_f32_16x16x32_bf16 v[36:39], v[172:175], v[196:199], v[36:39]
	v_mfma_f32_16x16x32_bf16 v[32:35], v[180:183], v[196:199], v[32:35]
	v_mfma_f32_16x16x32_bf16 v[20:23], v[172:175], v[204:207], v[20:23]
	v_mfma_f32_16x16x32_bf16 v[16:19], v[180:183], v[204:207], v[16:19]
	v_mfma_f32_16x16x32_bf16 v[4:7], v[172:175], v[212:215], v[4:7]
	v_mfma_f32_16x16x32_bf16 v[0:3], v[180:183], v[212:215], v[0:3]
	v_mfma_f32_16x16x32_bf16 v[52:55], v[176:179], v[192:195], v[52:55]
	v_mfma_f32_16x16x32_bf16 v[48:51], v[184:187], v[192:195], v[48:51]
	v_mfma_f32_16x16x32_bf16 v[36:39], v[176:179], v[200:203], v[36:39]
	v_mfma_f32_16x16x32_bf16 v[32:35], v[184:187], v[200:203], v[32:35]
	v_mfma_f32_16x16x32_bf16 v[20:23], v[176:179], v[208:211], v[20:23]
	v_mfma_f32_16x16x32_bf16 v[16:19], v[184:187], v[208:211], v[16:19]
	v_mfma_f32_16x16x32_bf16 v[4:7], v[176:179], v[216:219], v[4:7]
	v_mfma_f32_16x16x32_bf16 v[0:3], v[184:187], v[216:219], v[0:3]
	s_setprio 0
	s_barrier
	s_add_i32 s63, s63, 2
	s_add_u32 s19, s19, 0x100
	s_addc_u32 s57, s57, 0
	s_add_u32 s8, s8, 0x100
	s_addc_u32 s9, s9, 0
	s_cmp_gt_u32 s63, 13
	s_cbranch_scc0 .LBB0_477
	s_and_b64 vcc, exec, s[50:51]
	s_cbranch_vccz .LBB0_480
	s_barrier

; #define PG8_STAGE(bufoff, gbase, voff) do { _Pragma("unroll") for (int _i = 0; _i < 2; ++_i) \
;         __builtin_amdgcn_global_load_lds((const unsigned*)((const char*)(gbase) + (voff)[_i]), (LAS unsigned*)(lds + (bufoff) + ldsw + _i * 8192), 16, 0, 0); } while (0)
; #define PG8_LDA(dst, b, h) do { _Pragma("unroll") for (int m = 0; m < 4; ++m) _Pragma("unroll") for (int k = 0; k < 2; ++k) dst[m][k] = *(const LAS bf16x8*)(lds + PG8_SA(b, h) + aoff + m * 2048 + k * 1024); } while (0)
; #define PG8_LDB(dst, b, h) do { _Pragma("unroll") for (int n = 0; n < 2; ++n) _Pragma("unroll") for (int k = 0; k < 2; ++k) dst[n][k] = *(const LAS bf16x8*)(lds + PG8_SB(b, h) + boff + n * 2048 + k * 1024); } while (0)
; #define PG8_MMA(ai, bj, At, Bt) do { __builtin_amdgcn_s_setprio(1); _Pragma("unroll") for (int m = 0; m < 4; ++m) _Pragma("unroll") for (int n = 0; n < 2; ++n) _Pragma("unroll") for (int k = 0; k < 2; ++k) \
;         acc[ai][bj][m][n] = __builtin_amdgcn_mfma_f32_16x16x32_bf16(Bt[n][k], At[m][k], acc[ai][bj][m][n], 0, 0, 0); __builtin_amdgcn_s_setprio(0); } while (0)
; #define PG8_WAIT_V(n) asm volatile("s_waitcnt vmcnt(" #n ")" ::: "memory")
; #define PG8_WAIT_L(n) asm volatile("s_waitcnt lgkmcnt(" #n ")" ::: "memory")
; #define PG8_BAR __builtin_amdgcn_s_barrier()
; #define PG8_SCHED __builtin_amdgcn_sched_barrier(0)
; template <class Epi, class Sched>
; __device__ __forceinline__ void gemm_phase(LAS unsigned char* lds, const int K, const int lda, const int ldb, const Sched& S, const Epi& E) {
;     ...
;         for (int t = 0; t < nt; t += 2) {
;             const bool last = (t == nt - 2);
;             const char* a1 = cA + (size_t)(t + 1) * kstep;
;             const char* a2 = last ? nA : cA + (size_t)(t + 2) * kstep; const char* b2 = last ? nB : cB + (size_t)(t + 2) * kstep;
;             const char* a3 = a2 + kstep; const char* b3 = b2 + kstep;
;             PG8_LDB(B0, 0, 0); PG8_LDB(B1, 0, 1); PG8_SCHED; PG8_LDA(At, 0, 0); PG8_STAGE(PG8_SA(1, 1), a1 + hA, voffA);
;             PG8_WAIT_V(8); PG8_WAIT_L(0); PG8_BAR; PG8_MMA(0, 0, At, B0); PG8_MMA(0, 1, At, B1); PG8_BAR; PG8_SCHED;
;             PG8_LDA(At, 0, 1); PG8_STAGE(PG8_SB(0, 0), b2, voffB); PG8_STAGE(PG8_SB(0, 1), b2 + hB, voffB); PG8_STAGE(PG8_SA(0, 0), a2, voffA);
;             PG8_WAIT_V(8); PG8_WAIT_L(0); PG8_BAR; PG8_MMA(1, 0, At, B0); PG8_MMA(1, 1, At, B1); PG8_BAR; PG8_SCHED;
.LBB0_619:
	ds_read_b128 v[128:131], v208
	ds_read_b128 v[132:135], v235
	ds_read_b128 v[136:139], v208 offset:2048
	ds_read_b128 v[140:143], v235 offset:2048
	ds_read_b128 v[144:147], v209
	ds_read_b128 v[148:151], v236
	ds_read_b128 v[152:155], v209 offset:2048
	ds_read_b128 v[156:159], v236 offset:2048
	s_add_u32 s53, s62, 0xfff80080
	s_addc_u32 s55, s63, -1
	s_cmp_eq_u32 s47, 28
	s_cselect_b32 s67, s18, s55
	s_cselect_b32 s66, s19, s53
	s_cselect_b32 s65, s35, s41
	s_cselect_b32 s64, s38, s39
	v_lshl_add_u64 v[218:219], s[62:63], 0, v[186:187]
	s_add_i32 m0, s5, 0xc000
	ds_read_b128 v[160:163], v210
	ds_read_b128 v[164:167], v234
	ds_read_b128 v[168:171], v210 offset:2048
	ds_read_b128 v[172:175], v234 offset:2048
	ds_read_b128 v[192:195], v210 offset:4096
	ds_read_b128 v[196:199], v234 offset:4096
	ds_read_b128 v[200:203], v210 offset:6144
	ds_read_b128 v[214:217], v234 offset:6144
	global_load_lds_dwordx4 v[218:219], off
	v_lshl_add_u64 v[218:219], s[62:63], 0, v[184:185]
	s_add_i32 m0, s5, 0xe000
	s_nop 0
	global_load_lds_dwordx4 v[218:219], off
	s_waitcnt vmcnt(8)
	s_waitcnt lgkmcnt(0)
	s_barrier
	s_setprio 1
	s_waitcnt lgkmcnt(0)
	v_mfma_f32_16x16x32_bf16 v[124:127], v[160:163], v[128:131], v[124:127]
	v_mfma_f32_16x16x32_bf16 v[120:123], v[160:163], v[136:139], v[120:123]
	v_mfma_f32_16x16x32_bf16 v[108:111], v[168:171], v[128:131], v[108:111]
	v_mfma_f32_16x16x32_bf16 v[104:107], v[168:171], v[136:139], v[104:107]
	v_mfma_f32_16x16x32_bf16 v[92:95], v[192:195], v[128:131], v[92:95]
	v_mfma_f32_16x16x32_bf16 v[88:91], v[192:195], v[136:139], v[88:91]
	v_mfma_f32_16x16x32_bf16 v[76:79], v[200:203], v[128:131], v[76:79]
	v_mfma_f32_16x16x32_bf16 v[72:75], v[200:203], v[136:139], v[72:75]
	v_mfma_f32_16x16x32_bf16 v[124:127], v[164:167], v[132:135], v[124:127]
	v_mfma_f32_16x16x32_bf16 v[120:123], v[164:167], v[140:143], v[120:123]
	v_mfma_f32_16x16x32_bf16 v[108:111], v[172:175], v[132:135], v[108:111]
	v_mfma_f32_16x16x32_bf16 v[104:107], v[172:175], v[140:143], v[104:107]
	v_mfma_f32_16x16x32_bf16 v[92:95], v[196:199], v[132:135], v[92:95]
	v_mfma_f32_16x16x32_bf16 v[88:91], v[196:199], v[140:143], v[88:91]
	v_mfma_f32_16x16x32_bf16 v[76:79], v[214:217], v[132:135], v[76:79]
	v_mfma_f32_16x16x32_bf16 v[72:75], v[214:217], v[140:143], v[72:75]
	v_mfma_f32_16x16x32_bf16 v[116:119], v[160:163], v[144:147], v[116:119]
	v_mfma_f32_16x16x32_bf16 v[112:115], v[160:163], v[152:155], v[112:115]
	v_mfma_f32_16x16x32_bf16 v[100:103], v[168:171], v[144:147], v[100:103]
	v_mfma_f32_16x16x32_bf16 v[96:99], v[168:171], v[152:155], v[96:99]
	v_mfma_f32_16x16x32_bf16 v[84:87], v[192:195], v[144:147], v[84:87]
	v_mfma_f32_16x16x32_bf16 v[80:83], v[192:195], v[152:155], v[80:83]
	v_mfma_f32_16x16x32_bf16 v[68:71], v[200:203], v[144:147], v[68:71]
	v_mfma_f32_16x16x32_bf16 v[64:67], v[200:203], v[152:155], v[64:67]
	v_mfma_f32_16x16x32_bf16 v[116:119], v[164:167], v[148:151], v[116:119]
	v_mfma_f32_16x16x32_bf16 v[112:115], v[164:167], v[156:159], v[112:115]
	v_mfma_f32_16x16x32_bf16 v[100:103], v[172:175], v[148:151], v[100:103]
	v_mfma_f32_16x16x32_bf16 v[96:99], v[172:175], v[156:159], v[96:99]
	v_mfma_f32_16x16x32_bf16 v[84:87], v[196:199], v[148:151], v[84:87]
	v_mfma_f32_16x16x32_bf16 v[80:83], v[196:199], v[156:159], v[80:83]
	v_mfma_f32_16x16x32_bf16 v[68:71], v[214:217], v[148:151], v[68:71]
	v_mfma_f32_16x16x32_bf16 v[64:67], v[214:217], v[156:159], v[64:67]
	s_setprio 0
	s_barrier
	s_add_i32 s53, s29, s1
	v_lshl_add_u64 v[218:219], s[64:65], 0, v[178:179]
	s_mov_b32 m0, s53
	ds_read_b128 v[160:163], v210 offset:16384
	ds_read_b128 v[164:167], v234 offset:16384
	ds_read_b128 v[168:171], v210 offset:18432
	ds_read_b128 v[172:175], v234 offset:18432
	ds_read_b128 v[192:195], v210 offset:20480
	ds_read_b128 v[196:199], v234 offset:20480
	ds_read_b128 v[200:203], v210 offset:22528
	ds_read_b128 v[214:217], v234 offset:22528
	global_load_lds_dwordx4 v[218:219], off
	s_add_i32 m0, s53, 0x2000
	s_add_u32 s68, s64, 0x80000
	v_lshl_add_u64 v[220:221], s[64:65], 0, v[182:183]
	s_addc_u32 s69, s65, 0
	s_add_i32 s53, s34, s1
	global_load_lds_dwordx4 v[220:221], off
	v_lshl_add_u64 v[222:223], s[68:69], 0, v[178:179]
	s_mov_b32 m0, s53
	v_lshl_add_u64 v[224:225], s[66:67], 0, v[180:181]
	global_load_lds_dwordx4 v[222:223], off
	v_lshl_add_u64 v[222:223], s[68:69], 0, v[182:183]
	s_add_i32 m0, s53, 0x2000
	s_nop 0
	global_load_lds_dwordx4 v[222:223], off
	v_lshl_add_u64 v[222:223], s[66:67], 0, v[176:177]
	s_mov_b32 m0, s5
	s_nop 0
	global_load_lds_dwordx4 v[222:223], off
	s_mov_b32 m0, s14
	s_nop 0
	global_load_lds_dwordx4 v[224:225], off
	s_waitcnt vmcnt(8)
	s_waitcnt lgkmcnt(0)
	s_barrier
; #define PG8_STAGE(bufoff, gbase, voff) do { _Pragma("unroll") for (int _i = 0; _i < 2; ++_i) \
;         __builtin_amdgcn_global_load_lds((const unsigned*)((const char*)(gbase) + (voff)[_i]), (LAS unsigned*)(lds + (bufoff) + ldsw + _i * 8192), 16, 0, 0); } while (0)
; #define PG8_LDA(dst, b, h) do { _Pragma("unroll") for (int m = 0; m < 4; ++m) _Pragma("unroll") for (int k = 0; k < 2; ++k) dst[m][k] = *(const LAS bf16x8*)(lds + PG8_SA(b, h) + aoff + m * 2048 + k * 1024); } while (0)
; #define PG8_LDB(dst, b, h) do { _Pragma("unroll") for (int n = 0; n < 2; ++n) _Pragma("unroll") for (int k = 0; k < 2; ++k) dst[n][k] = *(const LAS bf16x8*)(lds + PG8_SB(b, h) + boff + n * 2048 + k * 1024); } while (0)
; #define PG8_MMA(ai, bj, At, Bt) do { __builtin_amdgcn_s_setprio(1); _Pragma("unroll") for (int m = 0; m < 4; ++m) _Pragma("unroll") for (int n = 0; n < 2; ++n) _Pragma("unroll") for (int k = 0; k < 2; ++k) \
;         acc[ai][bj][m][n] = __builtin_amdgcn_mfma_f32_16x16x32_bf16(Bt[n][k], At[m][k], acc[ai][bj][m][n], 0, 0, 0); __builtin_amdgcn_s_setprio(0); } while (0)
; #define PG8_WAIT_V(n) asm volatile("s_waitcnt vmcnt(" #n ")" ::: "memory")
; #define PG8_WAIT_L(n) asm volatile("s_waitcnt lgkmcnt(" #n ")" ::: "memory")
; #define PG8_BAR __builtin_amdgcn_s_barrier()
; #define PG8_SCHED __builtin_amdgcn_sched_barrier(0)
; template <class Epi, class Sched>
; __device__ __forceinline__ void gemm_phase(LAS unsigned char* lds, const int K, const int lda, const int ldb, const Sched& S, const Epi& E) {
;     ...
;             PG8_WAIT_V(8); PG8_WAIT_L(0); PG8_BAR; PG8_MMA(1, 0, At, B0); PG8_MMA(1, 1, At, B1); PG8_BAR; PG8_SCHED;
;             PG8_LDB(B0, 1, 0); PG8_LDB(B1, 1, 1); PG8_SCHED; PG8_LDA(At, 1, 0); PG8_STAGE(PG8_SA(0, 1), a2 + hA, voffA);
;             PG8_WAIT_V(8); PG8_WAIT_L(0); PG8_BAR; PG8_MMA(0, 0, At, B0); PG8_MMA(0, 1, At, B1); PG8_BAR; PG8_SCHED;
	s_setprio 1
	s_waitcnt lgkmcnt(0)
	v_mfma_f32_16x16x32_bf16 v[60:63], v[160:163], v[128:131], v[60:63]
	v_mfma_f32_16x16x32_bf16 v[56:59], v[160:163], v[136:139], v[56:59]
	v_mfma_f32_16x16x32_bf16 v[44:47], v[168:171], v[128:131], v[44:47]
	v_mfma_f32_16x16x32_bf16 v[40:43], v[168:171], v[136:139], v[40:43]
	v_mfma_f32_16x16x32_bf16 v[28:31], v[192:195], v[128:131], v[28:31]
	v_mfma_f32_16x16x32_bf16 v[24:27], v[192:195], v[136:139], v[24:27]
	v_mfma_f32_16x16x32_bf16 v[12:15], v[200:203], v[128:131], v[12:15]
	v_mfma_f32_16x16x32_bf16 v[8:11], v[200:203], v[136:139], v[8:11]
	v_mfma_f32_16x16x32_bf16 v[60:63], v[164:167], v[132:135], v[60:63]
	v_mfma_f32_16x16x32_bf16 v[56:59], v[164:167], v[140:143], v[56:59]
	v_mfma_f32_16x16x32_bf16 v[44:47], v[172:175], v[132:135], v[44:47]
	v_mfma_f32_16x16x32_bf16 v[40:43], v[172:175], v[140:143], v[40:43]
	v_mfma_f32_16x16x32_bf16 v[28:31], v[196:199], v[132:135], v[28:31]
	v_mfma_f32_16x16x32_bf16 v[24:27], v[196:199], v[140:143], v[24:27]
	v_mfma_f32_16x16x32_bf16 v[12:15], v[214:217], v[132:135], v[12:15]
	v_mfma_f32_16x16x32_bf16 v[8:11], v[214:217], v[140:143], v[8:11]
	v_mfma_f32_16x16x32_bf16 v[52:55], v[160:163], v[144:147], v[52:55]
	v_mfma_f32_16x16x32_bf16 v[48:51], v[160:163], v[152:155], v[48:51]
	v_mfma_f32_16x16x32_bf16 v[36:39], v[168:171], v[144:147], v[36:39]
	v_mfma_f32_16x16x32_bf16 v[32:35], v[168:171], v[152:155], v[32:35]
	v_mfma_f32_16x16x32_bf16 v[20:23], v[192:195], v[144:147], v[20:23]
	v_mfma_f32_16x16x32_bf16 v[16:19], v[192:195], v[152:155], v[16:19]
	v_mfma_f32_16x16x32_bf16 v[4:7], v[200:203], v[144:147], v[4:7]
	v_mfma_f32_16x16x32_bf16 v[0:3], v[200:203], v[152:155], v[0:3]
	v_mfma_f32_16x16x32_bf16 v[52:55], v[164:167], v[148:151], v[52:55]
	v_mfma_f32_16x16x32_bf16 v[48:51], v[164:167], v[156:159], v[48:51]
	v_mfma_f32_16x16x32_bf16 v[36:39], v[172:175], v[148:151], v[36:39]
	v_mfma_f32_16x16x32_bf16 v[32:35], v[172:175], v[156:159], v[32:35]
	v_mfma_f32_16x16x32_bf16 v[20:23], v[196:199], v[148:151], v[20:23]
	v_mfma_f32_16x16x32_bf16 v[16:19], v[196:199], v[156:159], v[16:19]
	v_mfma_f32_16x16x32_bf16 v[4:7], v[214:217], v[148:151], v[4:7]
	v_mfma_f32_16x16x32_bf16 v[0:3], v[214:217], v[156:159], v[0:3]
	s_setprio 0
	s_barrier
	s_add_i32 s53, 0, 0x18000
	s_add_i32 s55, 0, 0x1c000
	v_add_u32_e32 v140, s53, v205
	v_add_u32_e32 v238, s53, v237
	v_add_u32_e32 v156, 0x19000, v205
	v_add_u32_e32 v239, 0x19000, v237
	ds_read_b128 v[128:131], v140
	ds_read_b128 v[132:135], v238
	ds_read_b128 v[136:139], v140 offset:2048
	ds_read_b128 v[140:143], v238 offset:2048
	ds_read_b128 v[144:147], v156
	ds_read_b128 v[148:151], v239
	ds_read_b128 v[152:155], v156 offset:2048
	ds_read_b128 v[156:159], v239 offset:2048
	s_add_u32 s66, s66, 0x80000
	s_addc_u32 s67, s67, 0
	s_mov_b32 m0, s15
	v_lshl_add_u64 v[226:227], s[66:67], 0, v[176:177]
	ds_read_b128 v[160:163], v210 offset:32768
	ds_read_b128 v[164:167], v234 offset:32768
	ds_read_b128 v[168:171], v210 offset:34816
	ds_read_b128 v[172:175], v234 offset:34816
	ds_read_b128 v[192:195], v210 offset:36864
	ds_read_b128 v[196:199], v234 offset:36864
	ds_read_b128 v[200:203], v210 offset:38912
	ds_read_b128 v[214:217], v234 offset:38912
	global_load_lds_dwordx4 v[226:227], off
	v_lshl_add_u64 v[226:227], s[66:67], 0, v[180:181]
	s_mov_b32 m0, s17
	s_nop 0
	global_load_lds_dwordx4 v[226:227], off
	s_waitcnt vmcnt(8)
	s_waitcnt lgkmcnt(0)
	s_barrier
	s_setprio 1
	s_waitcnt lgkmcnt(0)
	v_mfma_f32_16x16x32_bf16 v[124:127], v[160:163], v[128:131], v[124:127]
	v_mfma_f32_16x16x32_bf16 v[120:123], v[160:163], v[136:139], v[120:123]
	v_mfma_f32_16x16x32_bf16 v[108:111], v[168:171], v[128:131], v[108:111]
	v_mfma_f32_16x16x32_bf16 v[104:107], v[168:171], v[136:139], v[104:107]
	v_mfma_f32_16x16x32_bf16 v[92:95], v[192:195], v[128:131], v[92:95]
	v_mfma_f32_16x16x32_bf16 v[88:91], v[192:195], v[136:139], v[88:91]
	v_mfma_f32_16x16x32_bf16 v[76:79], v[200:203], v[128:131], v[76:79]
	v_mfma_f32_16x16x32_bf16 v[72:75], v[200:203], v[136:139], v[72:75]
	v_mfma_f32_16x16x32_bf16 v[124:127], v[164:167], v[132:135], v[124:127]
	v_mfma_f32_16x16x32_bf16 v[120:123], v[164:167], v[140:143], v[120:123]
	v_mfma_f32_16x16x32_bf16 v[108:111], v[172:175], v[132:135], v[108:111]
	v_mfma_f32_16x16x32_bf16 v[104:107], v[172:175], v[140:143], v[104:107]
	v_mfma_f32_16x16x32_bf16 v[92:95], v[196:199], v[132:135], v[92:95]
	v_mfma_f32_16x16x32_bf16 v[88:91], v[196:199], v[140:143], v[88:91]
	v_mfma_f32_16x16x32_bf16 v[76:79], v[214:217], v[132:135], v[76:79]
	v_mfma_f32_16x16x32_bf16 v[72:75], v[214:217], v[140:143], v[72:75]
	v_mfma_f32_16x16x32_bf16 v[116:119], v[160:163], v[144:147], v[116:119]
	v_mfma_f32_16x16x32_bf16 v[112:115], v[160:163], v[152:155], v[112:115]
	v_mfma_f32_16x16x32_bf16 v[100:103], v[168:171], v[144:147], v[100:103]
	v_mfma_f32_16x16x32_bf16 v[96:99], v[168:171], v[152:155], v[96:99]
	v_mfma_f32_16x16x32_bf16 v[84:87], v[192:195], v[144:147], v[84:87]
	v_mfma_f32_16x16x32_bf16 v[80:83], v[192:195], v[152:155], v[80:83]
	v_mfma_f32_16x16x32_bf16 v[68:71], v[200:203], v[144:147], v[68:71]
	v_mfma_f32_16x16x32_bf16 v[64:67], v[200:203], v[152:155], v[64:67]
	v_mfma_f32_16x16x32_bf16 v[116:119], v[164:167], v[148:151], v[116:119]
	v_mfma_f32_16x16x32_bf16 v[112:115], v[164:167], v[156:159], v[112:115]
	v_mfma_f32_16x16x32_bf16 v[100:103], v[172:175], v[148:151], v[100:103]
	v_mfma_f32_16x16x32_bf16 v[96:99], v[172:175], v[156:159], v[96:99]
	v_mfma_f32_16x16x32_bf16 v[84:87], v[196:199], v[148:151], v[84:87]
	v_mfma_f32_16x16x32_bf16 v[80:83], v[196:199], v[156:159], v[80:83]
	v_mfma_f32_16x16x32_bf16 v[68:71], v[214:217], v[148:151], v[68:71]
	v_mfma_f32_16x16x32_bf16 v[64:67], v[214:217], v[156:159], v[64:67]
	s_setprio 0
	s_barrier
; #define PG8_STAGE(bufoff, gbase, voff) do { _Pragma("unroll") for (int _i = 0; _i < 2; ++_i) \
;         __builtin_amdgcn_global_load_lds((const unsigned*)((const char*)(gbase) + (voff)[_i]), (LAS unsigned*)(lds + (bufoff) + ldsw + _i * 8192), 16, 0, 0); } while (0)
; #define PG8_LDA(dst, b, h) do { _Pragma("unroll") for (int m = 0; m < 4; ++m) _Pragma("unroll") for (int k = 0; k < 2; ++k) dst[m][k] = *(const LAS bf16x8*)(lds + PG8_SA(b, h) + aoff + m * 2048 + k * 1024); } while (0)
; #define PG8_MMA(ai, bj, At, Bt) do { __builtin_amdgcn_s_setprio(1); _Pragma("unroll") for (int m = 0; m < 4; ++m) _Pragma("unroll") for (int n = 0; n < 2; ++n) _Pragma("unroll") for (int k = 0; k < 2; ++k) \
;         acc[ai][bj][m][n] = __builtin_amdgcn_mfma_f32_16x16x32_bf16(Bt[n][k], At[m][k], acc[ai][bj][m][n], 0, 0, 0); __builtin_amdgcn_s_setprio(0); } while (0)
; #define PG8_WAIT_V(n) asm volatile("s_waitcnt vmcnt(" #n ")" ::: "memory")
; #define PG8_WAIT_L(n) asm volatile("s_waitcnt lgkmcnt(" #n ")" ::: "memory")
; #define PG8_BAR __builtin_amdgcn_s_barrier()
; #define PG8_SCHED __builtin_amdgcn_sched_barrier(0)
; template <class Epi, class Sched>
; __device__ __forceinline__ void gemm_phase(LAS unsigned char* lds, const int K, const int lda, const int ldb, const Sched& S, const Epi& E) {
;     ...
;             PG8_LDA(At, 1, 1); PG8_STAGE(PG8_SB(1, 0), b3, voffB); PG8_STAGE(PG8_SB(1, 1), b3 + hB, voffB); PG8_STAGE(PG8_SA(1, 0), a3, voffA);
;             PG8_WAIT_V(8); PG8_WAIT_L(0); PG8_BAR; PG8_MMA(1, 0, At, B0); PG8_MMA(1, 1, At, B1); PG8_BAR; PG8_SCHED;
;         }
;         if (wr == 0) PG8_BAR;
	s_add_i32 s53, s53, s1
	v_lshl_add_u64 v[218:219], v[218:219], 0, s[48:49]
	s_mov_b32 m0, s53
	ds_read_b128 v[160:163], v210 offset:49152
	ds_read_b128 v[164:167], v234 offset:49152
	ds_read_b128 v[168:171], v210 offset:51200
	ds_read_b128 v[172:175], v234 offset:51200
	ds_read_b128 v[192:195], v210 offset:53248
	ds_read_b128 v[196:199], v234 offset:53248
	ds_read_b128 v[200:203], v210 offset:55296
	ds_read_b128 v[214:217], v234 offset:55296
	global_load_lds_dwordx4 v[218:219], off
	s_add_i32 m0, s53, 0x2000
	s_add_u32 s64, s64, 0x80080
	v_lshl_add_u64 v[218:219], v[220:221], 0, s[48:49]
	s_addc_u32 s65, s65, 0
	s_add_i32 s53, s55, s1
	global_load_lds_dwordx4 v[218:219], off
	v_lshl_add_u64 v[218:219], s[64:65], 0, v[178:179]
	s_mov_b32 m0, s53
	s_nop 0
	global_load_lds_dwordx4 v[218:219], off
	v_lshl_add_u64 v[218:219], s[64:65], 0, v[182:183]
	s_add_i32 m0, s53, 0x2000
	s_nop 0
	global_load_lds_dwordx4 v[218:219], off
	v_lshl_add_u64 v[218:219], v[222:223], 0, s[48:49]
	s_mov_b32 m0, s0
	s_nop 0
	global_load_lds_dwordx4 v[218:219], off
	v_lshl_add_u64 v[218:219], v[224:225], 0, s[48:49]
	s_mov_b32 m0, s24
	s_nop 0
	global_load_lds_dwordx4 v[218:219], off
	s_waitcnt vmcnt(8)
	s_waitcnt lgkmcnt(0)
	s_barrier
	s_setprio 1
	s_waitcnt lgkmcnt(0)
	v_mfma_f32_16x16x32_bf16 v[60:63], v[160:163], v[128:131], v[60:63]
	v_mfma_f32_16x16x32_bf16 v[56:59], v[160:163], v[136:139], v[56:59]
	v_mfma_f32_16x16x32_bf16 v[44:47], v[168:171], v[128:131], v[44:47]
	v_mfma_f32_16x16x32_bf16 v[40:43], v[168:171], v[136:139], v[40:43]
	v_mfma_f32_16x16x32_bf16 v[28:31], v[192:195], v[128:131], v[28:31]
	v_mfma_f32_16x16x32_bf16 v[24:27], v[192:195], v[136:139], v[24:27]
	v_mfma_f32_16x16x32_bf16 v[12:15], v[200:203], v[128:131], v[12:15]
	v_mfma_f32_16x16x32_bf16 v[8:11], v[200:203], v[136:139], v[8:11]
	v_mfma_f32_16x16x32_bf16 v[60:63], v[164:167], v[132:135], v[60:63]
	v_mfma_f32_16x16x32_bf16 v[56:59], v[164:167], v[140:143], v[56:59]
	v_mfma_f32_16x16x32_bf16 v[44:47], v[172:175], v[132:135], v[44:47]
	v_mfma_f32_16x16x32_bf16 v[40:43], v[172:175], v[140:143], v[40:43]
	v_mfma_f32_16x16x32_bf16 v[28:31], v[196:199], v[132:135], v[28:31]
	v_mfma_f32_16x16x32_bf16 v[24:27], v[196:199], v[140:143], v[24:27]
	v_mfma_f32_16x16x32_bf16 v[12:15], v[214:217], v[132:135], v[12:15]
	v_mfma_f32_16x16x32_bf16 v[8:11], v[214:217], v[140:143], v[8:11]
	v_mfma_f32_16x16x32_bf16 v[52:55], v[160:163], v[144:147], v[52:55]
	v_mfma_f32_16x16x32_bf16 v[48:51], v[160:163], v[152:155], v[48:51]
	v_mfma_f32_16x16x32_bf16 v[36:39], v[168:171], v[144:147], v[36:39]
	v_mfma_f32_16x16x32_bf16 v[32:35], v[168:171], v[152:155], v[32:35]
	v_mfma_f32_16x16x32_bf16 v[20:23], v[192:195], v[144:147], v[20:23]
	v_mfma_f32_16x16x32_bf16 v[16:19], v[192:195], v[152:155], v[16:19]
	v_mfma_f32_16x16x32_bf16 v[4:7], v[200:203], v[144:147], v[4:7]
	v_mfma_f32_16x16x32_bf16 v[0:3], v[200:203], v[152:155], v[0:3]
	v_mfma_f32_16x16x32_bf16 v[52:55], v[164:167], v[148:151], v[52:55]
	v_mfma_f32_16x16x32_bf16 v[48:51], v[164:167], v[156:159], v[48:51]
	v_mfma_f32_16x16x32_bf16 v[36:39], v[172:175], v[148:151], v[36:39]
	v_mfma_f32_16x16x32_bf16 v[32:35], v[172:175], v[156:159], v[32:35]
	v_mfma_f32_16x16x32_bf16 v[20:23], v[196:199], v[148:151], v[20:23]
	v_mfma_f32_16x16x32_bf16 v[16:19], v[196:199], v[156:159], v[16:19]
	v_mfma_f32_16x16x32_bf16 v[4:7], v[214:217], v[148:151], v[4:7]
	v_mfma_f32_16x16x32_bf16 v[0:3], v[214:217], v[156:159], v[0:3]
	s_setprio 0
	s_barrier
	s_add_i32 s47, s47, 2
	s_add_u32 s39, s39, 0x100
	s_addc_u32 s41, s41, 0
	s_add_u32 s62, s62, 0x100
	s_addc_u32 s63, s63, 0
	s_cmp_gt_u32 s47, 29
	s_cbranch_scc0 .LBB0_619
	s_and_b64 vcc, exec, s[50:51]
	s_cbranch_vccz .LBB0_622
	s_barrier

; #define PG8_STAGE(bufoff, gbase, voff) do { _Pragma("unroll") for (int _i = 0; _i < 2; ++_i) \
;         __builtin_amdgcn_global_load_lds((const unsigned*)((const char*)(gbase) + (voff)[_i]), (LAS unsigned*)(lds + (bufoff) + ldsw + _i * 8192), 16, 0, 0); } while (0)
; #define PG8_LDA(dst, b, h) do { _Pragma("unroll") for (int m = 0; m < 4; ++m) _Pragma("unroll") for (int k = 0; k < 2; ++k) dst[m][k] = *(const LAS bf16x8*)(lds + PG8_SA(b, h) + aoff + m * 2048 + k * 1024); } while (0)
; #define PG8_LDB(dst, b, h) do { _Pragma("unroll") for (int n = 0; n < 2; ++n) _Pragma("unroll") for (int k = 0; k < 2; ++k) dst[n][k] = *(const LAS bf16x8*)(lds + PG8_SB(b, h) + boff + n * 2048 + k * 1024); } while (0)
; #define PG8_MMA(ai, bj, At, Bt) do { __builtin_amdgcn_s_setprio(1); _Pragma("unroll") for (int m = 0; m < 4; ++m) _Pragma("unroll") for (int n = 0; n < 2; ++n) _Pragma("unroll") for (int k = 0; k < 2; ++k) \
;         acc[ai][bj][m][n] = __builtin_amdgcn_mfma_f32_16x16x32_bf16(Bt[n][k], At[m][k], acc[ai][bj][m][n], 0, 0, 0); __builtin_amdgcn_s_setprio(0); } while (0)
; #define PG8_WAIT_V(n) asm volatile("s_waitcnt vmcnt(" #n ")" ::: "memory")
; #define PG8_WAIT_L(n) asm volatile("s_waitcnt lgkmcnt(" #n ")" ::: "memory")
; #define PG8_BAR __builtin_amdgcn_s_barrier()
; #define PG8_SCHED __builtin_amdgcn_sched_barrier(0)
; template <class Epi, class Sched>
; __device__ __forceinline__ void gemm_phase(LAS unsigned char* lds, const int K, const int lda, const int ldb, const Sched& S, const Epi& E) {
;     ...
;         for (int t = 0; t < nt; t += 2) {
;             const bool last = (t == nt - 2);
;             const char* a1 = cA + (size_t)(t + 1) * kstep;
;             const char* a2 = last ? nA : cA + (size_t)(t + 2) * kstep; const char* b2 = last ? nB : cB + (size_t)(t + 2) * kstep;
;             const char* a3 = a2 + kstep; const char* b3 = b2 + kstep;
;             PG8_LDB(B0, 0, 0); PG8_LDB(B1, 0, 1); PG8_SCHED; PG8_LDA(At, 0, 0); PG8_STAGE(PG8_SA(1, 1), a1 + hA, voffA);
;             PG8_WAIT_V(8); PG8_WAIT_L(0); PG8_BAR; PG8_MMA(0, 0, At, B0); PG8_MMA(0, 1, At, B1); PG8_BAR; PG8_SCHED;
;             PG8_LDA(At, 0, 1); PG8_STAGE(PG8_SB(0, 0), b2, voffB); PG8_STAGE(PG8_SB(0, 1), b2 + hB, voffB); PG8_STAGE(PG8_SA(0, 0), a2, voffA);
;             PG8_WAIT_V(8); PG8_WAIT_L(0); PG8_BAR; PG8_MMA(1, 0, At, B0); PG8_MMA(1, 1, At, B1); PG8_BAR; PG8_SCHED;
.LBB0_695:
	s_waitcnt lgkmcnt(0)
	ds_read_b128 v[158:161], v236
	ds_read_b128 v[162:165], v248
	ds_read_b128 v[166:169], v236 offset:2048
	ds_read_b128 v[170:173], v248 offset:2048
	ds_read_b128 v[174:177], v237
	ds_read_b128 v[178:181], v249
	ds_read_b128 v[182:185], v237 offset:2048
	ds_read_b128 v[186:189], v249 offset:2048
	s_add_u32 s38, s64, 0xfff80080
	s_addc_u32 s39, s65, -1
	s_cmp_eq_u32 s29, 28
	s_cselect_b32 s71, s0, s39
	s_cselect_b32 s70, s1, s38
	s_cselect_b32 s69, s13, s28
	s_cselect_b32 s68, s18, s19
	v_lshl_add_u64 v[222:223], s[64:65], 0, v[148:149]
	s_add_i32 m0, s4, 0xc000
	ds_read_b128 v[190:193], v145
	ds_read_b128 v[194:197], v247
	ds_read_b128 v[198:201], v145 offset:2048
	ds_read_b128 v[202:205], v247 offset:2048
	ds_read_b128 v[206:209], v145 offset:4096
	ds_read_b128 v[210:213], v247 offset:4096
	ds_read_b128 v[214:217], v145 offset:6144
	ds_read_b128 v[218:221], v247 offset:6144
	global_load_lds_dwordx4 v[222:223], off
	v_lshl_add_u64 v[222:223], s[64:65], 0, v[146:147]
	s_add_i32 m0, s4, 0xe000
	s_nop 0
	global_load_lds_dwordx4 v[222:223], off
	s_waitcnt vmcnt(8)
	s_waitcnt lgkmcnt(0)
	s_barrier
	s_setprio 1
	s_waitcnt lgkmcnt(0)
	v_mfma_f32_16x16x32_bf16 v[124:127], v[158:161], v[190:193], v[124:127]
	v_mfma_f32_16x16x32_bf16 v[116:119], v[166:169], v[190:193], v[116:119]
	v_mfma_f32_16x16x32_bf16 v[108:111], v[158:161], v[198:201], v[108:111]
	v_mfma_f32_16x16x32_bf16 v[100:103], v[166:169], v[198:201], v[100:103]
	v_mfma_f32_16x16x32_bf16 v[92:95], v[158:161], v[206:209], v[92:95]
	v_mfma_f32_16x16x32_bf16 v[84:87], v[166:169], v[206:209], v[84:87]
	v_mfma_f32_16x16x32_bf16 v[76:79], v[158:161], v[214:217], v[76:79]
	v_mfma_f32_16x16x32_bf16 v[68:71], v[166:169], v[214:217], v[68:71]
	v_mfma_f32_16x16x32_bf16 v[124:127], v[162:165], v[194:197], v[124:127]
	v_mfma_f32_16x16x32_bf16 v[116:119], v[170:173], v[194:197], v[116:119]
	v_mfma_f32_16x16x32_bf16 v[108:111], v[162:165], v[202:205], v[108:111]
	v_mfma_f32_16x16x32_bf16 v[100:103], v[170:173], v[202:205], v[100:103]
	v_mfma_f32_16x16x32_bf16 v[92:95], v[162:165], v[210:213], v[92:95]
	v_mfma_f32_16x16x32_bf16 v[84:87], v[170:173], v[210:213], v[84:87]
	v_mfma_f32_16x16x32_bf16 v[76:79], v[162:165], v[218:221], v[76:79]
	v_mfma_f32_16x16x32_bf16 v[68:71], v[170:173], v[218:221], v[68:71]
	v_mfma_f32_16x16x32_bf16 v[120:123], v[174:177], v[190:193], v[120:123]
	v_mfma_f32_16x16x32_bf16 v[112:115], v[182:185], v[190:193], v[112:115]
	v_mfma_f32_16x16x32_bf16 v[104:107], v[174:177], v[198:201], v[104:107]
	v_mfma_f32_16x16x32_bf16 v[96:99], v[182:185], v[198:201], v[96:99]
	v_mfma_f32_16x16x32_bf16 v[88:91], v[174:177], v[206:209], v[88:91]
	v_mfma_f32_16x16x32_bf16 v[80:83], v[182:185], v[206:209], v[80:83]
	v_mfma_f32_16x16x32_bf16 v[72:75], v[174:177], v[214:217], v[72:75]
	v_mfma_f32_16x16x32_bf16 v[64:67], v[182:185], v[214:217], v[64:67]
	v_mfma_f32_16x16x32_bf16 v[120:123], v[178:181], v[194:197], v[120:123]
	v_mfma_f32_16x16x32_bf16 v[112:115], v[186:189], v[194:197], v[112:115]
	v_mfma_f32_16x16x32_bf16 v[104:107], v[178:181], v[202:205], v[104:107]
	v_mfma_f32_16x16x32_bf16 v[96:99], v[186:189], v[202:205], v[96:99]
	v_mfma_f32_16x16x32_bf16 v[88:91], v[178:181], v[210:213], v[88:91]
	v_mfma_f32_16x16x32_bf16 v[80:83], v[186:189], v[210:213], v[80:83]
	v_mfma_f32_16x16x32_bf16 v[72:75], v[178:181], v[218:221], v[72:75]
	v_mfma_f32_16x16x32_bf16 v[64:67], v[186:189], v[218:221], v[64:67]
	s_setprio 0
	s_barrier
	s_add_i32 s38, s79, s2
	v_lshl_add_u64 v[222:223], s[68:69], 0, v[130:131]
	s_mov_b32 m0, s38
	ds_read_b128 v[190:193], v145 offset:16384
	ds_read_b128 v[194:197], v247 offset:16384
	ds_read_b128 v[198:201], v145 offset:18432
	ds_read_b128 v[202:205], v247 offset:18432
	ds_read_b128 v[206:209], v145 offset:20480
	ds_read_b128 v[210:213], v247 offset:20480
	ds_read_b128 v[214:217], v145 offset:22528
	ds_read_b128 v[218:221], v247 offset:22528
	global_load_lds_dwordx4 v[222:223], off
	s_add_i32 m0, s38, 0x2000
	s_add_u32 s38, s68, 0x80000
	v_lshl_add_u64 v[224:225], s[68:69], 0, v[134:135]
	s_addc_u32 s39, s69, 0
	s_add_i32 s41, s80, s2
	global_load_lds_dwordx4 v[224:225], off
	v_lshl_add_u64 v[226:227], s[38:39], 0, v[130:131]
	s_mov_b32 m0, s41
	v_lshl_add_u64 v[228:229], s[70:71], 0, v[132:133]
	global_load_lds_dwordx4 v[226:227], off
	v_lshl_add_u64 v[226:227], s[38:39], 0, v[134:135]
	s_add_i32 m0, s41, 0x2000
	s_nop 0
	global_load_lds_dwordx4 v[226:227], off
	v_lshl_add_u64 v[226:227], s[70:71], 0, v[128:129]
	s_mov_b32 m0, s4
	s_nop 0
	global_load_lds_dwordx4 v[226:227], off
	s_mov_b32 m0, s5
	s_nop 0
	global_load_lds_dwordx4 v[228:229], off
	s_waitcnt vmcnt(8)
	s_waitcnt lgkmcnt(0)
	s_barrier
; #define PG8_STAGE(bufoff, gbase, voff) do { _Pragma("unroll") for (int _i = 0; _i < 2; ++_i) \
;         __builtin_amdgcn_global_load_lds((const unsigned*)((const char*)(gbase) + (voff)[_i]), (LAS unsigned*)(lds + (bufoff) + ldsw + _i * 8192), 16, 0, 0); } while (0)
; #define PG8_LDA(dst, b, h) do { _Pragma("unroll") for (int m = 0; m < 4; ++m) _Pragma("unroll") for (int k = 0; k < 2; ++k) dst[m][k] = *(const LAS bf16x8*)(lds + PG8_SA(b, h) + aoff + m * 2048 + k * 1024); } while (0)
; #define PG8_LDB(dst, b, h) do { _Pragma("unroll") for (int n = 0; n < 2; ++n) _Pragma("unroll") for (int k = 0; k < 2; ++k) dst[n][k] = *(const LAS bf16x8*)(lds + PG8_SB(b, h) + boff + n * 2048 + k * 1024); } while (0)
; #define PG8_MMA(ai, bj, At, Bt) do { __builtin_amdgcn_s_setprio(1); _Pragma("unroll") for (int m = 0; m < 4; ++m) _Pragma("unroll") for (int n = 0; n < 2; ++n) _Pragma("unroll") for (int k = 0; k < 2; ++k) \
;         acc[ai][bj][m][n] = __builtin_amdgcn_mfma_f32_16x16x32_bf16(Bt[n][k], At[m][k], acc[ai][bj][m][n], 0, 0, 0); __builtin_amdgcn_s_setprio(0); } while (0)
; #define PG8_WAIT_V(n) asm volatile("s_waitcnt vmcnt(" #n ")" ::: "memory")
; #define PG8_WAIT_L(n) asm volatile("s_waitcnt lgkmcnt(" #n ")" ::: "memory")
; #define PG8_BAR __builtin_amdgcn_s_barrier()
; #define PG8_SCHED __builtin_amdgcn_sched_barrier(0)
; template <class Epi, class Sched>
; __device__ __forceinline__ void gemm_phase(LAS unsigned char* lds, const int K, const int lda, const int ldb, const Sched& S, const Epi& E) {
;     ...
;             PG8_WAIT_V(8); PG8_WAIT_L(0); PG8_BAR; PG8_MMA(1, 0, At, B0); PG8_MMA(1, 1, At, B1); PG8_BAR; PG8_SCHED;
;             PG8_LDB(B0, 1, 0); PG8_LDB(B1, 1, 1); PG8_SCHED; PG8_LDA(At, 1, 0); PG8_STAGE(PG8_SA(0, 1), a2 + hA, voffA);
;             PG8_WAIT_V(8); PG8_WAIT_L(0); PG8_BAR; PG8_MMA(0, 0, At, B0); PG8_MMA(0, 1, At, B1); PG8_BAR; PG8_SCHED;
	s_setprio 1
	s_waitcnt lgkmcnt(0)
	v_mfma_f32_16x16x32_bf16 v[60:63], v[158:161], v[190:193], v[60:63]
	v_mfma_f32_16x16x32_bf16 v[52:55], v[166:169], v[190:193], v[52:55]
	v_mfma_f32_16x16x32_bf16 v[44:47], v[158:161], v[198:201], v[44:47]
	v_mfma_f32_16x16x32_bf16 v[36:39], v[166:169], v[198:201], v[36:39]
	v_mfma_f32_16x16x32_bf16 v[28:31], v[158:161], v[206:209], v[28:31]
	v_mfma_f32_16x16x32_bf16 v[20:23], v[166:169], v[206:209], v[20:23]
	v_mfma_f32_16x16x32_bf16 v[12:15], v[158:161], v[214:217], v[12:15]
	v_mfma_f32_16x16x32_bf16 v[4:7], v[166:169], v[214:217], v[4:7]
	v_mfma_f32_16x16x32_bf16 v[60:63], v[162:165], v[194:197], v[60:63]
	v_mfma_f32_16x16x32_bf16 v[52:55], v[170:173], v[194:197], v[52:55]
	v_mfma_f32_16x16x32_bf16 v[44:47], v[162:165], v[202:205], v[44:47]
	v_mfma_f32_16x16x32_bf16 v[36:39], v[170:173], v[202:205], v[36:39]
	v_mfma_f32_16x16x32_bf16 v[28:31], v[162:165], v[210:213], v[28:31]
	v_mfma_f32_16x16x32_bf16 v[20:23], v[170:173], v[210:213], v[20:23]
	v_mfma_f32_16x16x32_bf16 v[12:15], v[162:165], v[218:221], v[12:15]
	v_mfma_f32_16x16x32_bf16 v[4:7], v[170:173], v[218:221], v[4:7]
	v_mfma_f32_16x16x32_bf16 v[56:59], v[174:177], v[190:193], v[56:59]
	v_mfma_f32_16x16x32_bf16 v[48:51], v[182:185], v[190:193], v[48:51]
	v_mfma_f32_16x16x32_bf16 v[40:43], v[174:177], v[198:201], v[40:43]
	v_mfma_f32_16x16x32_bf16 v[32:35], v[182:185], v[198:201], v[32:35]
	v_mfma_f32_16x16x32_bf16 v[24:27], v[174:177], v[206:209], v[24:27]
	v_mfma_f32_16x16x32_bf16 v[16:19], v[182:185], v[206:209], v[16:19]
	v_mfma_f32_16x16x32_bf16 v[8:11], v[174:177], v[214:217], v[8:11]
	v_mfma_f32_16x16x32_bf16 v[0:3], v[182:185], v[214:217], v[0:3]
	v_mfma_f32_16x16x32_bf16 v[56:59], v[178:181], v[194:197], v[56:59]
	v_mfma_f32_16x16x32_bf16 v[48:51], v[186:189], v[194:197], v[48:51]
	v_mfma_f32_16x16x32_bf16 v[40:43], v[178:181], v[202:205], v[40:43]
	v_mfma_f32_16x16x32_bf16 v[32:35], v[186:189], v[202:205], v[32:35]
	v_mfma_f32_16x16x32_bf16 v[24:27], v[178:181], v[210:213], v[24:27]
	v_mfma_f32_16x16x32_bf16 v[16:19], v[186:189], v[210:213], v[16:19]
	v_mfma_f32_16x16x32_bf16 v[8:11], v[178:181], v[218:221], v[8:11]
	v_mfma_f32_16x16x32_bf16 v[0:3], v[186:189], v[218:221], v[0:3]
	s_setprio 0
	s_barrier
	s_add_i32 s41, 0, 0x18000
	v_add_u32_e32 v151, s41, v143
	v_add_u32_e32 v251, s41, v250
	s_add_i32 s57, 0, 0x1c000
	ds_read_b128 v[158:161], v151
	ds_read_b128 v[162:165], v251
	ds_read_b128 v[166:169], v151 offset:2048
	ds_read_b128 v[170:173], v251 offset:2048
	v_add_u32_e32 v151, s57, v143
	v_add_u32_e32 v251, s57, v250
	ds_read_b128 v[174:177], v151
	ds_read_b128 v[178:181], v251
	ds_read_b128 v[182:185], v151 offset:2048
	ds_read_b128 v[186:189], v251 offset:2048
	s_add_u32 s38, s70, 0x80000
	s_addc_u32 s39, s71, 0
	s_mov_b32 m0, s6
	v_lshl_add_u64 v[230:231], s[38:39], 0, v[128:129]
	ds_read_b128 v[190:193], v145 offset:32768
	ds_read_b128 v[194:197], v247 offset:32768
	ds_read_b128 v[198:201], v145 offset:34816
	ds_read_b128 v[202:205], v247 offset:34816
	ds_read_b128 v[206:209], v145 offset:36864
	ds_read_b128 v[210:213], v247 offset:36864
	ds_read_b128 v[214:217], v145 offset:38912
	ds_read_b128 v[218:221], v247 offset:38912
	global_load_lds_dwordx4 v[230:231], off
	v_lshl_add_u64 v[230:231], s[38:39], 0, v[132:133]
	s_mov_b32 m0, s7
	s_nop 0
	global_load_lds_dwordx4 v[230:231], off
	s_waitcnt vmcnt(8)
	s_waitcnt lgkmcnt(0)
	s_barrier
	s_setprio 1
	s_waitcnt lgkmcnt(0)
	v_mfma_f32_16x16x32_bf16 v[124:127], v[158:161], v[190:193], v[124:127]
	v_mfma_f32_16x16x32_bf16 v[116:119], v[166:169], v[190:193], v[116:119]
	v_mfma_f32_16x16x32_bf16 v[108:111], v[158:161], v[198:201], v[108:111]
	v_mfma_f32_16x16x32_bf16 v[100:103], v[166:169], v[198:201], v[100:103]
	v_mfma_f32_16x16x32_bf16 v[92:95], v[158:161], v[206:209], v[92:95]
	v_mfma_f32_16x16x32_bf16 v[84:87], v[166:169], v[206:209], v[84:87]
	v_mfma_f32_16x16x32_bf16 v[76:79], v[158:161], v[214:217], v[76:79]
	v_mfma_f32_16x16x32_bf16 v[68:71], v[166:169], v[214:217], v[68:71]
	v_mfma_f32_16x16x32_bf16 v[124:127], v[162:165], v[194:197], v[124:127]
	v_mfma_f32_16x16x32_bf16 v[116:119], v[170:173], v[194:197], v[116:119]
	v_mfma_f32_16x16x32_bf16 v[108:111], v[162:165], v[202:205], v[108:111]
	v_mfma_f32_16x16x32_bf16 v[100:103], v[170:173], v[202:205], v[100:103]
	v_mfma_f32_16x16x32_bf16 v[92:95], v[162:165], v[210:213], v[92:95]
	v_mfma_f32_16x16x32_bf16 v[84:87], v[170:173], v[210:213], v[84:87]
	v_mfma_f32_16x16x32_bf16 v[76:79], v[162:165], v[218:221], v[76:79]
	v_mfma_f32_16x16x32_bf16 v[68:71], v[170:173], v[218:221], v[68:71]
	v_mfma_f32_16x16x32_bf16 v[120:123], v[174:177], v[190:193], v[120:123]
	v_mfma_f32_16x16x32_bf16 v[112:115], v[182:185], v[190:193], v[112:115]
	v_mfma_f32_16x16x32_bf16 v[104:107], v[174:177], v[198:201], v[104:107]
	v_mfma_f32_16x16x32_bf16 v[96:99], v[182:185], v[198:201], v[96:99]
	v_mfma_f32_16x16x32_bf16 v[88:91], v[174:177], v[206:209], v[88:91]
	v_mfma_f32_16x16x32_bf16 v[80:83], v[182:185], v[206:209], v[80:83]
	v_mfma_f32_16x16x32_bf16 v[72:75], v[174:177], v[214:217], v[72:75]
	v_mfma_f32_16x16x32_bf16 v[64:67], v[182:185], v[214:217], v[64:67]
	v_mfma_f32_16x16x32_bf16 v[120:123], v[178:181], v[194:197], v[120:123]
	v_mfma_f32_16x16x32_bf16 v[112:115], v[186:189], v[194:197], v[112:115]
	v_mfma_f32_16x16x32_bf16 v[104:107], v[178:181], v[202:205], v[104:107]
	v_mfma_f32_16x16x32_bf16 v[96:99], v[186:189], v[202:205], v[96:99]
	v_mfma_f32_16x16x32_bf16 v[88:91], v[178:181], v[210:213], v[88:91]
	v_mfma_f32_16x16x32_bf16 v[80:83], v[186:189], v[210:213], v[80:83]
	v_mfma_f32_16x16x32_bf16 v[72:75], v[178:181], v[218:221], v[72:75]
	v_mfma_f32_16x16x32_bf16 v[64:67], v[186:189], v[218:221], v[64:67]
	s_setprio 0
	s_barrier
; #define PG8_STAGE(bufoff, gbase, voff) do { _Pragma("unroll") for (int _i = 0; _i < 2; ++_i) \
;         __builtin_amdgcn_global_load_lds((const unsigned*)((const char*)(gbase) + (voff)[_i]), (LAS unsigned*)(lds + (bufoff) + ldsw + _i * 8192), 16, 0, 0); } while (0)
; #define PG8_LDA(dst, b, h) do { _Pragma("unroll") for (int m = 0; m < 4; ++m) _Pragma("unroll") for (int k = 0; k < 2; ++k) dst[m][k] = *(const LAS bf16x8*)(lds + PG8_SA(b, h) + aoff + m * 2048 + k * 1024); } while (0)
; #define PG8_MMA(ai, bj, At, Bt) do { __builtin_amdgcn_s_setprio(1); _Pragma("unroll") for (int m = 0; m < 4; ++m) _Pragma("unroll") for (int n = 0; n < 2; ++n) _Pragma("unroll") for (int k = 0; k < 2; ++k) \
;         acc[ai][bj][m][n] = __builtin_amdgcn_mfma_f32_16x16x32_bf16(Bt[n][k], At[m][k], acc[ai][bj][m][n], 0, 0, 0); __builtin_amdgcn_s_setprio(0); } while (0)
; #define PG8_WAIT_V(n) asm volatile("s_waitcnt vmcnt(" #n ")" ::: "memory")
; #define PG8_WAIT_L(n) asm volatile("s_waitcnt lgkmcnt(" #n ")" ::: "memory")
; #define PG8_BAR __builtin_amdgcn_s_barrier()
; #define PG8_SCHED __builtin_amdgcn_sched_barrier(0)
; template <class Epi, class Sched>
; __device__ __forceinline__ void gemm_phase(LAS unsigned char* lds, const int K, const int lda, const int ldb, const Sched& S, const Epi& E) {
;     ...
;             PG8_LDA(At, 1, 1); PG8_STAGE(PG8_SB(1, 0), b3, voffB); PG8_STAGE(PG8_SB(1, 1), b3 + hB, voffB); PG8_STAGE(PG8_SA(1, 0), a3, voffA);
;             PG8_WAIT_V(8); PG8_WAIT_L(0); PG8_BAR; PG8_MMA(1, 0, At, B0); PG8_MMA(1, 1, At, B1); PG8_BAR; PG8_SCHED;
;         }
;         if (wr == 0) PG8_BAR;
	s_add_i32 s38, s41, s2
	v_lshl_add_u64 v[222:223], v[222:223], 0, s[52:53]
	s_mov_b32 m0, s38
	ds_read_b128 v[190:193], v145 offset:49152
	ds_read_b128 v[194:197], v247 offset:49152
	ds_read_b128 v[198:201], v145 offset:51200
	ds_read_b128 v[202:205], v247 offset:51200
	ds_read_b128 v[206:209], v145 offset:53248
	ds_read_b128 v[210:213], v247 offset:53248
	ds_read_b128 v[214:217], v145 offset:55296
	ds_read_b128 v[218:221], v247 offset:55296
	global_load_lds_dwordx4 v[222:223], off
	s_add_i32 m0, s38, 0x2000
	s_add_u32 s38, s68, 0x80080
	v_lshl_add_u64 v[222:223], v[224:225], 0, s[52:53]
	s_addc_u32 s39, s69, 0
	s_add_i32 s41, s57, s2
	global_load_lds_dwordx4 v[222:223], off
	v_lshl_add_u64 v[222:223], s[38:39], 0, v[130:131]
	s_mov_b32 m0, s41
	s_nop 0
	global_load_lds_dwordx4 v[222:223], off
	v_lshl_add_u64 v[222:223], s[38:39], 0, v[134:135]
	s_add_i32 m0, s41, 0x2000
	s_nop 0
	global_load_lds_dwordx4 v[222:223], off
	v_lshl_add_u64 v[222:223], v[226:227], 0, s[52:53]
	s_mov_b32 m0, s15
	s_nop 0
	global_load_lds_dwordx4 v[222:223], off
	v_lshl_add_u64 v[222:223], v[228:229], 0, s[52:53]
	s_mov_b32 m0, s17
	s_nop 0
	global_load_lds_dwordx4 v[222:223], off
	s_waitcnt vmcnt(8)
	s_waitcnt lgkmcnt(0)
	s_barrier
	s_setprio 1
	s_waitcnt lgkmcnt(0)
	v_mfma_f32_16x16x32_bf16 v[60:63], v[158:161], v[190:193], v[60:63]
	v_mfma_f32_16x16x32_bf16 v[52:55], v[166:169], v[190:193], v[52:55]
	v_mfma_f32_16x16x32_bf16 v[44:47], v[158:161], v[198:201], v[44:47]
	v_mfma_f32_16x16x32_bf16 v[36:39], v[166:169], v[198:201], v[36:39]
	v_mfma_f32_16x16x32_bf16 v[28:31], v[158:161], v[206:209], v[28:31]
	v_mfma_f32_16x16x32_bf16 v[20:23], v[166:169], v[206:209], v[20:23]
	v_mfma_f32_16x16x32_bf16 v[12:15], v[158:161], v[214:217], v[12:15]
	v_mfma_f32_16x16x32_bf16 v[4:7], v[166:169], v[214:217], v[4:7]
	v_mfma_f32_16x16x32_bf16 v[60:63], v[162:165], v[194:197], v[60:63]
	v_mfma_f32_16x16x32_bf16 v[52:55], v[170:173], v[194:197], v[52:55]
	v_mfma_f32_16x16x32_bf16 v[44:47], v[162:165], v[202:205], v[44:47]
	v_mfma_f32_16x16x32_bf16 v[36:39], v[170:173], v[202:205], v[36:39]
	v_mfma_f32_16x16x32_bf16 v[28:31], v[162:165], v[210:213], v[28:31]
	v_mfma_f32_16x16x32_bf16 v[20:23], v[170:173], v[210:213], v[20:23]
	v_mfma_f32_16x16x32_bf16 v[12:15], v[162:165], v[218:221], v[12:15]
	v_mfma_f32_16x16x32_bf16 v[4:7], v[170:173], v[218:221], v[4:7]
	v_mfma_f32_16x16x32_bf16 v[56:59], v[174:177], v[190:193], v[56:59]
	v_mfma_f32_16x16x32_bf16 v[48:51], v[182:185], v[190:193], v[48:51]
	v_mfma_f32_16x16x32_bf16 v[40:43], v[174:177], v[198:201], v[40:43]
	v_mfma_f32_16x16x32_bf16 v[32:35], v[182:185], v[198:201], v[32:35]
	v_mfma_f32_16x16x32_bf16 v[24:27], v[174:177], v[206:209], v[24:27]
	v_mfma_f32_16x16x32_bf16 v[16:19], v[182:185], v[206:209], v[16:19]
	v_mfma_f32_16x16x32_bf16 v[8:11], v[174:177], v[214:217], v[8:11]
	v_mfma_f32_16x16x32_bf16 v[0:3], v[182:185], v[214:217], v[0:3]
	v_mfma_f32_16x16x32_bf16 v[56:59], v[178:181], v[194:197], v[56:59]
	v_mfma_f32_16x16x32_bf16 v[48:51], v[186:189], v[194:197], v[48:51]
	v_mfma_f32_16x16x32_bf16 v[40:43], v[178:181], v[202:205], v[40:43]
	v_mfma_f32_16x16x32_bf16 v[32:35], v[186:189], v[202:205], v[32:35]
	v_mfma_f32_16x16x32_bf16 v[24:27], v[178:181], v[210:213], v[24:27]
	v_mfma_f32_16x16x32_bf16 v[16:19], v[186:189], v[210:213], v[16:19]
	v_mfma_f32_16x16x32_bf16 v[8:11], v[178:181], v[218:221], v[8:11]
	v_mfma_f32_16x16x32_bf16 v[0:3], v[186:189], v[218:221], v[0:3]
	s_setprio 0
	s_barrier
	s_add_i32 s29, s29, 2
	s_add_u32 s19, s19, 0x100
	s_addc_u32 s28, s28, 0
	s_add_u32 s64, s64, 0x100
	s_addc_u32 s65, s65, 0
	s_cmp_gt_u32 s29, 29
	s_cbranch_scc0 .LBB0_695
	s_and_b64 vcc, exec, s[54:55]
	s_cbranch_vccz .LBB0_698
	s_barrier

; #define PG8_STAGE(bufoff, gbase, voff) do { _Pragma("unroll") for (int _i = 0; _i < 2; ++_i) \
;         __builtin_amdgcn_global_load_lds((const unsigned*)((const char*)(gbase) + (voff)[_i]), (LAS unsigned*)(lds + (bufoff) + ldsw + _i * 8192), 16, 0, 0); } while (0)
; #define PG8_LDA(dst, b, h) do { _Pragma("unroll") for (int m = 0; m < 4; ++m) _Pragma("unroll") for (int k = 0; k < 2; ++k) dst[m][k] = *(const LAS bf16x8*)(lds + PG8_SA(b, h) + aoff + m * 2048 + k * 1024); } while (0)
; #define PG8_LDB(dst, b, h) do { _Pragma("unroll") for (int n = 0; n < 2; ++n) _Pragma("unroll") for (int k = 0; k < 2; ++k) dst[n][k] = *(const LAS bf16x8*)(lds + PG8_SB(b, h) + boff + n * 2048 + k * 1024); } while (0)
; #define PG8_MMA(ai, bj, At, Bt) do { __builtin_amdgcn_s_setprio(1); _Pragma("unroll") for (int m = 0; m < 4; ++m) _Pragma("unroll") for (int n = 0; n < 2; ++n) _Pragma("unroll") for (int k = 0; k < 2; ++k) \
;         acc[ai][bj][m][n] = __builtin_amdgcn_mfma_f32_16x16x32_bf16(Bt[n][k], At[m][k], acc[ai][bj][m][n], 0, 0, 0); __builtin_amdgcn_s_setprio(0); } while (0)
; #define PG8_WAIT_V(n) asm volatile("s_waitcnt vmcnt(" #n ")" ::: "memory")
; #define PG8_WAIT_L(n) asm volatile("s_waitcnt lgkmcnt(" #n ")" ::: "memory")
; #define PG8_BAR __builtin_amdgcn_s_barrier()
; #define PG8_SCHED __builtin_amdgcn_sched_barrier(0)
; template <class Epi, class Sched>
; __device__ __forceinline__ void gemm_phase(LAS unsigned char* lds, const int K, const int lda, const int ldb, const Sched& S, const Epi& E) {
;     ...
;         for (int t = 0; t < nt; t += 2) {
;             const bool last = (t == nt - 2);
;             const char* a1 = cA + (size_t)(t + 1) * kstep;
;             const char* a2 = last ? nA : cA + (size_t)(t + 2) * kstep; const char* b2 = last ? nB : cB + (size_t)(t + 2) * kstep;
;             const char* a3 = a2 + kstep; const char* b3 = b2 + kstep;
;             PG8_LDB(B0, 0, 0); PG8_LDB(B1, 0, 1); PG8_SCHED; PG8_LDA(At, 0, 0); PG8_STAGE(PG8_SA(1, 1), a1 + hA, voffA);
;             PG8_WAIT_V(8); PG8_WAIT_L(0); PG8_BAR; PG8_MMA(0, 0, At, B0); PG8_MMA(0, 1, At, B1); PG8_BAR; PG8_SCHED;
;             PG8_LDA(At, 0, 1); PG8_STAGE(PG8_SB(0, 0), b2, voffB); PG8_STAGE(PG8_SB(0, 1), b2 + hB, voffB); PG8_STAGE(PG8_SA(0, 0), a2, voffA);
;             PG8_WAIT_V(8); PG8_WAIT_L(0); PG8_BAR; PG8_MMA(1, 0, At, B0); PG8_MMA(1, 1, At, B1); PG8_BAR; PG8_SCHED;
.LBB0_889:
	ds_read_b128 v[104:107], v220
	ds_read_b128 v[112:115], v247
	ds_read_b128 v[124:127], v220 offset:2048
	ds_read_b128 v[140:143], v247 offset:2048
	ds_read_b128 v[144:147], v221
	ds_read_b128 v[148:151], v248
	ds_read_b128 v[152:155], v221 offset:2048
	ds_read_b128 v[156:159], v248 offset:2048
	s_add_u32 s29, s66, 0xfff80080
	s_addc_u32 s30, s67, -1
	s_cmp_eq_u32 s28, 28
	s_cselect_b32 s71, s18, s30
	s_cselect_b32 s70, s19, s29
	s_cselect_b32 s69, s24, s27
	s_cselect_b32 s68, s25, s26
	v_lshl_add_u64 v[208:209], s[66:67], 0, v[194:195]
	s_add_i32 m0, s2, 0xc000
	ds_read_b128 v[160:163], v222
	ds_read_b128 v[164:167], v246
	ds_read_b128 v[168:171], v222 offset:2048
	ds_read_b128 v[172:175], v246 offset:2048
	ds_read_b128 v[176:179], v222 offset:4096
	ds_read_b128 v[180:183], v246 offset:4096
	ds_read_b128 v[200:203], v222 offset:6144
	ds_read_b128 v[204:207], v246 offset:6144
	global_load_lds_dwordx4 v[208:209], off
	v_lshl_add_u64 v[208:209], s[66:67], 0, v[192:193]
	s_add_i32 m0, s2, 0xe000
	s_nop 0
	global_load_lds_dwordx4 v[208:209], off
	s_waitcnt vmcnt(8)
	s_waitcnt lgkmcnt(0)
	s_barrier
	s_setprio 1
	s_waitcnt lgkmcnt(0)
	v_mfma_f32_16x16x32_bf16 v[136:139], v[160:163], v[104:107], v[136:139]
	v_mfma_f32_16x16x32_bf16 v[132:135], v[160:163], v[124:127], v[132:135]
	v_mfma_f32_16x16x32_bf16 v[116:119], v[168:171], v[104:107], v[116:119]
	v_mfma_f32_16x16x32_bf16 v[108:111], v[168:171], v[124:127], v[108:111]
	v_mfma_f32_16x16x32_bf16 v[92:95], v[176:179], v[104:107], v[92:95]
	v_mfma_f32_16x16x32_bf16 v[88:91], v[176:179], v[124:127], v[88:91]
	v_mfma_f32_16x16x32_bf16 v[76:79], v[200:203], v[104:107], v[76:79]
	v_mfma_f32_16x16x32_bf16 v[72:75], v[200:203], v[124:127], v[72:75]
	v_mfma_f32_16x16x32_bf16 v[136:139], v[164:167], v[112:115], v[136:139]
	v_mfma_f32_16x16x32_bf16 v[132:135], v[164:167], v[140:143], v[132:135]
	v_mfma_f32_16x16x32_bf16 v[116:119], v[172:175], v[112:115], v[116:119]
	v_mfma_f32_16x16x32_bf16 v[108:111], v[172:175], v[140:143], v[108:111]
	v_mfma_f32_16x16x32_bf16 v[92:95], v[180:183], v[112:115], v[92:95]
	v_mfma_f32_16x16x32_bf16 v[88:91], v[180:183], v[140:143], v[88:91]
	v_mfma_f32_16x16x32_bf16 v[76:79], v[204:207], v[112:115], v[76:79]
	v_mfma_f32_16x16x32_bf16 v[72:75], v[204:207], v[140:143], v[72:75]
	v_mfma_f32_16x16x32_bf16 v[128:131], v[160:163], v[144:147], v[128:131]
	v_mfma_f32_16x16x32_bf16 v[120:123], v[160:163], v[152:155], v[120:123]
	v_mfma_f32_16x16x32_bf16 v[100:103], v[168:171], v[144:147], v[100:103]
	v_mfma_f32_16x16x32_bf16 v[96:99], v[168:171], v[152:155], v[96:99]
	v_mfma_f32_16x16x32_bf16 v[84:87], v[176:179], v[144:147], v[84:87]
	v_mfma_f32_16x16x32_bf16 v[80:83], v[176:179], v[152:155], v[80:83]
	v_mfma_f32_16x16x32_bf16 v[68:71], v[200:203], v[144:147], v[68:71]
	v_mfma_f32_16x16x32_bf16 v[64:67], v[200:203], v[152:155], v[64:67]
	v_mfma_f32_16x16x32_bf16 v[128:131], v[164:167], v[148:151], v[128:131]
	v_mfma_f32_16x16x32_bf16 v[120:123], v[164:167], v[156:159], v[120:123]
	v_mfma_f32_16x16x32_bf16 v[100:103], v[172:175], v[148:151], v[100:103]
	v_mfma_f32_16x16x32_bf16 v[96:99], v[172:175], v[156:159], v[96:99]
	v_mfma_f32_16x16x32_bf16 v[84:87], v[180:183], v[148:151], v[84:87]
	v_mfma_f32_16x16x32_bf16 v[80:83], v[180:183], v[156:159], v[80:83]
	v_mfma_f32_16x16x32_bf16 v[68:71], v[204:207], v[148:151], v[68:71]
	v_mfma_f32_16x16x32_bf16 v[64:67], v[204:207], v[156:159], v[64:67]
	s_setprio 0
	s_barrier
	s_add_i32 s29, s0, s1
	v_lshl_add_u64 v[208:209], s[68:69], 0, v[186:187]
	s_mov_b32 m0, s29
	ds_read_b128 v[160:163], v222 offset:16384
	ds_read_b128 v[164:167], v246 offset:16384
	ds_read_b128 v[168:171], v222 offset:18432
	ds_read_b128 v[172:175], v246 offset:18432
	ds_read_b128 v[176:179], v222 offset:20480
	ds_read_b128 v[180:183], v246 offset:20480
	ds_read_b128 v[200:203], v222 offset:22528
	ds_read_b128 v[204:207], v246 offset:22528
	global_load_lds_dwordx4 v[208:209], off
	s_add_i32 m0, s29, 0x2000
	s_add_u32 s30, s68, 0x80000
	v_lshl_add_u64 v[210:211], s[68:69], 0, v[190:191]
	s_addc_u32 s31, s69, 0
	s_add_i32 s29, s23, s1
	global_load_lds_dwordx4 v[210:211], off
	v_lshl_add_u64 v[212:213], s[30:31], 0, v[186:187]
	s_mov_b32 m0, s29
	v_lshl_add_u64 v[214:215], s[70:71], 0, v[188:189]
	global_load_lds_dwordx4 v[212:213], off
	v_lshl_add_u64 v[212:213], s[30:31], 0, v[190:191]
	s_add_i32 m0, s29, 0x2000
	s_nop 0
	global_load_lds_dwordx4 v[212:213], off
	v_lshl_add_u64 v[212:213], s[70:71], 0, v[184:185]
	s_mov_b32 m0, s2
	s_nop 0
	global_load_lds_dwordx4 v[212:213], off
	s_mov_b32 m0, s4
	s_nop 0
	global_load_lds_dwordx4 v[214:215], off
	s_waitcnt vmcnt(8)
	s_waitcnt lgkmcnt(0)
	s_barrier
; #define PG8_STAGE(bufoff, gbase, voff) do { _Pragma("unroll") for (int _i = 0; _i < 2; ++_i) \
;         __builtin_amdgcn_global_load_lds((const unsigned*)((const char*)(gbase) + (voff)[_i]), (LAS unsigned*)(lds + (bufoff) + ldsw + _i * 8192), 16, 0, 0); } while (0)
; #define PG8_LDA(dst, b, h) do { _Pragma("unroll") for (int m = 0; m < 4; ++m) _Pragma("unroll") for (int k = 0; k < 2; ++k) dst[m][k] = *(const LAS bf16x8*)(lds + PG8_SA(b, h) + aoff + m * 2048 + k * 1024); } while (0)
; #define PG8_LDB(dst, b, h) do { _Pragma("unroll") for (int n = 0; n < 2; ++n) _Pragma("unroll") for (int k = 0; k < 2; ++k) dst[n][k] = *(const LAS bf16x8*)(lds + PG8_SB(b, h) + boff + n * 2048 + k * 1024); } while (0)
; #define PG8_MMA(ai, bj, At, Bt) do { __builtin_amdgcn_s_setprio(1); _Pragma("unroll") for (int m = 0; m < 4; ++m) _Pragma("unroll") for (int n = 0; n < 2; ++n) _Pragma("unroll") for (int k = 0; k < 2; ++k) \
;         acc[ai][bj][m][n] = __builtin_amdgcn_mfma_f32_16x16x32_bf16(Bt[n][k], At[m][k], acc[ai][bj][m][n], 0, 0, 0); __builtin_amdgcn_s_setprio(0); } while (0)
; #define PG8_WAIT_V(n) asm volatile("s_waitcnt vmcnt(" #n ")" ::: "memory")
; #define PG8_WAIT_L(n) asm volatile("s_waitcnt lgkmcnt(" #n ")" ::: "memory")
; #define PG8_BAR __builtin_amdgcn_s_barrier()
; #define PG8_SCHED __builtin_amdgcn_sched_barrier(0)
; template <class Epi, class Sched>
; __device__ __forceinline__ void gemm_phase(LAS unsigned char* lds, const int K, const int lda, const int ldb, const Sched& S, const Epi& E) {
;     ...
;             PG8_WAIT_V(8); PG8_WAIT_L(0); PG8_BAR; PG8_MMA(1, 0, At, B0); PG8_MMA(1, 1, At, B1); PG8_BAR; PG8_SCHED;
;             PG8_LDB(B0, 1, 0); PG8_LDB(B1, 1, 1); PG8_SCHED; PG8_LDA(At, 1, 0); PG8_STAGE(PG8_SA(0, 1), a2 + hA, voffA);
;             PG8_WAIT_V(8); PG8_WAIT_L(0); PG8_BAR; PG8_MMA(0, 0, At, B0); PG8_MMA(0, 1, At, B1); PG8_BAR; PG8_SCHED;
	s_setprio 1
	s_waitcnt lgkmcnt(0)
	v_mfma_f32_16x16x32_bf16 v[60:63], v[160:163], v[104:107], v[60:63]
	v_mfma_f32_16x16x32_bf16 v[56:59], v[160:163], v[124:127], v[56:59]
	v_mfma_f32_16x16x32_bf16 v[44:47], v[168:171], v[104:107], v[44:47]
	v_mfma_f32_16x16x32_bf16 v[40:43], v[168:171], v[124:127], v[40:43]
	v_mfma_f32_16x16x32_bf16 v[28:31], v[176:179], v[104:107], v[28:31]
	v_mfma_f32_16x16x32_bf16 v[24:27], v[176:179], v[124:127], v[24:27]
	v_mfma_f32_16x16x32_bf16 v[12:15], v[200:203], v[104:107], v[12:15]
	v_mfma_f32_16x16x32_bf16 v[8:11], v[200:203], v[124:127], v[8:11]
	v_mfma_f32_16x16x32_bf16 v[60:63], v[164:167], v[112:115], v[60:63]
	v_mfma_f32_16x16x32_bf16 v[56:59], v[164:167], v[140:143], v[56:59]
	v_mfma_f32_16x16x32_bf16 v[44:47], v[172:175], v[112:115], v[44:47]
	v_mfma_f32_16x16x32_bf16 v[40:43], v[172:175], v[140:143], v[40:43]
	v_mfma_f32_16x16x32_bf16 v[28:31], v[180:183], v[112:115], v[28:31]
	v_mfma_f32_16x16x32_bf16 v[24:27], v[180:183], v[140:143], v[24:27]
	v_mfma_f32_16x16x32_bf16 v[12:15], v[204:207], v[112:115], v[12:15]
	v_mfma_f32_16x16x32_bf16 v[8:11], v[204:207], v[140:143], v[8:11]
	v_mfma_f32_16x16x32_bf16 v[52:55], v[160:163], v[144:147], v[52:55]
	v_mfma_f32_16x16x32_bf16 v[48:51], v[160:163], v[152:155], v[48:51]
	v_mfma_f32_16x16x32_bf16 v[36:39], v[168:171], v[144:147], v[36:39]
	v_mfma_f32_16x16x32_bf16 v[32:35], v[168:171], v[152:155], v[32:35]
	v_mfma_f32_16x16x32_bf16 v[20:23], v[176:179], v[144:147], v[20:23]
	v_mfma_f32_16x16x32_bf16 v[16:19], v[176:179], v[152:155], v[16:19]
	v_mfma_f32_16x16x32_bf16 v[4:7], v[200:203], v[144:147], v[4:7]
	v_mfma_f32_16x16x32_bf16 v[0:3], v[200:203], v[152:155], v[0:3]
	v_mfma_f32_16x16x32_bf16 v[52:55], v[164:167], v[148:151], v[52:55]
	v_mfma_f32_16x16x32_bf16 v[48:51], v[164:167], v[156:159], v[48:51]
	v_mfma_f32_16x16x32_bf16 v[36:39], v[172:175], v[148:151], v[36:39]
	v_mfma_f32_16x16x32_bf16 v[32:35], v[172:175], v[156:159], v[32:35]
	v_mfma_f32_16x16x32_bf16 v[20:23], v[180:183], v[148:151], v[20:23]
	v_mfma_f32_16x16x32_bf16 v[16:19], v[180:183], v[156:159], v[16:19]
	v_mfma_f32_16x16x32_bf16 v[4:7], v[204:207], v[148:151], v[4:7]
	v_mfma_f32_16x16x32_bf16 v[0:3], v[204:207], v[156:159], v[0:3]
	s_setprio 0
	s_barrier
	s_add_i32 s29, 0, 0x18000
	s_add_i32 s34, 0, 0x1c000
	v_add_u32_e32 v140, s29, v217
	v_add_u32_e32 v250, s29, v249
	v_add_u32_e32 v156, 0x19000, v217
	v_add_u32_e32 v251, 0x19000, v249
	ds_read_b128 v[104:107], v140
	ds_read_b128 v[112:115], v250
	ds_read_b128 v[124:127], v140 offset:2048
	ds_read_b128 v[140:143], v250 offset:2048
	ds_read_b128 v[144:147], v156
	ds_read_b128 v[148:151], v251
	ds_read_b128 v[152:155], v156 offset:2048
	ds_read_b128 v[156:159], v251 offset:2048
	s_add_u32 s30, s70, 0x80000
	s_addc_u32 s31, s71, 0
	s_mov_b32 m0, s5
	v_lshl_add_u64 v[226:227], s[30:31], 0, v[184:185]
	ds_read_b128 v[160:163], v222 offset:32768
	ds_read_b128 v[164:167], v246 offset:32768
	ds_read_b128 v[168:171], v222 offset:34816
	ds_read_b128 v[172:175], v246 offset:34816
	ds_read_b128 v[176:179], v222 offset:36864
	ds_read_b128 v[180:183], v246 offset:36864
	ds_read_b128 v[200:203], v222 offset:38912
	ds_read_b128 v[204:207], v246 offset:38912
	global_load_lds_dwordx4 v[226:227], off
	v_lshl_add_u64 v[226:227], s[30:31], 0, v[188:189]
	s_mov_b32 m0, s6
	s_nop 0
	global_load_lds_dwordx4 v[226:227], off
	s_waitcnt vmcnt(8)
	s_waitcnt lgkmcnt(0)
	s_barrier
	s_setprio 1
	s_waitcnt lgkmcnt(0)
	v_mfma_f32_16x16x32_bf16 v[136:139], v[160:163], v[104:107], v[136:139]
	v_mfma_f32_16x16x32_bf16 v[132:135], v[160:163], v[124:127], v[132:135]
	v_mfma_f32_16x16x32_bf16 v[116:119], v[168:171], v[104:107], v[116:119]
	v_mfma_f32_16x16x32_bf16 v[108:111], v[168:171], v[124:127], v[108:111]
	v_mfma_f32_16x16x32_bf16 v[92:95], v[176:179], v[104:107], v[92:95]
	v_mfma_f32_16x16x32_bf16 v[88:91], v[176:179], v[124:127], v[88:91]
	v_mfma_f32_16x16x32_bf16 v[76:79], v[200:203], v[104:107], v[76:79]
	v_mfma_f32_16x16x32_bf16 v[72:75], v[200:203], v[124:127], v[72:75]
	v_mfma_f32_16x16x32_bf16 v[136:139], v[164:167], v[112:115], v[136:139]
	v_mfma_f32_16x16x32_bf16 v[132:135], v[164:167], v[140:143], v[132:135]
	v_mfma_f32_16x16x32_bf16 v[116:119], v[172:175], v[112:115], v[116:119]
	v_mfma_f32_16x16x32_bf16 v[108:111], v[172:175], v[140:143], v[108:111]
	v_mfma_f32_16x16x32_bf16 v[92:95], v[180:183], v[112:115], v[92:95]
	v_mfma_f32_16x16x32_bf16 v[88:91], v[180:183], v[140:143], v[88:91]
	v_mfma_f32_16x16x32_bf16 v[76:79], v[204:207], v[112:115], v[76:79]
	v_mfma_f32_16x16x32_bf16 v[72:75], v[204:207], v[140:143], v[72:75]
	v_mfma_f32_16x16x32_bf16 v[128:131], v[160:163], v[144:147], v[128:131]
	v_mfma_f32_16x16x32_bf16 v[120:123], v[160:163], v[152:155], v[120:123]
	v_mfma_f32_16x16x32_bf16 v[100:103], v[168:171], v[144:147], v[100:103]
	v_mfma_f32_16x16x32_bf16 v[96:99], v[168:171], v[152:155], v[96:99]
	v_mfma_f32_16x16x32_bf16 v[84:87], v[176:179], v[144:147], v[84:87]
	v_mfma_f32_16x16x32_bf16 v[80:83], v[176:179], v[152:155], v[80:83]
	v_mfma_f32_16x16x32_bf16 v[68:71], v[200:203], v[144:147], v[68:71]
	v_mfma_f32_16x16x32_bf16 v[64:67], v[200:203], v[152:155], v[64:67]
	v_mfma_f32_16x16x32_bf16 v[128:131], v[164:167], v[148:151], v[128:131]
	v_mfma_f32_16x16x32_bf16 v[120:123], v[164:167], v[156:159], v[120:123]
	v_mfma_f32_16x16x32_bf16 v[100:103], v[172:175], v[148:151], v[100:103]
	v_mfma_f32_16x16x32_bf16 v[96:99], v[172:175], v[156:159], v[96:99]
	v_mfma_f32_16x16x32_bf16 v[84:87], v[180:183], v[148:151], v[84:87]
	v_mfma_f32_16x16x32_bf16 v[80:83], v[180:183], v[156:159], v[80:83]
	v_mfma_f32_16x16x32_bf16 v[68:71], v[204:207], v[148:151], v[68:71]
	v_mfma_f32_16x16x32_bf16 v[64:67], v[204:207], v[156:159], v[64:67]
	s_setprio 0
	s_barrier
; #define PG8_STAGE(bufoff, gbase, voff) do { _Pragma("unroll") for (int _i = 0; _i < 2; ++_i) \
;         __builtin_amdgcn_global_load_lds((const unsigned*)((const char*)(gbase) + (voff)[_i]), (LAS unsigned*)(lds + (bufoff) + ldsw + _i * 8192), 16, 0, 0); } while (0)
; #define PG8_LDA(dst, b, h) do { _Pragma("unroll") for (int m = 0; m < 4; ++m) _Pragma("unroll") for (int k = 0; k < 2; ++k) dst[m][k] = *(const LAS bf16x8*)(lds + PG8_SA(b, h) + aoff + m * 2048 + k * 1024); } while (0)
; #define PG8_MMA(ai, bj, At, Bt) do { __builtin_amdgcn_s_setprio(1); _Pragma("unroll") for (int m = 0; m < 4; ++m) _Pragma("unroll") for (int n = 0; n < 2; ++n) _Pragma("unroll") for (int k = 0; k < 2; ++k) \
;         acc[ai][bj][m][n] = __builtin_amdgcn_mfma_f32_16x16x32_bf16(Bt[n][k], At[m][k], acc[ai][bj][m][n], 0, 0, 0); __builtin_amdgcn_s_setprio(0); } while (0)
; #define PG8_WAIT_V(n) asm volatile("s_waitcnt vmcnt(" #n ")" ::: "memory")
; #define PG8_WAIT_L(n) asm volatile("s_waitcnt lgkmcnt(" #n ")" ::: "memory")
; #define PG8_BAR __builtin_amdgcn_s_barrier()
; #define PG8_SCHED __builtin_amdgcn_sched_barrier(0)
; template <class Epi, class Sched>
; __device__ __forceinline__ void gemm_phase(LAS unsigned char* lds, const int K, const int lda, const int ldb, const Sched& S, const Epi& E) {
;     ...
;             PG8_LDA(At, 1, 1); PG8_STAGE(PG8_SB(1, 0), b3, voffB); PG8_STAGE(PG8_SB(1, 1), b3 + hB, voffB); PG8_STAGE(PG8_SA(1, 0), a3, voffA);
;             PG8_WAIT_V(8); PG8_WAIT_L(0); PG8_BAR; PG8_MMA(1, 0, At, B0); PG8_MMA(1, 1, At, B1); PG8_BAR; PG8_SCHED;
;         }
;         if (wr == 0) PG8_BAR;
	s_add_i32 s29, s29, s1
	v_lshl_add_u64 v[208:209], v[208:209], 0, s[52:53]
	s_mov_b32 m0, s29
	ds_read_b128 v[160:163], v222 offset:49152
	ds_read_b128 v[164:167], v246 offset:49152
	ds_read_b128 v[168:171], v222 offset:51200
	ds_read_b128 v[172:175], v246 offset:51200
	ds_read_b128 v[176:179], v222 offset:53248
	ds_read_b128 v[180:183], v246 offset:53248
	ds_read_b128 v[200:203], v222 offset:55296
	ds_read_b128 v[204:207], v246 offset:55296
	global_load_lds_dwordx4 v[208:209], off
	s_add_i32 m0, s29, 0x2000
	s_add_u32 s30, s68, 0x80080
	v_lshl_add_u64 v[208:209], v[210:211], 0, s[52:53]
	s_addc_u32 s31, s69, 0
	s_add_i32 s29, s34, s1
	global_load_lds_dwordx4 v[208:209], off
	v_lshl_add_u64 v[208:209], s[30:31], 0, v[186:187]
	s_mov_b32 m0, s29
	s_nop 0
	global_load_lds_dwordx4 v[208:209], off
	v_lshl_add_u64 v[208:209], s[30:31], 0, v[190:191]
	s_add_i32 m0, s29, 0x2000
	s_nop 0
	global_load_lds_dwordx4 v[208:209], off
	v_lshl_add_u64 v[208:209], v[212:213], 0, s[52:53]
	s_mov_b32 m0, s14
	s_nop 0
	global_load_lds_dwordx4 v[208:209], off
	v_lshl_add_u64 v[208:209], v[214:215], 0, s[52:53]
	s_mov_b32 m0, s15
	s_nop 0
	global_load_lds_dwordx4 v[208:209], off
	s_waitcnt vmcnt(8)
	s_waitcnt lgkmcnt(0)
	s_barrier
	s_setprio 1
	s_waitcnt lgkmcnt(0)
	v_mfma_f32_16x16x32_bf16 v[60:63], v[160:163], v[104:107], v[60:63]
	v_mfma_f32_16x16x32_bf16 v[56:59], v[160:163], v[124:127], v[56:59]
	v_mfma_f32_16x16x32_bf16 v[44:47], v[168:171], v[104:107], v[44:47]
	v_mfma_f32_16x16x32_bf16 v[40:43], v[168:171], v[124:127], v[40:43]
	v_mfma_f32_16x16x32_bf16 v[28:31], v[176:179], v[104:107], v[28:31]
	v_mfma_f32_16x16x32_bf16 v[24:27], v[176:179], v[124:127], v[24:27]
	v_mfma_f32_16x16x32_bf16 v[12:15], v[200:203], v[104:107], v[12:15]
	v_mfma_f32_16x16x32_bf16 v[8:11], v[200:203], v[124:127], v[8:11]
	v_mfma_f32_16x16x32_bf16 v[60:63], v[164:167], v[112:115], v[60:63]
	v_mfma_f32_16x16x32_bf16 v[56:59], v[164:167], v[140:143], v[56:59]
	v_mfma_f32_16x16x32_bf16 v[44:47], v[172:175], v[112:115], v[44:47]
	v_mfma_f32_16x16x32_bf16 v[40:43], v[172:175], v[140:143], v[40:43]
	v_mfma_f32_16x16x32_bf16 v[28:31], v[180:183], v[112:115], v[28:31]
	v_mfma_f32_16x16x32_bf16 v[24:27], v[180:183], v[140:143], v[24:27]
	v_mfma_f32_16x16x32_bf16 v[12:15], v[204:207], v[112:115], v[12:15]
	v_mfma_f32_16x16x32_bf16 v[8:11], v[204:207], v[140:143], v[8:11]
	v_mfma_f32_16x16x32_bf16 v[52:55], v[160:163], v[144:147], v[52:55]
	v_mfma_f32_16x16x32_bf16 v[48:51], v[160:163], v[152:155], v[48:51]
	v_mfma_f32_16x16x32_bf16 v[36:39], v[168:171], v[144:147], v[36:39]
	v_mfma_f32_16x16x32_bf16 v[32:35], v[168:171], v[152:155], v[32:35]
	v_mfma_f32_16x16x32_bf16 v[20:23], v[176:179], v[144:147], v[20:23]
	v_mfma_f32_16x16x32_bf16 v[16:19], v[176:179], v[152:155], v[16:19]
	v_mfma_f32_16x16x32_bf16 v[4:7], v[200:203], v[144:147], v[4:7]
	v_mfma_f32_16x16x32_bf16 v[0:3], v[200:203], v[152:155], v[0:3]
	v_mfma_f32_16x16x32_bf16 v[52:55], v[164:167], v[148:151], v[52:55]
	v_mfma_f32_16x16x32_bf16 v[48:51], v[164:167], v[156:159], v[48:51]
	v_mfma_f32_16x16x32_bf16 v[36:39], v[172:175], v[148:151], v[36:39]
	v_mfma_f32_16x16x32_bf16 v[32:35], v[172:175], v[156:159], v[32:35]
	v_mfma_f32_16x16x32_bf16 v[20:23], v[180:183], v[148:151], v[20:23]
	v_mfma_f32_16x16x32_bf16 v[16:19], v[180:183], v[156:159], v[16:19]
	v_mfma_f32_16x16x32_bf16 v[4:7], v[204:207], v[148:151], v[4:7]
	v_mfma_f32_16x16x32_bf16 v[0:3], v[204:207], v[156:159], v[0:3]
	s_setprio 0
	s_barrier
	s_add_i32 s28, s28, 2
	s_add_u32 s26, s26, 0x100
	s_addc_u32 s27, s27, 0
	s_add_u32 s66, s66, 0x100
	s_addc_u32 s67, s67, 0
	s_cmp_gt_u32 s28, 29
	s_cbranch_scc0 .LBB0_889
	s_and_b64 vcc, exec, s[54:55]
	s_cbranch_vccz .LBB0_892
	s_barrier

; #define PG8_STAGE(bufoff, gbase, voff) do { _Pragma("unroll") for (int _i = 0; _i < 2; ++_i) \
;         __builtin_amdgcn_global_load_lds((const unsigned*)((const char*)(gbase) + (voff)[_i]), (LAS unsigned*)(lds + (bufoff) + ldsw + _i * 8192), 16, 0, 0); } while (0)
; #define PG8_LDA(dst, b, h) do { _Pragma("unroll") for (int m = 0; m < 4; ++m) _Pragma("unroll") for (int k = 0; k < 2; ++k) dst[m][k] = *(const LAS bf16x8*)(lds + PG8_SA(b, h) + aoff + m * 2048 + k * 1024); } while (0)
; #define PG8_LDB(dst, b, h) do { _Pragma("unroll") for (int n = 0; n < 2; ++n) _Pragma("unroll") for (int k = 0; k < 2; ++k) dst[n][k] = *(const LAS bf16x8*)(lds + PG8_SB(b, h) + boff + n * 2048 + k * 1024); } while (0)
; #define PG8_MMA(ai, bj, At, Bt) do { __builtin_amdgcn_s_setprio(1); _Pragma("unroll") for (int m = 0; m < 4; ++m) _Pragma("unroll") for (int n = 0; n < 2; ++n) _Pragma("unroll") for (int k = 0; k < 2; ++k) \
;         acc[ai][bj][m][n] = __builtin_amdgcn_mfma_f32_16x16x32_bf16(Bt[n][k], At[m][k], acc[ai][bj][m][n], 0, 0, 0); __builtin_amdgcn_s_setprio(0); } while (0)
; #define PG8_WAIT_V(n) asm volatile("s_waitcnt vmcnt(" #n ")" ::: "memory")
; #define PG8_WAIT_L(n) asm volatile("s_waitcnt lgkmcnt(" #n ")" ::: "memory")
; #define PG8_BAR __builtin_amdgcn_s_barrier()
; #define PG8_SCHED __builtin_amdgcn_sched_barrier(0)
; template <class Epi, class Sched>
; __device__ __forceinline__ void gemm_phase(LAS unsigned char* lds, const int K, const int lda, const int ldb, const Sched& S, const Epi& E) {
;     ...
;         for (int t = 0; t < nt; t += 2) {
;             const bool last = (t == nt - 2);
;             const char* a1 = cA + (size_t)(t + 1) * kstep;
;             const char* a2 = last ? nA : cA + (size_t)(t + 2) * kstep; const char* b2 = last ? nB : cB + (size_t)(t + 2) * kstep;
;             const char* a3 = a2 + kstep; const char* b3 = b2 + kstep;
;             PG8_LDB(B0, 0, 0); PG8_LDB(B1, 0, 1); PG8_SCHED; PG8_LDA(At, 0, 0); PG8_STAGE(PG8_SA(1, 1), a1 + hA, voffA);
;             PG8_WAIT_V(8); PG8_WAIT_L(0); PG8_BAR; PG8_MMA(0, 0, At, B0); PG8_MMA(0, 1, At, B1); PG8_BAR; PG8_SCHED;
;             PG8_LDA(At, 0, 1); PG8_STAGE(PG8_SB(0, 0), b2, voffB); PG8_STAGE(PG8_SB(0, 1), b2 + hB, voffB); PG8_STAGE(PG8_SA(0, 0), a2, voffA);
;             PG8_WAIT_V(8); PG8_WAIT_L(0); PG8_BAR; PG8_MMA(1, 0, At, B0); PG8_MMA(1, 1, At, B1); PG8_BAR; PG8_SCHED;
.LBB0_963:
	ds_read_b128 v[174:177], v188
	ds_read_b128 v[178:181], v147
	ds_read_b128 v[190:193], v188 offset:2048
	ds_read_b128 v[194:197], v147 offset:2048
	ds_read_b128 v[198:201], v189
	ds_read_b128 v[202:205], v149
	ds_read_b128 v[206:209], v189 offset:2048
	ds_read_b128 v[210:213], v149 offset:2048
	s_add_u32 s61, s66, 0xfff80080
	s_addc_u32 s68, s67, -1
	s_cmp_eq_u32 s59, 28
	s_cselect_b32 s71, s11, s68
	s_cselect_b32 s70, s18, s61
	s_cselect_b32 s69, s39, s57
	s_cselect_b32 s68, s41, s55
	v_lshl_add_u64 v[182:183], s[66:67], 0, v[140:141]
	s_add_i32 m0, s1, 0xc000
	ds_read_b128 v[214:217], v163
	ds_read_b128 v[218:221], v145
	ds_read_b128 v[222:225], v163 offset:2048
	ds_read_b128 v[226:229], v145 offset:2048
	ds_read_b128 v[230:233], v163 offset:4096
	ds_read_b128 v[236:239], v145 offset:4096
	ds_read_b128 v[240:243], v163 offset:6144
	ds_read_b128 v[244:247], v145 offset:6144
	global_load_lds_dwordx4 v[182:183], off
	v_lshl_add_u64 v[182:183], s[66:67], 0, v[138:139]
	s_add_i32 m0, s1, 0xe000
	s_nop 0
	global_load_lds_dwordx4 v[182:183], off
	s_waitcnt vmcnt(8)
	s_waitcnt lgkmcnt(0)
	s_barrier
	s_setprio 1
	s_waitcnt lgkmcnt(0)
	v_mfma_f32_16x16x32_bf16 v[124:127], v[214:217], v[174:177], v[124:127]
	v_mfma_f32_16x16x32_bf16 v[120:123], v[214:217], v[190:193], v[120:123]
	v_mfma_f32_16x16x32_bf16 v[108:111], v[222:225], v[174:177], v[108:111]
	v_mfma_f32_16x16x32_bf16 v[104:107], v[222:225], v[190:193], v[104:107]
	v_mfma_f32_16x16x32_bf16 v[92:95], v[230:233], v[174:177], v[92:95]
	v_mfma_f32_16x16x32_bf16 v[88:91], v[230:233], v[190:193], v[88:91]
	v_mfma_f32_16x16x32_bf16 v[76:79], v[240:243], v[174:177], v[76:79]
	v_mfma_f32_16x16x32_bf16 v[72:75], v[240:243], v[190:193], v[72:75]
	v_mfma_f32_16x16x32_bf16 v[124:127], v[218:221], v[178:181], v[124:127]
	v_mfma_f32_16x16x32_bf16 v[120:123], v[218:221], v[194:197], v[120:123]
	v_mfma_f32_16x16x32_bf16 v[108:111], v[226:229], v[178:181], v[108:111]
	v_mfma_f32_16x16x32_bf16 v[104:107], v[226:229], v[194:197], v[104:107]
	v_mfma_f32_16x16x32_bf16 v[92:95], v[236:239], v[178:181], v[92:95]
	v_mfma_f32_16x16x32_bf16 v[88:91], v[236:239], v[194:197], v[88:91]
	v_mfma_f32_16x16x32_bf16 v[76:79], v[244:247], v[178:181], v[76:79]
	v_mfma_f32_16x16x32_bf16 v[72:75], v[244:247], v[194:197], v[72:75]
	v_mfma_f32_16x16x32_bf16 v[116:119], v[214:217], v[198:201], v[116:119]
	v_mfma_f32_16x16x32_bf16 v[112:115], v[214:217], v[206:209], v[112:115]
	v_mfma_f32_16x16x32_bf16 v[100:103], v[222:225], v[198:201], v[100:103]
	v_mfma_f32_16x16x32_bf16 v[96:99], v[222:225], v[206:209], v[96:99]
	v_mfma_f32_16x16x32_bf16 v[84:87], v[230:233], v[198:201], v[84:87]
	v_mfma_f32_16x16x32_bf16 v[80:83], v[230:233], v[206:209], v[80:83]
	v_mfma_f32_16x16x32_bf16 v[68:71], v[240:243], v[198:201], v[68:71]
	v_mfma_f32_16x16x32_bf16 v[64:67], v[240:243], v[206:209], v[64:67]
	v_mfma_f32_16x16x32_bf16 v[116:119], v[218:221], v[202:205], v[116:119]
	v_mfma_f32_16x16x32_bf16 v[112:115], v[218:221], v[210:213], v[112:115]
	v_mfma_f32_16x16x32_bf16 v[100:103], v[226:229], v[202:205], v[100:103]
	v_mfma_f32_16x16x32_bf16 v[96:99], v[226:229], v[210:213], v[96:99]
	v_mfma_f32_16x16x32_bf16 v[84:87], v[236:239], v[202:205], v[84:87]
	v_mfma_f32_16x16x32_bf16 v[80:83], v[236:239], v[210:213], v[80:83]
	v_mfma_f32_16x16x32_bf16 v[68:71], v[244:247], v[202:205], v[68:71]
	v_mfma_f32_16x16x32_bf16 v[64:67], v[244:247], v[210:213], v[64:67]
	s_setprio 0
	s_barrier
	s_add_i32 s61, s30, s2
	v_lshl_add_u64 v[182:183], s[68:69], 0, v[132:133]
	s_mov_b32 m0, s61
	ds_read_b128 v[214:217], v163 offset:16384
	ds_read_b128 v[218:221], v145 offset:16384
	ds_read_b128 v[222:225], v163 offset:18432
	ds_read_b128 v[226:229], v145 offset:18432
	ds_read_b128 v[230:233], v163 offset:20480
	ds_read_b128 v[236:239], v145 offset:20480
	ds_read_b128 v[240:243], v163 offset:22528
	ds_read_b128 v[244:247], v145 offset:22528
	global_load_lds_dwordx4 v[182:183], off
	s_add_i32 m0, s61, 0x2000
	s_add_u32 s72, s68, 0x80000
	v_lshl_add_u64 v[234:235], s[68:69], 0, v[128:129]
	s_addc_u32 s73, s69, 0
	s_add_i32 s61, s31, s2
	global_load_lds_dwordx4 v[234:235], off
	v_lshl_add_u64 v[248:249], s[72:73], 0, v[132:133]
	s_mov_b32 m0, s61
	v_lshl_add_u64 v[250:251], s[70:71], 0, v[130:131]
	global_load_lds_dwordx4 v[248:249], off
	v_lshl_add_u64 v[248:249], s[72:73], 0, v[128:129]
	s_add_i32 m0, s61, 0x2000
	s_nop 0
	global_load_lds_dwordx4 v[248:249], off
	v_lshl_add_u64 v[248:249], s[70:71], 0, v[134:135]
	s_mov_b32 m0, s1
	s_nop 0
	global_load_lds_dwordx4 v[248:249], off
	s_mov_b32 m0, s6
	s_nop 0
	global_load_lds_dwordx4 v[250:251], off
	s_waitcnt vmcnt(8)
	s_waitcnt lgkmcnt(0)
	s_barrier
; #define PG8_STAGE(bufoff, gbase, voff) do { _Pragma("unroll") for (int _i = 0; _i < 2; ++_i) \
;         __builtin_amdgcn_global_load_lds((const unsigned*)((const char*)(gbase) + (voff)[_i]), (LAS unsigned*)(lds + (bufoff) + ldsw + _i * 8192), 16, 0, 0); } while (0)
; #define PG8_LDA(dst, b, h) do { _Pragma("unroll") for (int m = 0; m < 4; ++m) _Pragma("unroll") for (int k = 0; k < 2; ++k) dst[m][k] = *(const LAS bf16x8*)(lds + PG8_SA(b, h) + aoff + m * 2048 + k * 1024); } while (0)
; #define PG8_LDB(dst, b, h) do { _Pragma("unroll") for (int n = 0; n < 2; ++n) _Pragma("unroll") for (int k = 0; k < 2; ++k) dst[n][k] = *(const LAS bf16x8*)(lds + PG8_SB(b, h) + boff + n * 2048 + k * 1024); } while (0)
; #define PG8_MMA(ai, bj, At, Bt) do { __builtin_amdgcn_s_setprio(1); _Pragma("unroll") for (int m = 0; m < 4; ++m) _Pragma("unroll") for (int n = 0; n < 2; ++n) _Pragma("unroll") for (int k = 0; k < 2; ++k) \
;         acc[ai][bj][m][n] = __builtin_amdgcn_mfma_f32_16x16x32_bf16(Bt[n][k], At[m][k], acc[ai][bj][m][n], 0, 0, 0); __builtin_amdgcn_s_setprio(0); } while (0)
; #define PG8_WAIT_V(n) asm volatile("s_waitcnt vmcnt(" #n ")" ::: "memory")
; #define PG8_WAIT_L(n) asm volatile("s_waitcnt lgkmcnt(" #n ")" ::: "memory")
; #define PG8_BAR __builtin_amdgcn_s_barrier()
; #define PG8_SCHED __builtin_amdgcn_sched_barrier(0)
; template <class Epi, class Sched>
; __device__ __forceinline__ void gemm_phase(LAS unsigned char* lds, const int K, const int lda, const int ldb, const Sched& S, const Epi& E) {
;     ...
;             PG8_WAIT_V(8); PG8_WAIT_L(0); PG8_BAR; PG8_MMA(1, 0, At, B0); PG8_MMA(1, 1, At, B1); PG8_BAR; PG8_SCHED;
;             PG8_LDB(B0, 1, 0); PG8_LDB(B1, 1, 1); PG8_SCHED; PG8_LDA(At, 1, 0); PG8_STAGE(PG8_SA(0, 1), a2 + hA, voffA);
;             PG8_WAIT_V(8); PG8_WAIT_L(0); PG8_BAR; PG8_MMA(0, 0, At, B0); PG8_MMA(0, 1, At, B1); PG8_BAR; PG8_SCHED;
	s_setprio 1
	s_waitcnt lgkmcnt(0)
	v_mfma_f32_16x16x32_bf16 v[60:63], v[214:217], v[174:177], v[60:63]
	v_mfma_f32_16x16x32_bf16 v[56:59], v[214:217], v[190:193], v[56:59]
	v_mfma_f32_16x16x32_bf16 v[44:47], v[222:225], v[174:177], v[44:47]
	v_mfma_f32_16x16x32_bf16 v[40:43], v[222:225], v[190:193], v[40:43]
	v_mfma_f32_16x16x32_bf16 v[28:31], v[230:233], v[174:177], v[28:31]
	v_mfma_f32_16x16x32_bf16 v[24:27], v[230:233], v[190:193], v[24:27]
	v_mfma_f32_16x16x32_bf16 v[12:15], v[240:243], v[174:177], v[12:15]
	v_mfma_f32_16x16x32_bf16 v[8:11], v[240:243], v[190:193], v[8:11]
	v_mfma_f32_16x16x32_bf16 v[60:63], v[218:221], v[178:181], v[60:63]
	v_mfma_f32_16x16x32_bf16 v[56:59], v[218:221], v[194:197], v[56:59]
	v_mfma_f32_16x16x32_bf16 v[44:47], v[226:229], v[178:181], v[44:47]
	v_mfma_f32_16x16x32_bf16 v[40:43], v[226:229], v[194:197], v[40:43]
	v_mfma_f32_16x16x32_bf16 v[28:31], v[236:239], v[178:181], v[28:31]
	v_mfma_f32_16x16x32_bf16 v[24:27], v[236:239], v[194:197], v[24:27]
	v_mfma_f32_16x16x32_bf16 v[12:15], v[244:247], v[178:181], v[12:15]
	v_mfma_f32_16x16x32_bf16 v[8:11], v[244:247], v[194:197], v[8:11]
	v_mfma_f32_16x16x32_bf16 v[52:55], v[214:217], v[198:201], v[52:55]
	v_mfma_f32_16x16x32_bf16 v[48:51], v[214:217], v[206:209], v[48:51]
	v_mfma_f32_16x16x32_bf16 v[36:39], v[222:225], v[198:201], v[36:39]
	v_mfma_f32_16x16x32_bf16 v[32:35], v[222:225], v[206:209], v[32:35]
	v_mfma_f32_16x16x32_bf16 v[20:23], v[230:233], v[198:201], v[20:23]
	v_mfma_f32_16x16x32_bf16 v[16:19], v[230:233], v[206:209], v[16:19]
	v_mfma_f32_16x16x32_bf16 v[4:7], v[240:243], v[198:201], v[4:7]
	v_mfma_f32_16x16x32_bf16 v[0:3], v[240:243], v[206:209], v[0:3]
	v_mfma_f32_16x16x32_bf16 v[52:55], v[218:221], v[202:205], v[52:55]
	v_mfma_f32_16x16x32_bf16 v[48:51], v[218:221], v[210:213], v[48:51]
	v_mfma_f32_16x16x32_bf16 v[36:39], v[226:229], v[202:205], v[36:39]
	v_mfma_f32_16x16x32_bf16 v[32:35], v[226:229], v[210:213], v[32:35]
	v_mfma_f32_16x16x32_bf16 v[20:23], v[236:239], v[202:205], v[20:23]
	v_mfma_f32_16x16x32_bf16 v[16:19], v[236:239], v[210:213], v[16:19]
	v_mfma_f32_16x16x32_bf16 v[4:7], v[244:247], v[202:205], v[4:7]
	v_mfma_f32_16x16x32_bf16 v[0:3], v[244:247], v[210:213], v[0:3]
	s_setprio 0
	s_barrier
	s_add_i32 s61, 0, 0x18000
	v_add_u32_e32 v143, s61, v161
	v_add_u32_e32 v158, s61, v151
	s_add_i32 s72, 0, 0x1c000
	ds_read_b128 v[174:177], v143
	ds_read_b128 v[178:181], v158
	ds_read_b128 v[190:193], v143 offset:2048
	ds_read_b128 v[194:197], v158 offset:2048
	v_add_u32_e32 v143, 0x19000, v161
	v_add_u32_e32 v158, 0x19000, v151
	ds_read_b128 v[198:201], v143
	ds_read_b128 v[202:205], v158
	ds_read_b128 v[206:209], v143 offset:2048
	ds_read_b128 v[210:213], v158 offset:2048
	s_add_u32 s70, s70, 0x80000
	s_addc_u32 s71, s71, 0
	s_mov_b32 m0, s7
	v_lshl_add_u64 v[252:253], s[70:71], 0, v[134:135]
	ds_read_b128 v[214:217], v163 offset:32768
	ds_read_b128 v[218:221], v145 offset:32768
	ds_read_b128 v[222:225], v163 offset:34816
	ds_read_b128 v[226:229], v145 offset:34816
	ds_read_b128 v[230:233], v163 offset:36864
	ds_read_b128 v[236:239], v145 offset:36864
	ds_read_b128 v[240:243], v163 offset:38912
	ds_read_b128 v[244:247], v145 offset:38912
	global_load_lds_dwordx4 v[252:253], off
	v_lshl_add_u64 v[252:253], s[70:71], 0, v[130:131]
	s_mov_b32 m0, s14
	s_nop 0
	global_load_lds_dwordx4 v[252:253], off
	s_waitcnt vmcnt(8)
	s_waitcnt lgkmcnt(0)
	s_barrier
	s_setprio 1
	s_waitcnt lgkmcnt(0)
	v_mfma_f32_16x16x32_bf16 v[124:127], v[214:217], v[174:177], v[124:127]
	v_mfma_f32_16x16x32_bf16 v[120:123], v[214:217], v[190:193], v[120:123]
	v_mfma_f32_16x16x32_bf16 v[108:111], v[222:225], v[174:177], v[108:111]
	v_mfma_f32_16x16x32_bf16 v[104:107], v[222:225], v[190:193], v[104:107]
	v_mfma_f32_16x16x32_bf16 v[92:95], v[230:233], v[174:177], v[92:95]
	v_mfma_f32_16x16x32_bf16 v[88:91], v[230:233], v[190:193], v[88:91]
	v_mfma_f32_16x16x32_bf16 v[76:79], v[240:243], v[174:177], v[76:79]
	v_mfma_f32_16x16x32_bf16 v[72:75], v[240:243], v[190:193], v[72:75]
	v_mfma_f32_16x16x32_bf16 v[124:127], v[218:221], v[178:181], v[124:127]
	v_mfma_f32_16x16x32_bf16 v[120:123], v[218:221], v[194:197], v[120:123]
	v_mfma_f32_16x16x32_bf16 v[108:111], v[226:229], v[178:181], v[108:111]
	v_mfma_f32_16x16x32_bf16 v[104:107], v[226:229], v[194:197], v[104:107]
	v_mfma_f32_16x16x32_bf16 v[92:95], v[236:239], v[178:181], v[92:95]
	v_mfma_f32_16x16x32_bf16 v[88:91], v[236:239], v[194:197], v[88:91]
	v_mfma_f32_16x16x32_bf16 v[76:79], v[244:247], v[178:181], v[76:79]
	v_mfma_f32_16x16x32_bf16 v[72:75], v[244:247], v[194:197], v[72:75]
	v_mfma_f32_16x16x32_bf16 v[116:119], v[214:217], v[198:201], v[116:119]
	v_mfma_f32_16x16x32_bf16 v[112:115], v[214:217], v[206:209], v[112:115]
	v_mfma_f32_16x16x32_bf16 v[100:103], v[222:225], v[198:201], v[100:103]
	v_mfma_f32_16x16x32_bf16 v[96:99], v[222:225], v[206:209], v[96:99]
	v_mfma_f32_16x16x32_bf16 v[84:87], v[230:233], v[198:201], v[84:87]
	v_mfma_f32_16x16x32_bf16 v[80:83], v[230:233], v[206:209], v[80:83]
	v_mfma_f32_16x16x32_bf16 v[68:71], v[240:243], v[198:201], v[68:71]
	v_mfma_f32_16x16x32_bf16 v[64:67], v[240:243], v[206:209], v[64:67]
	v_mfma_f32_16x16x32_bf16 v[116:119], v[218:221], v[202:205], v[116:119]
	v_mfma_f32_16x16x32_bf16 v[112:115], v[218:221], v[210:213], v[112:115]
	v_mfma_f32_16x16x32_bf16 v[100:103], v[226:229], v[202:205], v[100:103]
	v_mfma_f32_16x16x32_bf16 v[96:99], v[226:229], v[210:213], v[96:99]
	v_mfma_f32_16x16x32_bf16 v[84:87], v[236:239], v[202:205], v[84:87]
	v_mfma_f32_16x16x32_bf16 v[80:83], v[236:239], v[210:213], v[80:83]
	v_mfma_f32_16x16x32_bf16 v[68:71], v[244:247], v[202:205], v[68:71]
	v_mfma_f32_16x16x32_bf16 v[64:67], v[244:247], v[210:213], v[64:67]
	s_setprio 0
	s_barrier
; #define PG8_STAGE(bufoff, gbase, voff) do { _Pragma("unroll") for (int _i = 0; _i < 2; ++_i) \
;         __builtin_amdgcn_global_load_lds((const unsigned*)((const char*)(gbase) + (voff)[_i]), (LAS unsigned*)(lds + (bufoff) + ldsw + _i * 8192), 16, 0, 0); } while (0)
; #define PG8_LDA(dst, b, h) do { _Pragma("unroll") for (int m = 0; m < 4; ++m) _Pragma("unroll") for (int k = 0; k < 2; ++k) dst[m][k] = *(const LAS bf16x8*)(lds + PG8_SA(b, h) + aoff + m * 2048 + k * 1024); } while (0)
; #define PG8_MMA(ai, bj, At, Bt) do { __builtin_amdgcn_s_setprio(1); _Pragma("unroll") for (int m = 0; m < 4; ++m) _Pragma("unroll") for (int n = 0; n < 2; ++n) _Pragma("unroll") for (int k = 0; k < 2; ++k) \
;         acc[ai][bj][m][n] = __builtin_amdgcn_mfma_f32_16x16x32_bf16(Bt[n][k], At[m][k], acc[ai][bj][m][n], 0, 0, 0); __builtin_amdgcn_s_setprio(0); } while (0)
; #define PG8_WAIT_V(n) asm volatile("s_waitcnt vmcnt(" #n ")" ::: "memory")
; #define PG8_WAIT_L(n) asm volatile("s_waitcnt lgkmcnt(" #n ")" ::: "memory")
; #define PG8_BAR __builtin_amdgcn_s_barrier()
; #define PG8_SCHED __builtin_amdgcn_sched_barrier(0)
; template <class Epi, class Sched>
; __device__ __forceinline__ void gemm_phase(LAS unsigned char* lds, const int K, const int lda, const int ldb, const Sched& S, const Epi& E) {
;     ...
;             PG8_LDA(At, 1, 1); PG8_STAGE(PG8_SB(1, 0), b3, voffB); PG8_STAGE(PG8_SB(1, 1), b3 + hB, voffB); PG8_STAGE(PG8_SA(1, 0), a3, voffA);
;             PG8_WAIT_V(8); PG8_WAIT_L(0); PG8_BAR; PG8_MMA(1, 0, At, B0); PG8_MMA(1, 1, At, B1); PG8_BAR; PG8_SCHED;
;         }
;         if (wr == 0) PG8_BAR;
	s_add_i32 s61, s61, s2
	v_lshl_add_u64 v[182:183], v[182:183], 0, s[50:51]
	s_mov_b32 m0, s61
	ds_read_b128 v[214:217], v163 offset:49152
	ds_read_b128 v[218:221], v145 offset:49152
	ds_read_b128 v[222:225], v163 offset:51200
	ds_read_b128 v[226:229], v145 offset:51200
	ds_read_b128 v[230:233], v163 offset:53248
	ds_read_b128 v[236:239], v145 offset:53248
	ds_read_b128 v[240:243], v163 offset:55296
	ds_read_b128 v[244:247], v145 offset:55296
	global_load_lds_dwordx4 v[182:183], off
	s_add_i32 m0, s61, 0x2000
	s_add_u32 s68, s68, 0x80080
	v_lshl_add_u64 v[182:183], v[234:235], 0, s[50:51]
	s_addc_u32 s69, s69, 0
	s_add_i32 s61, s72, s2
	global_load_lds_dwordx4 v[182:183], off
	v_lshl_add_u64 v[182:183], s[68:69], 0, v[132:133]
	s_mov_b32 m0, s61
	s_nop 0
	global_load_lds_dwordx4 v[182:183], off
	v_lshl_add_u64 v[182:183], s[68:69], 0, v[128:129]
	s_add_i32 m0, s61, 0x2000
	s_nop 0
	global_load_lds_dwordx4 v[182:183], off
	v_lshl_add_u64 v[182:183], v[248:249], 0, s[50:51]
	s_mov_b32 m0, s17
	s_nop 0
	global_load_lds_dwordx4 v[182:183], off
	v_lshl_add_u64 v[182:183], v[250:251], 0, s[50:51]
	s_mov_b32 m0, s21
	s_nop 0
	global_load_lds_dwordx4 v[182:183], off
	s_waitcnt vmcnt(8)
	s_waitcnt lgkmcnt(0)
	s_barrier
	s_setprio 1
	s_waitcnt lgkmcnt(0)
	v_mfma_f32_16x16x32_bf16 v[60:63], v[214:217], v[174:177], v[60:63]
	v_mfma_f32_16x16x32_bf16 v[56:59], v[214:217], v[190:193], v[56:59]
	v_mfma_f32_16x16x32_bf16 v[44:47], v[222:225], v[174:177], v[44:47]
	v_mfma_f32_16x16x32_bf16 v[40:43], v[222:225], v[190:193], v[40:43]
	v_mfma_f32_16x16x32_bf16 v[28:31], v[230:233], v[174:177], v[28:31]
	v_mfma_f32_16x16x32_bf16 v[24:27], v[230:233], v[190:193], v[24:27]
	v_mfma_f32_16x16x32_bf16 v[12:15], v[240:243], v[174:177], v[12:15]
	v_mfma_f32_16x16x32_bf16 v[8:11], v[240:243], v[190:193], v[8:11]
	v_mfma_f32_16x16x32_bf16 v[60:63], v[218:221], v[178:181], v[60:63]
	v_mfma_f32_16x16x32_bf16 v[56:59], v[218:221], v[194:197], v[56:59]
	v_mfma_f32_16x16x32_bf16 v[44:47], v[226:229], v[178:181], v[44:47]
	v_mfma_f32_16x16x32_bf16 v[40:43], v[226:229], v[194:197], v[40:43]
	v_mfma_f32_16x16x32_bf16 v[28:31], v[236:239], v[178:181], v[28:31]
	v_mfma_f32_16x16x32_bf16 v[24:27], v[236:239], v[194:197], v[24:27]
	v_mfma_f32_16x16x32_bf16 v[12:15], v[244:247], v[178:181], v[12:15]
	v_mfma_f32_16x16x32_bf16 v[8:11], v[244:247], v[194:197], v[8:11]
	v_mfma_f32_16x16x32_bf16 v[52:55], v[214:217], v[198:201], v[52:55]
	v_mfma_f32_16x16x32_bf16 v[48:51], v[214:217], v[206:209], v[48:51]
	v_mfma_f32_16x16x32_bf16 v[36:39], v[222:225], v[198:201], v[36:39]
	v_mfma_f32_16x16x32_bf16 v[32:35], v[222:225], v[206:209], v[32:35]
	v_mfma_f32_16x16x32_bf16 v[20:23], v[230:233], v[198:201], v[20:23]
	v_mfma_f32_16x16x32_bf16 v[16:19], v[230:233], v[206:209], v[16:19]
	v_mfma_f32_16x16x32_bf16 v[4:7], v[240:243], v[198:201], v[4:7]
	v_mfma_f32_16x16x32_bf16 v[0:3], v[240:243], v[206:209], v[0:3]
	v_mfma_f32_16x16x32_bf16 v[52:55], v[218:221], v[202:205], v[52:55]
	v_mfma_f32_16x16x32_bf16 v[48:51], v[218:221], v[210:213], v[48:51]
	v_mfma_f32_16x16x32_bf16 v[36:39], v[226:229], v[202:205], v[36:39]
	v_mfma_f32_16x16x32_bf16 v[32:35], v[226:229], v[210:213], v[32:35]
	v_mfma_f32_16x16x32_bf16 v[20:23], v[236:239], v[202:205], v[20:23]
	v_mfma_f32_16x16x32_bf16 v[16:19], v[236:239], v[210:213], v[16:19]
	v_mfma_f32_16x16x32_bf16 v[4:7], v[244:247], v[202:205], v[4:7]
	v_mfma_f32_16x16x32_bf16 v[0:3], v[244:247], v[210:213], v[0:3]
	s_setprio 0
	s_barrier
	s_add_i32 s59, s59, 2
	s_add_u32 s55, s55, 0x100
	s_addc_u32 s57, s57, 0
	s_add_u32 s66, s66, 0x100
	s_addc_u32 s67, s67, 0
	s_cmp_gt_u32 s59, 29
	s_cbranch_scc0 .LBB0_963
	s_and_b64 vcc, exec, s[52:53]
	s_cbranch_vccz .LBB0_966
	s_barrier

; #define PG8_STAGE(bufoff, gbase, voff) do { _Pragma("unroll") for (int _i = 0; _i < 2; ++_i) \
;         __builtin_amdgcn_global_load_lds((const unsigned*)((const char*)(gbase) + (voff)[_i]), (LAS unsigned*)(lds + (bufoff) + ldsw + _i * 8192), 16, 0, 0); } while (0)
; #define PG8_LDA(dst, b, h) do { _Pragma("unroll") for (int m = 0; m < 4; ++m) _Pragma("unroll") for (int k = 0; k < 2; ++k) dst[m][k] = *(const LAS bf16x8*)(lds + PG8_SA(b, h) + aoff + m * 2048 + k * 1024); } while (0)
; #define PG8_LDB(dst, b, h) do { _Pragma("unroll") for (int n = 0; n < 2; ++n) _Pragma("unroll") for (int k = 0; k < 2; ++k) dst[n][k] = *(const LAS bf16x8*)(lds + PG8_SB(b, h) + boff + n * 2048 + k * 1024); } while (0)
; #define PG8_MMA(ai, bj, At, Bt) do { __builtin_amdgcn_s_setprio(1); _Pragma("unroll") for (int m = 0; m < 4; ++m) _Pragma("unroll") for (int n = 0; n < 2; ++n) _Pragma("unroll") for (int k = 0; k < 2; ++k) \
;         acc[ai][bj][m][n] = __builtin_amdgcn_mfma_f32_16x16x32_bf16(Bt[n][k], At[m][k], acc[ai][bj][m][n], 0, 0, 0); __builtin_amdgcn_s_setprio(0); } while (0)
; #define PG8_WAIT_V(n) asm volatile("s_waitcnt vmcnt(" #n ")" ::: "memory")
; #define PG8_WAIT_L(n) asm volatile("s_waitcnt lgkmcnt(" #n ")" ::: "memory")
; #define PG8_BAR __builtin_amdgcn_s_barrier()
; #define PG8_SCHED __builtin_amdgcn_sched_barrier(0)
; template <class Epi, class Sched>
; __device__ __forceinline__ void gemm_phase(LAS unsigned char* lds, const int K, const int lda, const int ldb, const Sched& S, const Epi& E) {
;     ...
;         for (int t = 0; t < nt; t += 2) {
;             const bool last = (t == nt - 2);
;             const char* a1 = cA + (size_t)(t + 1) * kstep;
;             const char* a2 = last ? nA : cA + (size_t)(t + 2) * kstep; const char* b2 = last ? nB : cB + (size_t)(t + 2) * kstep;
;             const char* a3 = a2 + kstep; const char* b3 = b2 + kstep;
;             PG8_LDB(B0, 0, 0); PG8_LDB(B1, 0, 1); PG8_SCHED; PG8_LDA(At, 0, 0); PG8_STAGE(PG8_SA(1, 1), a1 + hA, voffA);
;             PG8_WAIT_V(8); PG8_WAIT_L(0); PG8_BAR; PG8_MMA(0, 0, At, B0); PG8_MMA(0, 1, At, B1); PG8_BAR; PG8_SCHED;
;             PG8_LDA(At, 0, 1); PG8_STAGE(PG8_SB(0, 0), b2, voffB); PG8_STAGE(PG8_SB(0, 1), b2 + hB, voffB); PG8_STAGE(PG8_SA(0, 0), a2, voffA);
;             PG8_WAIT_V(8); PG8_WAIT_L(0); PG8_BAR; PG8_MMA(1, 0, At, B0); PG8_MMA(1, 1, At, B1); PG8_BAR; PG8_SCHED;
.LBB0_1180:
	ds_read_b128 v[156:159], v151
	ds_read_b128 v[160:163], v151 offset:1024
	ds_read_b128 v[164:167], v151 offset:2048
	ds_read_b128 v[168:171], v151 offset:3072
	ds_read_b128 v[172:175], v152
	ds_read_b128 v[176:179], v152 offset:1024
	ds_read_b128 v[180:183], v152 offset:2048
	ds_read_b128 v[184:187], v152 offset:3072
	s_add_u32 s60, s12, 0xfff00080
	s_addc_u32 s61, s13, -1
	s_cmp_eq_u32 s74, 28
	s_cselect_b32 s63, s53, s61
	s_cselect_b32 s62, s52, s60
	s_cselect_b32 s61, s59, s57
	s_cselect_b32 s60, s58, s21
	v_lshl_add_u64 v[146:147], s[12:13], 0, v[140:141]
	s_add_i32 m0, s15, 0xc000
	ds_read_b128 v[188:191], v153
	ds_read_b128 v[192:195], v153 offset:1024
	ds_read_b128 v[196:199], v153 offset:2048
	ds_read_b128 v[200:203], v153 offset:3072
	ds_read_b128 v[204:207], v153 offset:4096
	ds_read_b128 v[208:211], v153 offset:5120
	ds_read_b128 v[212:215], v153 offset:6144
	ds_read_b128 v[216:219], v153 offset:7168
	global_load_lds_dwordx4 v[146:147], off
	v_lshl_add_u64 v[146:147], s[12:13], 0, v[138:139]
	s_add_i32 m0, s15, 0xe000
	s_nop 0
	global_load_lds_dwordx4 v[146:147], off
	s_waitcnt vmcnt(8)
	s_waitcnt lgkmcnt(0)
	s_barrier
	s_setprio 1
	s_waitcnt lgkmcnt(0)
	v_mfma_f32_16x16x32_bf16 v[124:127], v[156:159], v[188:191], v[124:127]
	v_mfma_f32_16x16x32_bf16 v[120:123], v[164:167], v[188:191], v[120:123]
	v_mfma_f32_16x16x32_bf16 v[108:111], v[156:159], v[196:199], v[108:111]
	v_mfma_f32_16x16x32_bf16 v[104:107], v[164:167], v[196:199], v[104:107]
	v_mfma_f32_16x16x32_bf16 v[92:95], v[156:159], v[204:207], v[92:95]
	v_mfma_f32_16x16x32_bf16 v[88:91], v[164:167], v[204:207], v[88:91]
	v_mfma_f32_16x16x32_bf16 v[76:79], v[156:159], v[212:215], v[76:79]
	v_mfma_f32_16x16x32_bf16 v[72:75], v[164:167], v[212:215], v[72:75]
	v_mfma_f32_16x16x32_bf16 v[124:127], v[160:163], v[192:195], v[124:127]
	v_mfma_f32_16x16x32_bf16 v[120:123], v[168:171], v[192:195], v[120:123]
	v_mfma_f32_16x16x32_bf16 v[108:111], v[160:163], v[200:203], v[108:111]
	v_mfma_f32_16x16x32_bf16 v[104:107], v[168:171], v[200:203], v[104:107]
	v_mfma_f32_16x16x32_bf16 v[92:95], v[160:163], v[208:211], v[92:95]
	v_mfma_f32_16x16x32_bf16 v[88:91], v[168:171], v[208:211], v[88:91]
	v_mfma_f32_16x16x32_bf16 v[76:79], v[160:163], v[216:219], v[76:79]
	v_mfma_f32_16x16x32_bf16 v[72:75], v[168:171], v[216:219], v[72:75]
	v_mfma_f32_16x16x32_bf16 v[116:119], v[172:175], v[188:191], v[116:119]
	v_mfma_f32_16x16x32_bf16 v[112:115], v[180:183], v[188:191], v[112:115]
	v_mfma_f32_16x16x32_bf16 v[100:103], v[172:175], v[196:199], v[100:103]
	v_mfma_f32_16x16x32_bf16 v[96:99], v[180:183], v[196:199], v[96:99]
	v_mfma_f32_16x16x32_bf16 v[84:87], v[172:175], v[204:207], v[84:87]
	v_mfma_f32_16x16x32_bf16 v[80:83], v[180:183], v[204:207], v[80:83]
	v_mfma_f32_16x16x32_bf16 v[68:71], v[172:175], v[212:215], v[68:71]
	v_mfma_f32_16x16x32_bf16 v[64:67], v[180:183], v[212:215], v[64:67]
	v_mfma_f32_16x16x32_bf16 v[116:119], v[176:179], v[192:195], v[116:119]
	v_mfma_f32_16x16x32_bf16 v[112:115], v[184:187], v[192:195], v[112:115]
	v_mfma_f32_16x16x32_bf16 v[100:103], v[176:179], v[200:203], v[100:103]
	v_mfma_f32_16x16x32_bf16 v[96:99], v[184:187], v[200:203], v[96:99]
	v_mfma_f32_16x16x32_bf16 v[84:87], v[176:179], v[208:211], v[84:87]
	v_mfma_f32_16x16x32_bf16 v[80:83], v[184:187], v[208:211], v[80:83]
	v_mfma_f32_16x16x32_bf16 v[68:71], v[176:179], v[216:219], v[68:71]
	v_mfma_f32_16x16x32_bf16 v[64:67], v[184:187], v[216:219], v[64:67]
	s_setprio 0
	s_barrier
	s_add_i32 s75, s0, s14
	v_lshl_add_u64 v[146:147], s[60:61], 0, v[132:133]
	s_mov_b32 m0, s75
	ds_read_b128 v[188:191], v153 offset:16384
	ds_read_b128 v[192:195], v153 offset:17408
	ds_read_b128 v[196:199], v153 offset:18432
	ds_read_b128 v[200:203], v153 offset:19456
	ds_read_b128 v[204:207], v153 offset:20480
	ds_read_b128 v[208:211], v153 offset:21504
	ds_read_b128 v[212:215], v153 offset:22528
	ds_read_b128 v[216:219], v153 offset:23552
	global_load_lds_dwordx4 v[146:147], off
	s_add_i32 m0, s75, 0x2000
	s_add_u32 s76, s60, 0x400000
	v_lshl_add_u64 v[220:221], s[60:61], 0, v[128:129]
	s_addc_u32 s77, s61, 0
	s_add_i32 s75, s38, s14
	global_load_lds_dwordx4 v[220:221], off
	v_lshl_add_u64 v[222:223], s[76:77], 0, v[132:133]
	s_mov_b32 m0, s75
	v_lshl_add_u64 v[224:225], s[62:63], 0, v[130:131]
	global_load_lds_dwordx4 v[222:223], off
	v_lshl_add_u64 v[222:223], s[76:77], 0, v[128:129]
	s_add_i32 m0, s75, 0x2000
	s_nop 0
	global_load_lds_dwordx4 v[222:223], off
	v_lshl_add_u64 v[222:223], s[62:63], 0, v[134:135]
	s_mov_b32 m0, s15
	s_nop 0
	global_load_lds_dwordx4 v[222:223], off
	s_mov_b32 m0, s18
	s_nop 0
	global_load_lds_dwordx4 v[224:225], off
	s_waitcnt vmcnt(8)
	s_waitcnt lgkmcnt(0)
	s_barrier
; #define PG8_STAGE(bufoff, gbase, voff) do { _Pragma("unroll") for (int _i = 0; _i < 2; ++_i) \
;         __builtin_amdgcn_global_load_lds((const unsigned*)((const char*)(gbase) + (voff)[_i]), (LAS unsigned*)(lds + (bufoff) + ldsw + _i * 8192), 16, 0, 0); } while (0)
; #define PG8_LDA(dst, b, h) do { _Pragma("unroll") for (int m = 0; m < 4; ++m) _Pragma("unroll") for (int k = 0; k < 2; ++k) dst[m][k] = *(const LAS bf16x8*)(lds + PG8_SA(b, h) + aoff + m * 2048 + k * 1024); } while (0)
; #define PG8_LDB(dst, b, h) do { _Pragma("unroll") for (int n = 0; n < 2; ++n) _Pragma("unroll") for (int k = 0; k < 2; ++k) dst[n][k] = *(const LAS bf16x8*)(lds + PG8_SB(b, h) + boff + n * 2048 + k * 1024); } while (0)
; #define PG8_MMA(ai, bj, At, Bt) do { __builtin_amdgcn_s_setprio(1); _Pragma("unroll") for (int m = 0; m < 4; ++m) _Pragma("unroll") for (int n = 0; n < 2; ++n) _Pragma("unroll") for (int k = 0; k < 2; ++k) \
;         acc[ai][bj][m][n] = __builtin_amdgcn_mfma_f32_16x16x32_bf16(Bt[n][k], At[m][k], acc[ai][bj][m][n], 0, 0, 0); __builtin_amdgcn_s_setprio(0); } while (0)
; #define PG8_WAIT_V(n) asm volatile("s_waitcnt vmcnt(" #n ")" ::: "memory")
; #define PG8_WAIT_L(n) asm volatile("s_waitcnt lgkmcnt(" #n ")" ::: "memory")
; #define PG8_BAR __builtin_amdgcn_s_barrier()
; #define PG8_SCHED __builtin_amdgcn_sched_barrier(0)
; template <class Epi, class Sched>
; __device__ __forceinline__ void gemm_phase(LAS unsigned char* lds, const int K, const int lda, const int ldb, const Sched& S, const Epi& E) {
;     ...
;             PG8_WAIT_V(8); PG8_WAIT_L(0); PG8_BAR; PG8_MMA(1, 0, At, B0); PG8_MMA(1, 1, At, B1); PG8_BAR; PG8_SCHED;
;             PG8_LDB(B0, 1, 0); PG8_LDB(B1, 1, 1); PG8_SCHED; PG8_LDA(At, 1, 0); PG8_STAGE(PG8_SA(0, 1), a2 + hA, voffA);
;             PG8_WAIT_V(8); PG8_WAIT_L(0); PG8_BAR; PG8_MMA(0, 0, At, B0); PG8_MMA(0, 1, At, B1); PG8_BAR; PG8_SCHED;
	s_setprio 1
	s_waitcnt lgkmcnt(0)
	v_mfma_f32_16x16x32_bf16 v[60:63], v[156:159], v[188:191], v[60:63]
	v_mfma_f32_16x16x32_bf16 v[56:59], v[164:167], v[188:191], v[56:59]
	v_mfma_f32_16x16x32_bf16 v[44:47], v[156:159], v[196:199], v[44:47]
	v_mfma_f32_16x16x32_bf16 v[40:43], v[164:167], v[196:199], v[40:43]
	v_mfma_f32_16x16x32_bf16 v[28:31], v[156:159], v[204:207], v[28:31]
	v_mfma_f32_16x16x32_bf16 v[24:27], v[164:167], v[204:207], v[24:27]
	v_mfma_f32_16x16x32_bf16 v[12:15], v[156:159], v[212:215], v[12:15]
	v_mfma_f32_16x16x32_bf16 v[8:11], v[164:167], v[212:215], v[8:11]
	v_mfma_f32_16x16x32_bf16 v[60:63], v[160:163], v[192:195], v[60:63]
	v_mfma_f32_16x16x32_bf16 v[56:59], v[168:171], v[192:195], v[56:59]
	v_mfma_f32_16x16x32_bf16 v[44:47], v[160:163], v[200:203], v[44:47]
	v_mfma_f32_16x16x32_bf16 v[40:43], v[168:171], v[200:203], v[40:43]
	v_mfma_f32_16x16x32_bf16 v[28:31], v[160:163], v[208:211], v[28:31]
	v_mfma_f32_16x16x32_bf16 v[24:27], v[168:171], v[208:211], v[24:27]
	v_mfma_f32_16x16x32_bf16 v[12:15], v[160:163], v[216:219], v[12:15]
	v_mfma_f32_16x16x32_bf16 v[8:11], v[168:171], v[216:219], v[8:11]
	v_mfma_f32_16x16x32_bf16 v[52:55], v[172:175], v[188:191], v[52:55]
	v_mfma_f32_16x16x32_bf16 v[48:51], v[180:183], v[188:191], v[48:51]
	v_mfma_f32_16x16x32_bf16 v[36:39], v[172:175], v[196:199], v[36:39]
	v_mfma_f32_16x16x32_bf16 v[32:35], v[180:183], v[196:199], v[32:35]
	v_mfma_f32_16x16x32_bf16 v[20:23], v[172:175], v[204:207], v[20:23]
	v_mfma_f32_16x16x32_bf16 v[16:19], v[180:183], v[204:207], v[16:19]
	v_mfma_f32_16x16x32_bf16 v[4:7], v[172:175], v[212:215], v[4:7]
	v_mfma_f32_16x16x32_bf16 v[0:3], v[180:183], v[212:215], v[0:3]
	v_mfma_f32_16x16x32_bf16 v[52:55], v[176:179], v[192:195], v[52:55]
	v_mfma_f32_16x16x32_bf16 v[48:51], v[184:187], v[192:195], v[48:51]
	v_mfma_f32_16x16x32_bf16 v[36:39], v[176:179], v[200:203], v[36:39]
	v_mfma_f32_16x16x32_bf16 v[32:35], v[184:187], v[200:203], v[32:35]
	v_mfma_f32_16x16x32_bf16 v[20:23], v[176:179], v[208:211], v[20:23]
	v_mfma_f32_16x16x32_bf16 v[16:19], v[184:187], v[208:211], v[16:19]
	v_mfma_f32_16x16x32_bf16 v[4:7], v[176:179], v[216:219], v[4:7]
	v_mfma_f32_16x16x32_bf16 v[0:3], v[184:187], v[216:219], v[0:3]
	s_setprio 0
	s_barrier
	s_add_i32 s75, 0, 0x18000
	v_add_u32_e32 v136, s75, v149
	s_add_i32 s76, 0, 0x1c000
	ds_read_b128 v[156:159], v136
	ds_read_b128 v[160:163], v136 offset:1024
	ds_read_b128 v[164:167], v136 offset:2048
	ds_read_b128 v[168:171], v136 offset:3072
	v_add_u32_e32 v136, s76, v149
	ds_read_b128 v[172:175], v136
	ds_read_b128 v[176:179], v136 offset:1024
	ds_read_b128 v[180:183], v136 offset:2048
	ds_read_b128 v[184:187], v136 offset:3072
	s_add_u32 s62, s62, 0x100000
	s_addc_u32 s63, s63, 0
	s_mov_b32 m0, s23
	v_lshl_add_u64 v[226:227], s[62:63], 0, v[134:135]
	ds_read_b128 v[188:191], v153 offset:32768
	ds_read_b128 v[192:195], v153 offset:33792
	ds_read_b128 v[196:199], v153 offset:34816
	ds_read_b128 v[200:203], v153 offset:35840
	ds_read_b128 v[204:207], v153 offset:36864
	ds_read_b128 v[208:211], v153 offset:37888
	ds_read_b128 v[212:215], v153 offset:38912
	ds_read_b128 v[216:219], v153 offset:39936
	global_load_lds_dwordx4 v[226:227], off
	v_lshl_add_u64 v[226:227], s[62:63], 0, v[130:131]
	s_mov_b32 m0, s26
	s_nop 0
	global_load_lds_dwordx4 v[226:227], off
	s_waitcnt vmcnt(8)
	s_waitcnt lgkmcnt(0)
	s_barrier
	s_setprio 1
	s_waitcnt lgkmcnt(0)
	v_mfma_f32_16x16x32_bf16 v[124:127], v[156:159], v[188:191], v[124:127]
	v_mfma_f32_16x16x32_bf16 v[120:123], v[164:167], v[188:191], v[120:123]
	v_mfma_f32_16x16x32_bf16 v[108:111], v[156:159], v[196:199], v[108:111]
	v_mfma_f32_16x16x32_bf16 v[104:107], v[164:167], v[196:199], v[104:107]
	v_mfma_f32_16x16x32_bf16 v[92:95], v[156:159], v[204:207], v[92:95]
	v_mfma_f32_16x16x32_bf16 v[88:91], v[164:167], v[204:207], v[88:91]
	v_mfma_f32_16x16x32_bf16 v[76:79], v[156:159], v[212:215], v[76:79]
	v_mfma_f32_16x16x32_bf16 v[72:75], v[164:167], v[212:215], v[72:75]
	v_mfma_f32_16x16x32_bf16 v[124:127], v[160:163], v[192:195], v[124:127]
	v_mfma_f32_16x16x32_bf16 v[120:123], v[168:171], v[192:195], v[120:123]
	v_mfma_f32_16x16x32_bf16 v[108:111], v[160:163], v[200:203], v[108:111]
	v_mfma_f32_16x16x32_bf16 v[104:107], v[168:171], v[200:203], v[104:107]
	v_mfma_f32_16x16x32_bf16 v[92:95], v[160:163], v[208:211], v[92:95]
	v_mfma_f32_16x16x32_bf16 v[88:91], v[168:171], v[208:211], v[88:91]
	v_mfma_f32_16x16x32_bf16 v[76:79], v[160:163], v[216:219], v[76:79]
	v_mfma_f32_16x16x32_bf16 v[72:75], v[168:171], v[216:219], v[72:75]
	v_mfma_f32_16x16x32_bf16 v[116:119], v[172:175], v[188:191], v[116:119]
	v_mfma_f32_16x16x32_bf16 v[112:115], v[180:183], v[188:191], v[112:115]
	v_mfma_f32_16x16x32_bf16 v[100:103], v[172:175], v[196:199], v[100:103]
	v_mfma_f32_16x16x32_bf16 v[96:99], v[180:183], v[196:199], v[96:99]
	v_mfma_f32_16x16x32_bf16 v[84:87], v[172:175], v[204:207], v[84:87]
	v_mfma_f32_16x16x32_bf16 v[80:83], v[180:183], v[204:207], v[80:83]
	v_mfma_f32_16x16x32_bf16 v[68:71], v[172:175], v[212:215], v[68:71]
	v_mfma_f32_16x16x32_bf16 v[64:67], v[180:183], v[212:215], v[64:67]
	v_mfma_f32_16x16x32_bf16 v[116:119], v[176:179], v[192:195], v[116:119]
	v_mfma_f32_16x16x32_bf16 v[112:115], v[184:187], v[192:195], v[112:115]
	v_mfma_f32_16x16x32_bf16 v[100:103], v[176:179], v[200:203], v[100:103]
	v_mfma_f32_16x16x32_bf16 v[96:99], v[184:187], v[200:203], v[96:99]
	v_mfma_f32_16x16x32_bf16 v[84:87], v[176:179], v[208:211], v[84:87]
	v_mfma_f32_16x16x32_bf16 v[80:83], v[184:187], v[208:211], v[80:83]
	v_mfma_f32_16x16x32_bf16 v[68:71], v[176:179], v[216:219], v[68:71]
	v_mfma_f32_16x16x32_bf16 v[64:67], v[184:187], v[216:219], v[64:67]
	s_setprio 0
	s_barrier
; #define PG8_STAGE(bufoff, gbase, voff) do { _Pragma("unroll") for (int _i = 0; _i < 2; ++_i) \
;         __builtin_amdgcn_global_load_lds((const unsigned*)((const char*)(gbase) + (voff)[_i]), (LAS unsigned*)(lds + (bufoff) + ldsw + _i * 8192), 16, 0, 0); } while (0)
; #define PG8_LDA(dst, b, h) do { _Pragma("unroll") for (int m = 0; m < 4; ++m) _Pragma("unroll") for (int k = 0; k < 2; ++k) dst[m][k] = *(const LAS bf16x8*)(lds + PG8_SA(b, h) + aoff + m * 2048 + k * 1024); } while (0)
; #define PG8_MMA(ai, bj, At, Bt) do { __builtin_amdgcn_s_setprio(1); _Pragma("unroll") for (int m = 0; m < 4; ++m) _Pragma("unroll") for (int n = 0; n < 2; ++n) _Pragma("unroll") for (int k = 0; k < 2; ++k) \
;         acc[ai][bj][m][n] = __builtin_amdgcn_mfma_f32_16x16x32_bf16(Bt[n][k], At[m][k], acc[ai][bj][m][n], 0, 0, 0); __builtin_amdgcn_s_setprio(0); } while (0)
; #define PG8_WAIT_V(n) asm volatile("s_waitcnt vmcnt(" #n ")" ::: "memory")
; #define PG8_WAIT_L(n) asm volatile("s_waitcnt lgkmcnt(" #n ")" ::: "memory")
; #define PG8_BAR __builtin_amdgcn_s_barrier()
; #define PG8_SCHED __builtin_amdgcn_sched_barrier(0)
; template <class Epi, class Sched>
; __device__ __forceinline__ void gemm_phase(LAS unsigned char* lds, const int K, const int lda, const int ldb, const Sched& S, const Epi& E) {
;     ...
;             PG8_LDA(At, 1, 1); PG8_STAGE(PG8_SB(1, 0), b3, voffB); PG8_STAGE(PG8_SB(1, 1), b3 + hB, voffB); PG8_STAGE(PG8_SA(1, 0), a3, voffA);
;             PG8_WAIT_V(8); PG8_WAIT_L(0); PG8_BAR; PG8_MMA(1, 0, At, B0); PG8_MMA(1, 1, At, B1); PG8_BAR; PG8_SCHED;
;         }
;         if (wr == 0) PG8_BAR;
	s_add_i32 s62, s75, s14
	v_lshl_add_u64 v[146:147], v[146:147], 0, s[48:49]
	s_mov_b32 m0, s62
	ds_read_b128 v[188:191], v153 offset:49152
	ds_read_b128 v[192:195], v153 offset:50176
	ds_read_b128 v[196:199], v153 offset:51200
	ds_read_b128 v[200:203], v153 offset:52224
	ds_read_b128 v[204:207], v153 offset:53248
	ds_read_b128 v[208:211], v153 offset:54272
	ds_read_b128 v[212:215], v153 offset:55296
	ds_read_b128 v[216:219], v153 offset:56320
	global_load_lds_dwordx4 v[146:147], off
	s_add_i32 m0, s62, 0x2000
	s_add_u32 s60, s60, 0x400080
	v_lshl_add_u64 v[146:147], v[220:221], 0, s[48:49]
	s_addc_u32 s61, s61, 0
	s_add_i32 s62, s76, s14
	global_load_lds_dwordx4 v[146:147], off
	v_lshl_add_u64 v[146:147], s[60:61], 0, v[132:133]
	s_mov_b32 m0, s62
	s_nop 0
	global_load_lds_dwordx4 v[146:147], off
	v_lshl_add_u64 v[146:147], s[60:61], 0, v[128:129]
	s_add_i32 m0, s62, 0x2000
	s_nop 0
	global_load_lds_dwordx4 v[146:147], off
	v_lshl_add_u64 v[146:147], v[222:223], 0, s[48:49]
	s_mov_b32 m0, s30
	s_nop 0
	global_load_lds_dwordx4 v[146:147], off
	v_lshl_add_u64 v[146:147], v[224:225], 0, s[48:49]
	s_mov_b32 m0, s31
	s_nop 0
	global_load_lds_dwordx4 v[146:147], off
	s_waitcnt vmcnt(8)
	s_waitcnt lgkmcnt(0)
	s_barrier
	s_setprio 1
	s_waitcnt lgkmcnt(0)
	v_mfma_f32_16x16x32_bf16 v[60:63], v[156:159], v[188:191], v[60:63]
	v_mfma_f32_16x16x32_bf16 v[56:59], v[164:167], v[188:191], v[56:59]
	v_mfma_f32_16x16x32_bf16 v[44:47], v[156:159], v[196:199], v[44:47]
	v_mfma_f32_16x16x32_bf16 v[40:43], v[164:167], v[196:199], v[40:43]
	v_mfma_f32_16x16x32_bf16 v[28:31], v[156:159], v[204:207], v[28:31]
	v_mfma_f32_16x16x32_bf16 v[24:27], v[164:167], v[204:207], v[24:27]
	v_mfma_f32_16x16x32_bf16 v[12:15], v[156:159], v[212:215], v[12:15]
	v_mfma_f32_16x16x32_bf16 v[8:11], v[164:167], v[212:215], v[8:11]
	v_mfma_f32_16x16x32_bf16 v[60:63], v[160:163], v[192:195], v[60:63]
	v_mfma_f32_16x16x32_bf16 v[56:59], v[168:171], v[192:195], v[56:59]
	v_mfma_f32_16x16x32_bf16 v[44:47], v[160:163], v[200:203], v[44:47]
	v_mfma_f32_16x16x32_bf16 v[40:43], v[168:171], v[200:203], v[40:43]
	v_mfma_f32_16x16x32_bf16 v[28:31], v[160:163], v[208:211], v[28:31]
	v_mfma_f32_16x16x32_bf16 v[24:27], v[168:171], v[208:211], v[24:27]
	v_mfma_f32_16x16x32_bf16 v[12:15], v[160:163], v[216:219], v[12:15]
	v_mfma_f32_16x16x32_bf16 v[8:11], v[168:171], v[216:219], v[8:11]
	v_mfma_f32_16x16x32_bf16 v[52:55], v[172:175], v[188:191], v[52:55]
	v_mfma_f32_16x16x32_bf16 v[48:51], v[180:183], v[188:191], v[48:51]
	v_mfma_f32_16x16x32_bf16 v[36:39], v[172:175], v[196:199], v[36:39]
	v_mfma_f32_16x16x32_bf16 v[32:35], v[180:183], v[196:199], v[32:35]
	v_mfma_f32_16x16x32_bf16 v[20:23], v[172:175], v[204:207], v[20:23]
	v_mfma_f32_16x16x32_bf16 v[16:19], v[180:183], v[204:207], v[16:19]
	v_mfma_f32_16x16x32_bf16 v[4:7], v[172:175], v[212:215], v[4:7]
	v_mfma_f32_16x16x32_bf16 v[0:3], v[180:183], v[212:215], v[0:3]
	v_mfma_f32_16x16x32_bf16 v[52:55], v[176:179], v[192:195], v[52:55]
	v_mfma_f32_16x16x32_bf16 v[48:51], v[184:187], v[192:195], v[48:51]
	v_mfma_f32_16x16x32_bf16 v[36:39], v[176:179], v[200:203], v[36:39]
	v_mfma_f32_16x16x32_bf16 v[32:35], v[184:187], v[200:203], v[32:35]
	v_mfma_f32_16x16x32_bf16 v[20:23], v[176:179], v[208:211], v[20:23]
	v_mfma_f32_16x16x32_bf16 v[16:19], v[184:187], v[208:211], v[16:19]
	v_mfma_f32_16x16x32_bf16 v[4:7], v[176:179], v[216:219], v[4:7]
	v_mfma_f32_16x16x32_bf16 v[0:3], v[184:187], v[216:219], v[0:3]
	s_setprio 0
	s_barrier
	s_add_i32 s74, s74, 2
	s_add_u32 s21, s21, 0x100
	s_addc_u32 s57, s57, 0
	s_add_u32 s12, s12, 0x100
	s_addc_u32 s13, s13, 0
	s_cmp_gt_u32 s74, 29
	s_cbranch_scc0 .LBB0_1180
	s_and_b64 vcc, exec, s[50:51]
	s_cbranch_vccz .LBB0_1183
	s_barrier

; #define PG8_STAGE(bufoff, gbase, voff) do { _Pragma("unroll") for (int _i = 0; _i < 2; ++_i) \
;         __builtin_amdgcn_global_load_lds((const unsigned*)((const char*)(gbase) + (voff)[_i]), (LAS unsigned*)(lds + (bufoff) + ldsw + _i * 8192), 16, 0, 0); } while (0)
; #define PG8_LDA(dst, b, h) do { _Pragma("unroll") for (int m = 0; m < 4; ++m) _Pragma("unroll") for (int k = 0; k < 2; ++k) dst[m][k] = *(const LAS bf16x8*)(lds + PG8_SA(b, h) + aoff + m * 2048 + k * 1024); } while (0)
; #define PG8_LDB(dst, b, h) do { _Pragma("unroll") for (int n = 0; n < 2; ++n) _Pragma("unroll") for (int k = 0; k < 2; ++k) dst[n][k] = *(const LAS bf16x8*)(lds + PG8_SB(b, h) + boff + n * 2048 + k * 1024); } while (0)
; #define PG8_MMA(ai, bj, At, Bt) do { __builtin_amdgcn_s_setprio(1); _Pragma("unroll") for (int m = 0; m < 4; ++m) _Pragma("unroll") for (int n = 0; n < 2; ++n) _Pragma("unroll") for (int k = 0; k < 2; ++k) \
;         acc[ai][bj][m][n] = __builtin_amdgcn_mfma_f32_16x16x32_bf16(Bt[n][k], At[m][k], acc[ai][bj][m][n], 0, 0, 0); __builtin_amdgcn_s_setprio(0); } while (0)
; #define PG8_WAIT_V(n) asm volatile("s_waitcnt vmcnt(" #n ")" ::: "memory")
; #define PG8_WAIT_L(n) asm volatile("s_waitcnt lgkmcnt(" #n ")" ::: "memory")
; #define PG8_BAR __builtin_amdgcn_s_barrier()
; #define PG8_SCHED __builtin_amdgcn_sched_barrier(0)
; template <class Epi, class Sched>
; __device__ __forceinline__ void gemm_phase(LAS unsigned char* lds, const int K, const int lda, const int ldb, const Sched& S, const Epi& E) {
;     ...
;         for (int t = 0; t < nt; t += 2) {
;             const bool last = (t == nt - 2);
;             const char* a1 = cA + (size_t)(t + 1) * kstep;
;             const char* a2 = last ? nA : cA + (size_t)(t + 2) * kstep; const char* b2 = last ? nB : cB + (size_t)(t + 2) * kstep;
;             const char* a3 = a2 + kstep; const char* b3 = b2 + kstep;
;             PG8_LDB(B0, 0, 0); PG8_LDB(B1, 0, 1); PG8_SCHED; PG8_LDA(At, 0, 0); PG8_STAGE(PG8_SA(1, 1), a1 + hA, voffA);
;             PG8_WAIT_V(8); PG8_WAIT_L(0); PG8_BAR; PG8_MMA(0, 0, At, B0); PG8_MMA(0, 1, At, B1); PG8_BAR; PG8_SCHED;
;             PG8_LDA(At, 0, 1); PG8_STAGE(PG8_SB(0, 0), b2, voffB); PG8_STAGE(PG8_SB(0, 1), b2 + hB, voffB); PG8_STAGE(PG8_SA(0, 0), a2, voffA);
;             PG8_WAIT_V(8); PG8_WAIT_L(0); PG8_BAR; PG8_MMA(1, 0, At, B0); PG8_MMA(1, 1, At, B1); PG8_BAR; PG8_SCHED;
.LBB0_1230:
	ds_read_b128 v[156:159], v151
	ds_read_b128 v[160:163], v151 offset:1024
	ds_read_b128 v[164:167], v151 offset:2048
	ds_read_b128 v[168:171], v151 offset:3072
	ds_read_b128 v[172:175], v152
	ds_read_b128 v[176:179], v152 offset:1024
	ds_read_b128 v[180:183], v152 offset:2048
	ds_read_b128 v[184:187], v152 offset:3072
	s_add_u32 s54, s12, 0xffe00080
	s_addc_u32 s55, s13, -1
	s_cmp_eq_u32 s78, 12
	s_cselect_b32 s57, s27, s55
	s_cselect_b32 s56, s26, s54
	s_cselect_b32 s55, s53, s51
	s_cselect_b32 s54, s52, s23
	v_lshl_add_u64 v[146:147], s[12:13], 0, v[140:141]
	s_add_i32 m0, s15, 0xc000
	ds_read_b128 v[188:191], v153
	ds_read_b128 v[192:195], v153 offset:1024
	ds_read_b128 v[196:199], v153 offset:2048
	ds_read_b128 v[200:203], v153 offset:3072
	ds_read_b128 v[204:207], v153 offset:4096
	ds_read_b128 v[208:211], v153 offset:5120
	ds_read_b128 v[212:215], v153 offset:6144
	ds_read_b128 v[216:219], v153 offset:7168
	global_load_lds_dwordx4 v[146:147], off
	v_lshl_add_u64 v[146:147], s[12:13], 0, v[138:139]
	s_add_i32 m0, s15, 0xe000
	s_nop 0
	global_load_lds_dwordx4 v[146:147], off
	s_waitcnt vmcnt(8)
	s_waitcnt lgkmcnt(0)
	s_barrier
	s_setprio 1
	s_waitcnt lgkmcnt(0)
	v_mfma_f32_16x16x32_bf16 v[124:127], v[156:159], v[188:191], v[124:127]
	v_mfma_f32_16x16x32_bf16 v[120:123], v[164:167], v[188:191], v[120:123]
	v_mfma_f32_16x16x32_bf16 v[108:111], v[156:159], v[196:199], v[108:111]
	v_mfma_f32_16x16x32_bf16 v[104:107], v[164:167], v[196:199], v[104:107]
	v_mfma_f32_16x16x32_bf16 v[92:95], v[156:159], v[204:207], v[92:95]
	v_mfma_f32_16x16x32_bf16 v[88:91], v[164:167], v[204:207], v[88:91]
	v_mfma_f32_16x16x32_bf16 v[76:79], v[156:159], v[212:215], v[76:79]
	v_mfma_f32_16x16x32_bf16 v[72:75], v[164:167], v[212:215], v[72:75]
	v_mfma_f32_16x16x32_bf16 v[124:127], v[160:163], v[192:195], v[124:127]
	v_mfma_f32_16x16x32_bf16 v[120:123], v[168:171], v[192:195], v[120:123]
	v_mfma_f32_16x16x32_bf16 v[108:111], v[160:163], v[200:203], v[108:111]
	v_mfma_f32_16x16x32_bf16 v[104:107], v[168:171], v[200:203], v[104:107]
	v_mfma_f32_16x16x32_bf16 v[92:95], v[160:163], v[208:211], v[92:95]
	v_mfma_f32_16x16x32_bf16 v[88:91], v[168:171], v[208:211], v[88:91]
	v_mfma_f32_16x16x32_bf16 v[76:79], v[160:163], v[216:219], v[76:79]
	v_mfma_f32_16x16x32_bf16 v[72:75], v[168:171], v[216:219], v[72:75]
	v_mfma_f32_16x16x32_bf16 v[116:119], v[172:175], v[188:191], v[116:119]
	v_mfma_f32_16x16x32_bf16 v[112:115], v[180:183], v[188:191], v[112:115]
	v_mfma_f32_16x16x32_bf16 v[100:103], v[172:175], v[196:199], v[100:103]
	v_mfma_f32_16x16x32_bf16 v[96:99], v[180:183], v[196:199], v[96:99]
	v_mfma_f32_16x16x32_bf16 v[84:87], v[172:175], v[204:207], v[84:87]
	v_mfma_f32_16x16x32_bf16 v[80:83], v[180:183], v[204:207], v[80:83]
	v_mfma_f32_16x16x32_bf16 v[68:71], v[172:175], v[212:215], v[68:71]
	v_mfma_f32_16x16x32_bf16 v[64:67], v[180:183], v[212:215], v[64:67]
	v_mfma_f32_16x16x32_bf16 v[116:119], v[176:179], v[192:195], v[116:119]
	v_mfma_f32_16x16x32_bf16 v[112:115], v[184:187], v[192:195], v[112:115]
	v_mfma_f32_16x16x32_bf16 v[100:103], v[176:179], v[200:203], v[100:103]
	v_mfma_f32_16x16x32_bf16 v[96:99], v[184:187], v[200:203], v[96:99]
	v_mfma_f32_16x16x32_bf16 v[84:87], v[176:179], v[208:211], v[84:87]
	v_mfma_f32_16x16x32_bf16 v[80:83], v[184:187], v[208:211], v[80:83]
	v_mfma_f32_16x16x32_bf16 v[68:71], v[176:179], v[216:219], v[68:71]
	v_mfma_f32_16x16x32_bf16 v[64:67], v[184:187], v[216:219], v[64:67]
	s_setprio 0
	s_barrier
	s_add_i32 s79, s59, s14
	v_lshl_add_u64 v[146:147], s[54:55], 0, v[132:133]
	s_mov_b32 m0, s79
	ds_read_b128 v[188:191], v153 offset:16384
	ds_read_b128 v[192:195], v153 offset:17408
	ds_read_b128 v[196:199], v153 offset:18432
	ds_read_b128 v[200:203], v153 offset:19456
	ds_read_b128 v[204:207], v153 offset:20480
	ds_read_b128 v[208:211], v153 offset:21504
	ds_read_b128 v[212:215], v153 offset:22528
	ds_read_b128 v[216:219], v153 offset:23552
	global_load_lds_dwordx4 v[146:147], off
	s_add_i32 m0, s79, 0x2000
	s_add_u32 s80, s54, 0x400000
	v_lshl_add_u64 v[220:221], s[54:55], 0, v[128:129]
	s_addc_u32 s81, s55, 0
	s_add_i32 s79, s60, s14
	global_load_lds_dwordx4 v[220:221], off
	v_lshl_add_u64 v[222:223], s[80:81], 0, v[132:133]
	s_mov_b32 m0, s79
	v_lshl_add_u64 v[224:225], s[56:57], 0, v[130:131]
	global_load_lds_dwordx4 v[222:223], off
	v_lshl_add_u64 v[222:223], s[80:81], 0, v[128:129]
	s_add_i32 m0, s79, 0x2000
	s_nop 0
	global_load_lds_dwordx4 v[222:223], off
	v_lshl_add_u64 v[222:223], s[56:57], 0, v[134:135]
	s_mov_b32 m0, s15
	s_nop 0
	global_load_lds_dwordx4 v[222:223], off
	s_mov_b32 m0, s0
	s_nop 0
	global_load_lds_dwordx4 v[224:225], off
	s_waitcnt vmcnt(8)
	s_waitcnt lgkmcnt(0)
	s_barrier
; #define PG8_STAGE(bufoff, gbase, voff) do { _Pragma("unroll") for (int _i = 0; _i < 2; ++_i) \
;         __builtin_amdgcn_global_load_lds((const unsigned*)((const char*)(gbase) + (voff)[_i]), (LAS unsigned*)(lds + (bufoff) + ldsw + _i * 8192), 16, 0, 0); } while (0)
; #define PG8_LDA(dst, b, h) do { _Pragma("unroll") for (int m = 0; m < 4; ++m) _Pragma("unroll") for (int k = 0; k < 2; ++k) dst[m][k] = *(const LAS bf16x8*)(lds + PG8_SA(b, h) + aoff + m * 2048 + k * 1024); } while (0)
; #define PG8_LDB(dst, b, h) do { _Pragma("unroll") for (int n = 0; n < 2; ++n) _Pragma("unroll") for (int k = 0; k < 2; ++k) dst[n][k] = *(const LAS bf16x8*)(lds + PG8_SB(b, h) + boff + n * 2048 + k * 1024); } while (0)
; #define PG8_MMA(ai, bj, At, Bt) do { __builtin_amdgcn_s_setprio(1); _Pragma("unroll") for (int m = 0; m < 4; ++m) _Pragma("unroll") for (int n = 0; n < 2; ++n) _Pragma("unroll") for (int k = 0; k < 2; ++k) \
;         acc[ai][bj][m][n] = __builtin_amdgcn_mfma_f32_16x16x32_bf16(Bt[n][k], At[m][k], acc[ai][bj][m][n], 0, 0, 0); __builtin_amdgcn_s_setprio(0); } while (0)
; #define PG8_WAIT_V(n) asm volatile("s_waitcnt vmcnt(" #n ")" ::: "memory")
; #define PG8_WAIT_L(n) asm volatile("s_waitcnt lgkmcnt(" #n ")" ::: "memory")
; #define PG8_BAR __builtin_amdgcn_s_barrier()
; #define PG8_SCHED __builtin_amdgcn_sched_barrier(0)
; template <class Epi, class Sched>
; __device__ __forceinline__ void gemm_phase(LAS unsigned char* lds, const int K, const int lda, const int ldb, const Sched& S, const Epi& E) {
;     ...
;             PG8_WAIT_V(8); PG8_WAIT_L(0); PG8_BAR; PG8_MMA(1, 0, At, B0); PG8_MMA(1, 1, At, B1); PG8_BAR; PG8_SCHED;
;             PG8_LDB(B0, 1, 0); PG8_LDB(B1, 1, 1); PG8_SCHED; PG8_LDA(At, 1, 0); PG8_STAGE(PG8_SA(0, 1), a2 + hA, voffA);
;             PG8_WAIT_V(8); PG8_WAIT_L(0); PG8_BAR; PG8_MMA(0, 0, At, B0); PG8_MMA(0, 1, At, B1); PG8_BAR; PG8_SCHED;
	s_setprio 1
	s_waitcnt lgkmcnt(0)
	v_mfma_f32_16x16x32_bf16 v[60:63], v[156:159], v[188:191], v[60:63]
	v_mfma_f32_16x16x32_bf16 v[56:59], v[164:167], v[188:191], v[56:59]
	v_mfma_f32_16x16x32_bf16 v[44:47], v[156:159], v[196:199], v[44:47]
	v_mfma_f32_16x16x32_bf16 v[40:43], v[164:167], v[196:199], v[40:43]
	v_mfma_f32_16x16x32_bf16 v[28:31], v[156:159], v[204:207], v[28:31]
	v_mfma_f32_16x16x32_bf16 v[24:27], v[164:167], v[204:207], v[24:27]
	v_mfma_f32_16x16x32_bf16 v[12:15], v[156:159], v[212:215], v[12:15]
	v_mfma_f32_16x16x32_bf16 v[8:11], v[164:167], v[212:215], v[8:11]
	v_mfma_f32_16x16x32_bf16 v[60:63], v[160:163], v[192:195], v[60:63]
	v_mfma_f32_16x16x32_bf16 v[56:59], v[168:171], v[192:195], v[56:59]
	v_mfma_f32_16x16x32_bf16 v[44:47], v[160:163], v[200:203], v[44:47]
	v_mfma_f32_16x16x32_bf16 v[40:43], v[168:171], v[200:203], v[40:43]
	v_mfma_f32_16x16x32_bf16 v[28:31], v[160:163], v[208:211], v[28:31]
	v_mfma_f32_16x16x32_bf16 v[24:27], v[168:171], v[208:211], v[24:27]
	v_mfma_f32_16x16x32_bf16 v[12:15], v[160:163], v[216:219], v[12:15]
	v_mfma_f32_16x16x32_bf16 v[8:11], v[168:171], v[216:219], v[8:11]
	v_mfma_f32_16x16x32_bf16 v[52:55], v[172:175], v[188:191], v[52:55]
	v_mfma_f32_16x16x32_bf16 v[48:51], v[180:183], v[188:191], v[48:51]
	v_mfma_f32_16x16x32_bf16 v[36:39], v[172:175], v[196:199], v[36:39]
	v_mfma_f32_16x16x32_bf16 v[32:35], v[180:183], v[196:199], v[32:35]
	v_mfma_f32_16x16x32_bf16 v[20:23], v[172:175], v[204:207], v[20:23]
	v_mfma_f32_16x16x32_bf16 v[16:19], v[180:183], v[204:207], v[16:19]
	v_mfma_f32_16x16x32_bf16 v[4:7], v[172:175], v[212:215], v[4:7]
	v_mfma_f32_16x16x32_bf16 v[0:3], v[180:183], v[212:215], v[0:3]
	v_mfma_f32_16x16x32_bf16 v[52:55], v[176:179], v[192:195], v[52:55]
	v_mfma_f32_16x16x32_bf16 v[48:51], v[184:187], v[192:195], v[48:51]
	v_mfma_f32_16x16x32_bf16 v[36:39], v[176:179], v[200:203], v[36:39]
	v_mfma_f32_16x16x32_bf16 v[32:35], v[184:187], v[200:203], v[32:35]
	v_mfma_f32_16x16x32_bf16 v[20:23], v[176:179], v[208:211], v[20:23]
	v_mfma_f32_16x16x32_bf16 v[16:19], v[184:187], v[208:211], v[16:19]
	v_mfma_f32_16x16x32_bf16 v[4:7], v[176:179], v[216:219], v[4:7]
	v_mfma_f32_16x16x32_bf16 v[0:3], v[184:187], v[216:219], v[0:3]
	s_setprio 0
	s_barrier
	s_add_i32 s79, 0, 0x18000
	v_add_u32_e32 v136, s79, v149
	s_add_i32 s80, 0, 0x1c000
	ds_read_b128 v[156:159], v136
	ds_read_b128 v[160:163], v136 offset:1024
	ds_read_b128 v[164:167], v136 offset:2048
	ds_read_b128 v[168:171], v136 offset:3072
	v_add_u32_e32 v136, s80, v149
	ds_read_b128 v[172:175], v136
	ds_read_b128 v[176:179], v136 offset:1024
	ds_read_b128 v[180:183], v136 offset:2048
	ds_read_b128 v[184:187], v136 offset:3072
	s_add_u32 s56, s56, 0x200000
	s_addc_u32 s57, s57, 0
	s_mov_b32 m0, s30
	v_lshl_add_u64 v[226:227], s[56:57], 0, v[134:135]
	ds_read_b128 v[188:191], v153 offset:32768
	ds_read_b128 v[192:195], v153 offset:33792
	ds_read_b128 v[196:199], v153 offset:34816
	ds_read_b128 v[200:203], v153 offset:35840
	ds_read_b128 v[204:207], v153 offset:36864
	ds_read_b128 v[208:211], v153 offset:37888
	ds_read_b128 v[212:215], v153 offset:38912
	ds_read_b128 v[216:219], v153 offset:39936
	global_load_lds_dwordx4 v[226:227], off
	v_lshl_add_u64 v[226:227], s[56:57], 0, v[130:131]
	s_mov_b32 m0, s31
	s_nop 0
	global_load_lds_dwordx4 v[226:227], off
	s_waitcnt vmcnt(8)
	s_waitcnt lgkmcnt(0)
	s_barrier
	s_setprio 1
	s_waitcnt lgkmcnt(0)
	v_mfma_f32_16x16x32_bf16 v[124:127], v[156:159], v[188:191], v[124:127]
	v_mfma_f32_16x16x32_bf16 v[120:123], v[164:167], v[188:191], v[120:123]
	v_mfma_f32_16x16x32_bf16 v[108:111], v[156:159], v[196:199], v[108:111]
	v_mfma_f32_16x16x32_bf16 v[104:107], v[164:167], v[196:199], v[104:107]
	v_mfma_f32_16x16x32_bf16 v[92:95], v[156:159], v[204:207], v[92:95]
	v_mfma_f32_16x16x32_bf16 v[88:91], v[164:167], v[204:207], v[88:91]
	v_mfma_f32_16x16x32_bf16 v[76:79], v[156:159], v[212:215], v[76:79]
	v_mfma_f32_16x16x32_bf16 v[72:75], v[164:167], v[212:215], v[72:75]
	v_mfma_f32_16x16x32_bf16 v[124:127], v[160:163], v[192:195], v[124:127]
	v_mfma_f32_16x16x32_bf16 v[120:123], v[168:171], v[192:195], v[120:123]
	v_mfma_f32_16x16x32_bf16 v[108:111], v[160:163], v[200:203], v[108:111]
	v_mfma_f32_16x16x32_bf16 v[104:107], v[168:171], v[200:203], v[104:107]
	v_mfma_f32_16x16x32_bf16 v[92:95], v[160:163], v[208:211], v[92:95]
	v_mfma_f32_16x16x32_bf16 v[88:91], v[168:171], v[208:211], v[88:91]
	v_mfma_f32_16x16x32_bf16 v[76:79], v[160:163], v[216:219], v[76:79]
	v_mfma_f32_16x16x32_bf16 v[72:75], v[168:171], v[216:219], v[72:75]
	v_mfma_f32_16x16x32_bf16 v[116:119], v[172:175], v[188:191], v[116:119]
	v_mfma_f32_16x16x32_bf16 v[112:115], v[180:183], v[188:191], v[112:115]
	v_mfma_f32_16x16x32_bf16 v[100:103], v[172:175], v[196:199], v[100:103]
	v_mfma_f32_16x16x32_bf16 v[96:99], v[180:183], v[196:199], v[96:99]
	v_mfma_f32_16x16x32_bf16 v[84:87], v[172:175], v[204:207], v[84:87]
	v_mfma_f32_16x16x32_bf16 v[80:83], v[180:183], v[204:207], v[80:83]
	v_mfma_f32_16x16x32_bf16 v[68:71], v[172:175], v[212:215], v[68:71]
	v_mfma_f32_16x16x32_bf16 v[64:67], v[180:183], v[212:215], v[64:67]
	v_mfma_f32_16x16x32_bf16 v[116:119], v[176:179], v[192:195], v[116:119]
	v_mfma_f32_16x16x32_bf16 v[112:115], v[184:187], v[192:195], v[112:115]
	v_mfma_f32_16x16x32_bf16 v[100:103], v[176:179], v[200:203], v[100:103]
	v_mfma_f32_16x16x32_bf16 v[96:99], v[184:187], v[200:203], v[96:99]
	v_mfma_f32_16x16x32_bf16 v[84:87], v[176:179], v[208:211], v[84:87]
	v_mfma_f32_16x16x32_bf16 v[80:83], v[184:187], v[208:211], v[80:83]
	v_mfma_f32_16x16x32_bf16 v[68:71], v[176:179], v[216:219], v[68:71]
	v_mfma_f32_16x16x32_bf16 v[64:67], v[184:187], v[216:219], v[64:67]
	s_setprio 0
	s_barrier
; #define PG8_STAGE(bufoff, gbase, voff) do { _Pragma("unroll") for (int _i = 0; _i < 2; ++_i) \
;         __builtin_amdgcn_global_load_lds((const unsigned*)((const char*)(gbase) + (voff)[_i]), (LAS unsigned*)(lds + (bufoff) + ldsw + _i * 8192), 16, 0, 0); } while (0)
; #define PG8_LDA(dst, b, h) do { _Pragma("unroll") for (int m = 0; m < 4; ++m) _Pragma("unroll") for (int k = 0; k < 2; ++k) dst[m][k] = *(const LAS bf16x8*)(lds + PG8_SA(b, h) + aoff + m * 2048 + k * 1024); } while (0)
; #define PG8_MMA(ai, bj, At, Bt) do { __builtin_amdgcn_s_setprio(1); _Pragma("unroll") for (int m = 0; m < 4; ++m) _Pragma("unroll") for (int n = 0; n < 2; ++n) _Pragma("unroll") for (int k = 0; k < 2; ++k) \
;         acc[ai][bj][m][n] = __builtin_amdgcn_mfma_f32_16x16x32_bf16(Bt[n][k], At[m][k], acc[ai][bj][m][n], 0, 0, 0); __builtin_amdgcn_s_setprio(0); } while (0)
; #define PG8_WAIT_V(n) asm volatile("s_waitcnt vmcnt(" #n ")" ::: "memory")
; #define PG8_WAIT_L(n) asm volatile("s_waitcnt lgkmcnt(" #n ")" ::: "memory")
; #define PG8_BAR __builtin_amdgcn_s_barrier()
; #define PG8_SCHED __builtin_amdgcn_sched_barrier(0)
; template <class Epi, class Sched>
; __device__ __forceinline__ void gemm_phase(LAS unsigned char* lds, const int K, const int lda, const int ldb, const Sched& S, const Epi& E) {
;     ...
;             PG8_LDA(At, 1, 1); PG8_STAGE(PG8_SB(1, 0), b3, voffB); PG8_STAGE(PG8_SB(1, 1), b3 + hB, voffB); PG8_STAGE(PG8_SA(1, 0), a3, voffA);
;             PG8_WAIT_V(8); PG8_WAIT_L(0); PG8_BAR; PG8_MMA(1, 0, At, B0); PG8_MMA(1, 1, At, B1); PG8_BAR; PG8_SCHED;
;         }
;         if (wr == 0) PG8_BAR;
	s_add_i32 s56, s79, s14
	v_lshl_add_u64 v[146:147], v[146:147], 0, s[20:21]
	s_mov_b32 m0, s56
	ds_read_b128 v[188:191], v153 offset:49152
	ds_read_b128 v[192:195], v153 offset:50176
	ds_read_b128 v[196:199], v153 offset:51200
	ds_read_b128 v[200:203], v153 offset:52224
	ds_read_b128 v[204:207], v153 offset:53248
	ds_read_b128 v[208:211], v153 offset:54272
	ds_read_b128 v[212:215], v153 offset:55296
	ds_read_b128 v[216:219], v153 offset:56320
	global_load_lds_dwordx4 v[146:147], off
	s_add_i32 m0, s56, 0x2000
	s_add_u32 s54, s54, 0x400080
	v_lshl_add_u64 v[146:147], v[220:221], 0, s[20:21]
	s_addc_u32 s55, s55, 0
	s_add_i32 s56, s80, s14
	global_load_lds_dwordx4 v[146:147], off
	v_lshl_add_u64 v[146:147], s[54:55], 0, v[132:133]
	s_mov_b32 m0, s56
	s_nop 0
	global_load_lds_dwordx4 v[146:147], off
	v_lshl_add_u64 v[146:147], s[54:55], 0, v[128:129]
	s_add_i32 m0, s56, 0x2000
	s_nop 0
	global_load_lds_dwordx4 v[146:147], off
	v_lshl_add_u64 v[146:147], v[222:223], 0, s[20:21]
	s_mov_b32 m0, s38
	s_nop 0
	global_load_lds_dwordx4 v[146:147], off
	v_lshl_add_u64 v[146:147], v[224:225], 0, s[20:21]
	s_mov_b32 m0, s39
	s_nop 0
	global_load_lds_dwordx4 v[146:147], off
	s_waitcnt vmcnt(8)
	s_waitcnt lgkmcnt(0)
	s_barrier
	s_setprio 1
	s_waitcnt lgkmcnt(0)
	v_mfma_f32_16x16x32_bf16 v[60:63], v[156:159], v[188:191], v[60:63]
	v_mfma_f32_16x16x32_bf16 v[56:59], v[164:167], v[188:191], v[56:59]
	v_mfma_f32_16x16x32_bf16 v[44:47], v[156:159], v[196:199], v[44:47]
	v_mfma_f32_16x16x32_bf16 v[40:43], v[164:167], v[196:199], v[40:43]
	v_mfma_f32_16x16x32_bf16 v[28:31], v[156:159], v[204:207], v[28:31]
	v_mfma_f32_16x16x32_bf16 v[24:27], v[164:167], v[204:207], v[24:27]
	v_mfma_f32_16x16x32_bf16 v[12:15], v[156:159], v[212:215], v[12:15]
	v_mfma_f32_16x16x32_bf16 v[8:11], v[164:167], v[212:215], v[8:11]
	v_mfma_f32_16x16x32_bf16 v[60:63], v[160:163], v[192:195], v[60:63]
	v_mfma_f32_16x16x32_bf16 v[56:59], v[168:171], v[192:195], v[56:59]
	v_mfma_f32_16x16x32_bf16 v[44:47], v[160:163], v[200:203], v[44:47]
	v_mfma_f32_16x16x32_bf16 v[40:43], v[168:171], v[200:203], v[40:43]
	v_mfma_f32_16x16x32_bf16 v[28:31], v[160:163], v[208:211], v[28:31]
	v_mfma_f32_16x16x32_bf16 v[24:27], v[168:171], v[208:211], v[24:27]
	v_mfma_f32_16x16x32_bf16 v[12:15], v[160:163], v[216:219], v[12:15]
	v_mfma_f32_16x16x32_bf16 v[8:11], v[168:171], v[216:219], v[8:11]
	v_mfma_f32_16x16x32_bf16 v[52:55], v[172:175], v[188:191], v[52:55]
	v_mfma_f32_16x16x32_bf16 v[48:51], v[180:183], v[188:191], v[48:51]
	v_mfma_f32_16x16x32_bf16 v[36:39], v[172:175], v[196:199], v[36:39]
	v_mfma_f32_16x16x32_bf16 v[32:35], v[180:183], v[196:199], v[32:35]
	v_mfma_f32_16x16x32_bf16 v[20:23], v[172:175], v[204:207], v[20:23]
	v_mfma_f32_16x16x32_bf16 v[16:19], v[180:183], v[204:207], v[16:19]
	v_mfma_f32_16x16x32_bf16 v[4:7], v[172:175], v[212:215], v[4:7]
	v_mfma_f32_16x16x32_bf16 v[0:3], v[180:183], v[212:215], v[0:3]
	v_mfma_f32_16x16x32_bf16 v[52:55], v[176:179], v[192:195], v[52:55]
	v_mfma_f32_16x16x32_bf16 v[48:51], v[184:187], v[192:195], v[48:51]
	v_mfma_f32_16x16x32_bf16 v[36:39], v[176:179], v[200:203], v[36:39]
	v_mfma_f32_16x16x32_bf16 v[32:35], v[184:187], v[200:203], v[32:35]
	v_mfma_f32_16x16x32_bf16 v[20:23], v[176:179], v[208:211], v[20:23]
	v_mfma_f32_16x16x32_bf16 v[16:19], v[184:187], v[208:211], v[16:19]
	v_mfma_f32_16x16x32_bf16 v[4:7], v[176:179], v[216:219], v[4:7]
	v_mfma_f32_16x16x32_bf16 v[0:3], v[184:187], v[216:219], v[0:3]
	s_setprio 0
	s_barrier
	s_add_i32 s78, s78, 2
	s_add_u32 s23, s23, 0x100
	s_addc_u32 s51, s51, 0
	s_add_u32 s12, s12, 0x100
	s_addc_u32 s13, s13, 0
	s_cmp_gt_u32 s78, 13
	s_cbranch_scc0 .LBB0_1230
	s_and_b64 vcc, exec, s[24:25]
	s_cbranch_vccz .LBB0_1233
	s_barrier

; #define PG8_STAGE(bufoff, gbase, voff) do { _Pragma("unroll") for (int _i = 0; _i < 2; ++_i) \
;         __builtin_amdgcn_global_load_lds((const unsigned*)((const char*)(gbase) + (voff)[_i]), (LAS unsigned*)(lds + (bufoff) + ldsw + _i * 8192), 16, 0, 0); } while (0)
; #define PG8_LDA(dst, b, h) do { _Pragma("unroll") for (int m = 0; m < 4; ++m) _Pragma("unroll") for (int k = 0; k < 2; ++k) dst[m][k] = *(const LAS bf16x8*)(lds + PG8_SA(b, h) + aoff + m * 2048 + k * 1024); } while (0)
; #define PG8_LDB(dst, b, h) do { _Pragma("unroll") for (int n = 0; n < 2; ++n) _Pragma("unroll") for (int k = 0; k < 2; ++k) dst[n][k] = *(const LAS bf16x8*)(lds + PG8_SB(b, h) + boff + n * 2048 + k * 1024); } while (0)
; #define PG8_MMA(ai, bj, At, Bt) do { __builtin_amdgcn_s_setprio(1); _Pragma("unroll") for (int m = 0; m < 4; ++m) _Pragma("unroll") for (int n = 0; n < 2; ++n) _Pragma("unroll") for (int k = 0; k < 2; ++k) \
;         acc[ai][bj][m][n] = __builtin_amdgcn_mfma_f32_16x16x32_bf16(Bt[n][k], At[m][k], acc[ai][bj][m][n], 0, 0, 0); __builtin_amdgcn_s_setprio(0); } while (0)
; #define PG8_WAIT_V(n) asm volatile("s_waitcnt vmcnt(" #n ")" ::: "memory")
; #define PG8_WAIT_L(n) asm volatile("s_waitcnt lgkmcnt(" #n ")" ::: "memory")
; #define PG8_BAR __builtin_amdgcn_s_barrier()
; #define PG8_SCHED __builtin_amdgcn_sched_barrier(0)
; template <class Epi, class Sched>
; __device__ __forceinline__ void gemm_phase(LAS unsigned char* lds, const int K, const int lda, const int ldb, const Sched& S, const Epi& E) {
;     ...
;         for (int t = 0; t < nt; t += 2) {
;             const bool last = (t == nt - 2);
;             const char* a1 = cA + (size_t)(t + 1) * kstep;
;             const char* a2 = last ? nA : cA + (size_t)(t + 2) * kstep; const char* b2 = last ? nB : cB + (size_t)(t + 2) * kstep;
;             const char* a3 = a2 + kstep; const char* b3 = b2 + kstep;
;             PG8_LDB(B0, 0, 0); PG8_LDB(B1, 0, 1); PG8_SCHED; PG8_LDA(At, 0, 0); PG8_STAGE(PG8_SA(1, 1), a1 + hA, voffA);
;             PG8_WAIT_V(8); PG8_WAIT_L(0); PG8_BAR; PG8_MMA(0, 0, At, B0); PG8_MMA(0, 1, At, B1); PG8_BAR; PG8_SCHED;
;             PG8_LDA(At, 0, 1); PG8_STAGE(PG8_SB(0, 0), b2, voffB); PG8_STAGE(PG8_SB(0, 1), b2 + hB, voffB); PG8_STAGE(PG8_SA(0, 0), a2, voffA);
;             PG8_WAIT_V(8); PG8_WAIT_L(0); PG8_BAR; PG8_MMA(1, 0, At, B0); PG8_MMA(1, 1, At, B1); PG8_BAR; PG8_SCHED;
.LBB0_1372:
	ds_read_b128 v[104:107], v220
	ds_read_b128 v[112:115], v247
	ds_read_b128 v[124:127], v220 offset:2048
	ds_read_b128 v[140:143], v247 offset:2048
	ds_read_b128 v[144:147], v221
	ds_read_b128 v[148:151], v248
	ds_read_b128 v[152:155], v221 offset:2048
	ds_read_b128 v[156:159], v248 offset:2048
	s_add_u32 s51, s52, 0xfff80080
	s_addc_u32 s54, s53, -1
	s_cmp_eq_u32 s41, 28
	s_cselect_b32 s57, s17, s54
	s_cselect_b32 s56, s27, s51
	s_cselect_b32 s55, s25, s39
	s_cselect_b32 s54, s35, s38
	v_lshl_add_u64 v[208:209], s[52:53], 0, v[194:195]
	s_add_i32 m0, s2, 0xc000
	ds_read_b128 v[160:163], v222
	ds_read_b128 v[164:167], v246
	ds_read_b128 v[168:171], v222 offset:2048
	ds_read_b128 v[172:175], v246 offset:2048
	ds_read_b128 v[176:179], v222 offset:4096
	ds_read_b128 v[180:183], v246 offset:4096
	ds_read_b128 v[200:203], v222 offset:6144
	ds_read_b128 v[204:207], v246 offset:6144
	global_load_lds_dwordx4 v[208:209], off
	v_lshl_add_u64 v[208:209], s[52:53], 0, v[192:193]
	s_add_i32 m0, s2, 0xe000
	s_nop 0
	global_load_lds_dwordx4 v[208:209], off
	s_waitcnt vmcnt(8)
	s_waitcnt lgkmcnt(0)
	s_barrier
	s_setprio 1
	s_waitcnt lgkmcnt(0)
	v_mfma_f32_16x16x32_bf16 v[136:139], v[160:163], v[104:107], v[136:139]
	v_mfma_f32_16x16x32_bf16 v[132:135], v[160:163], v[124:127], v[132:135]
	v_mfma_f32_16x16x32_bf16 v[116:119], v[168:171], v[104:107], v[116:119]
	v_mfma_f32_16x16x32_bf16 v[108:111], v[168:171], v[124:127], v[108:111]
	v_mfma_f32_16x16x32_bf16 v[92:95], v[176:179], v[104:107], v[92:95]
	v_mfma_f32_16x16x32_bf16 v[88:91], v[176:179], v[124:127], v[88:91]
	v_mfma_f32_16x16x32_bf16 v[76:79], v[200:203], v[104:107], v[76:79]
	v_mfma_f32_16x16x32_bf16 v[72:75], v[200:203], v[124:127], v[72:75]
	v_mfma_f32_16x16x32_bf16 v[136:139], v[164:167], v[112:115], v[136:139]
	v_mfma_f32_16x16x32_bf16 v[132:135], v[164:167], v[140:143], v[132:135]
	v_mfma_f32_16x16x32_bf16 v[116:119], v[172:175], v[112:115], v[116:119]
	v_mfma_f32_16x16x32_bf16 v[108:111], v[172:175], v[140:143], v[108:111]
	v_mfma_f32_16x16x32_bf16 v[92:95], v[180:183], v[112:115], v[92:95]
	v_mfma_f32_16x16x32_bf16 v[88:91], v[180:183], v[140:143], v[88:91]
	v_mfma_f32_16x16x32_bf16 v[76:79], v[204:207], v[112:115], v[76:79]
	v_mfma_f32_16x16x32_bf16 v[72:75], v[204:207], v[140:143], v[72:75]
	v_mfma_f32_16x16x32_bf16 v[128:131], v[160:163], v[144:147], v[128:131]
	v_mfma_f32_16x16x32_bf16 v[120:123], v[160:163], v[152:155], v[120:123]
	v_mfma_f32_16x16x32_bf16 v[100:103], v[168:171], v[144:147], v[100:103]
	v_mfma_f32_16x16x32_bf16 v[96:99], v[168:171], v[152:155], v[96:99]
	v_mfma_f32_16x16x32_bf16 v[84:87], v[176:179], v[144:147], v[84:87]
	v_mfma_f32_16x16x32_bf16 v[80:83], v[176:179], v[152:155], v[80:83]
	v_mfma_f32_16x16x32_bf16 v[68:71], v[200:203], v[144:147], v[68:71]
	v_mfma_f32_16x16x32_bf16 v[64:67], v[200:203], v[152:155], v[64:67]
	v_mfma_f32_16x16x32_bf16 v[128:131], v[164:167], v[148:151], v[128:131]
	v_mfma_f32_16x16x32_bf16 v[120:123], v[164:167], v[156:159], v[120:123]
	v_mfma_f32_16x16x32_bf16 v[100:103], v[172:175], v[148:151], v[100:103]
	v_mfma_f32_16x16x32_bf16 v[96:99], v[172:175], v[156:159], v[96:99]
	v_mfma_f32_16x16x32_bf16 v[84:87], v[180:183], v[148:151], v[84:87]
	v_mfma_f32_16x16x32_bf16 v[80:83], v[180:183], v[156:159], v[80:83]
	v_mfma_f32_16x16x32_bf16 v[68:71], v[204:207], v[148:151], v[68:71]
	v_mfma_f32_16x16x32_bf16 v[64:67], v[204:207], v[156:159], v[64:67]
	s_setprio 0
	s_barrier
	s_add_i32 s51, s0, s1
	v_lshl_add_u64 v[208:209], s[54:55], 0, v[186:187]
	s_mov_b32 m0, s51
	ds_read_b128 v[160:163], v222 offset:16384
	ds_read_b128 v[164:167], v246 offset:16384
	ds_read_b128 v[168:171], v222 offset:18432
	ds_read_b128 v[172:175], v246 offset:18432
	ds_read_b128 v[176:179], v222 offset:20480
	ds_read_b128 v[180:183], v246 offset:20480
	ds_read_b128 v[200:203], v222 offset:22528
	ds_read_b128 v[204:207], v246 offset:22528
	global_load_lds_dwordx4 v[208:209], off
	s_add_i32 m0, s51, 0x2000
	s_add_u32 s58, s54, 0x80000
	v_lshl_add_u64 v[210:211], s[54:55], 0, v[190:191]
	s_addc_u32 s59, s55, 0
	s_add_i32 s51, s34, s1
	global_load_lds_dwordx4 v[210:211], off
	v_lshl_add_u64 v[212:213], s[58:59], 0, v[186:187]
	s_mov_b32 m0, s51
	v_lshl_add_u64 v[214:215], s[56:57], 0, v[188:189]
	global_load_lds_dwordx4 v[212:213], off
	v_lshl_add_u64 v[212:213], s[58:59], 0, v[190:191]
	s_add_i32 m0, s51, 0x2000
	s_nop 0
	global_load_lds_dwordx4 v[212:213], off
	v_lshl_add_u64 v[212:213], s[56:57], 0, v[184:185]
	s_mov_b32 m0, s2
	s_nop 0
	global_load_lds_dwordx4 v[212:213], off
	s_mov_b32 m0, s4
	s_nop 0
	global_load_lds_dwordx4 v[214:215], off
	s_waitcnt vmcnt(8)
	s_waitcnt lgkmcnt(0)
	s_barrier
; #define PG8_STAGE(bufoff, gbase, voff) do { _Pragma("unroll") for (int _i = 0; _i < 2; ++_i) \
;         __builtin_amdgcn_global_load_lds((const unsigned*)((const char*)(gbase) + (voff)[_i]), (LAS unsigned*)(lds + (bufoff) + ldsw + _i * 8192), 16, 0, 0); } while (0)
; #define PG8_LDA(dst, b, h) do { _Pragma("unroll") for (int m = 0; m < 4; ++m) _Pragma("unroll") for (int k = 0; k < 2; ++k) dst[m][k] = *(const LAS bf16x8*)(lds + PG8_SA(b, h) + aoff + m * 2048 + k * 1024); } while (0)
; #define PG8_LDB(dst, b, h) do { _Pragma("unroll") for (int n = 0; n < 2; ++n) _Pragma("unroll") for (int k = 0; k < 2; ++k) dst[n][k] = *(const LAS bf16x8*)(lds + PG8_SB(b, h) + boff + n * 2048 + k * 1024); } while (0)
; #define PG8_MMA(ai, bj, At, Bt) do { __builtin_amdgcn_s_setprio(1); _Pragma("unroll") for (int m = 0; m < 4; ++m) _Pragma("unroll") for (int n = 0; n < 2; ++n) _Pragma("unroll") for (int k = 0; k < 2; ++k) \
;         acc[ai][bj][m][n] = __builtin_amdgcn_mfma_f32_16x16x32_bf16(Bt[n][k], At[m][k], acc[ai][bj][m][n], 0, 0, 0); __builtin_amdgcn_s_setprio(0); } while (0)
; #define PG8_WAIT_V(n) asm volatile("s_waitcnt vmcnt(" #n ")" ::: "memory")
; #define PG8_WAIT_L(n) asm volatile("s_waitcnt lgkmcnt(" #n ")" ::: "memory")
; #define PG8_BAR __builtin_amdgcn_s_barrier()
; #define PG8_SCHED __builtin_amdgcn_sched_barrier(0)
; template <class Epi, class Sched>
; __device__ __forceinline__ void gemm_phase(LAS unsigned char* lds, const int K, const int lda, const int ldb, const Sched& S, const Epi& E) {
;     ...
;             PG8_WAIT_V(8); PG8_WAIT_L(0); PG8_BAR; PG8_MMA(1, 0, At, B0); PG8_MMA(1, 1, At, B1); PG8_BAR; PG8_SCHED;
;             PG8_LDB(B0, 1, 0); PG8_LDB(B1, 1, 1); PG8_SCHED; PG8_LDA(At, 1, 0); PG8_STAGE(PG8_SA(0, 1), a2 + hA, voffA);
;             PG8_WAIT_V(8); PG8_WAIT_L(0); PG8_BAR; PG8_MMA(0, 0, At, B0); PG8_MMA(0, 1, At, B1); PG8_BAR; PG8_SCHED;
	s_setprio 1
	s_waitcnt lgkmcnt(0)
	v_mfma_f32_16x16x32_bf16 v[60:63], v[160:163], v[104:107], v[60:63]
	v_mfma_f32_16x16x32_bf16 v[56:59], v[160:163], v[124:127], v[56:59]
	v_mfma_f32_16x16x32_bf16 v[44:47], v[168:171], v[104:107], v[44:47]
	v_mfma_f32_16x16x32_bf16 v[40:43], v[168:171], v[124:127], v[40:43]
	v_mfma_f32_16x16x32_bf16 v[28:31], v[176:179], v[104:107], v[28:31]
	v_mfma_f32_16x16x32_bf16 v[24:27], v[176:179], v[124:127], v[24:27]
	v_mfma_f32_16x16x32_bf16 v[12:15], v[200:203], v[104:107], v[12:15]
	v_mfma_f32_16x16x32_bf16 v[8:11], v[200:203], v[124:127], v[8:11]
	v_mfma_f32_16x16x32_bf16 v[60:63], v[164:167], v[112:115], v[60:63]
	v_mfma_f32_16x16x32_bf16 v[56:59], v[164:167], v[140:143], v[56:59]
	v_mfma_f32_16x16x32_bf16 v[44:47], v[172:175], v[112:115], v[44:47]
	v_mfma_f32_16x16x32_bf16 v[40:43], v[172:175], v[140:143], v[40:43]
	v_mfma_f32_16x16x32_bf16 v[28:31], v[180:183], v[112:115], v[28:31]
	v_mfma_f32_16x16x32_bf16 v[24:27], v[180:183], v[140:143], v[24:27]
	v_mfma_f32_16x16x32_bf16 v[12:15], v[204:207], v[112:115], v[12:15]
	v_mfma_f32_16x16x32_bf16 v[8:11], v[204:207], v[140:143], v[8:11]
	v_mfma_f32_16x16x32_bf16 v[52:55], v[160:163], v[144:147], v[52:55]
	v_mfma_f32_16x16x32_bf16 v[48:51], v[160:163], v[152:155], v[48:51]
	v_mfma_f32_16x16x32_bf16 v[36:39], v[168:171], v[144:147], v[36:39]
	v_mfma_f32_16x16x32_bf16 v[32:35], v[168:171], v[152:155], v[32:35]
	v_mfma_f32_16x16x32_bf16 v[20:23], v[176:179], v[144:147], v[20:23]
	v_mfma_f32_16x16x32_bf16 v[16:19], v[176:179], v[152:155], v[16:19]
	v_mfma_f32_16x16x32_bf16 v[4:7], v[200:203], v[144:147], v[4:7]
	v_mfma_f32_16x16x32_bf16 v[0:3], v[200:203], v[152:155], v[0:3]
	v_mfma_f32_16x16x32_bf16 v[52:55], v[164:167], v[148:151], v[52:55]
	v_mfma_f32_16x16x32_bf16 v[48:51], v[164:167], v[156:159], v[48:51]
	v_mfma_f32_16x16x32_bf16 v[36:39], v[172:175], v[148:151], v[36:39]
	v_mfma_f32_16x16x32_bf16 v[32:35], v[172:175], v[156:159], v[32:35]
	v_mfma_f32_16x16x32_bf16 v[20:23], v[180:183], v[148:151], v[20:23]
	v_mfma_f32_16x16x32_bf16 v[16:19], v[180:183], v[156:159], v[16:19]
	v_mfma_f32_16x16x32_bf16 v[4:7], v[204:207], v[148:151], v[4:7]
	v_mfma_f32_16x16x32_bf16 v[0:3], v[204:207], v[156:159], v[0:3]
	s_setprio 0
	s_barrier
	s_add_i32 s51, 0, 0x18000
	s_add_i32 s58, 0, 0x1c000
	v_add_u32_e32 v140, s51, v217
	v_add_u32_e32 v250, s51, v249
	v_add_u32_e32 v156, 0x19000, v217
	v_add_u32_e32 v251, 0x19000, v249
	ds_read_b128 v[104:107], v140
	ds_read_b128 v[112:115], v250
	ds_read_b128 v[124:127], v140 offset:2048
	ds_read_b128 v[140:143], v250 offset:2048
	ds_read_b128 v[144:147], v156
	ds_read_b128 v[148:151], v251
	ds_read_b128 v[152:155], v156 offset:2048
	ds_read_b128 v[156:159], v251 offset:2048
	s_add_u32 s56, s56, 0x80000
	s_addc_u32 s57, s57, 0
	s_mov_b32 m0, s5
	v_lshl_add_u64 v[226:227], s[56:57], 0, v[184:185]
	ds_read_b128 v[160:163], v222 offset:32768
	ds_read_b128 v[164:167], v246 offset:32768
	ds_read_b128 v[168:171], v222 offset:34816
	ds_read_b128 v[172:175], v246 offset:34816
	ds_read_b128 v[176:179], v222 offset:36864
	ds_read_b128 v[180:183], v246 offset:36864
	ds_read_b128 v[200:203], v222 offset:38912
	ds_read_b128 v[204:207], v246 offset:38912
	global_load_lds_dwordx4 v[226:227], off
	v_lshl_add_u64 v[226:227], s[56:57], 0, v[188:189]
	s_mov_b32 m0, s6
	s_nop 0
	global_load_lds_dwordx4 v[226:227], off
	s_waitcnt vmcnt(8)
	s_waitcnt lgkmcnt(0)
	s_barrier
	s_setprio 1
	s_waitcnt lgkmcnt(0)
	v_mfma_f32_16x16x32_bf16 v[136:139], v[160:163], v[104:107], v[136:139]
	v_mfma_f32_16x16x32_bf16 v[132:135], v[160:163], v[124:127], v[132:135]
	v_mfma_f32_16x16x32_bf16 v[116:119], v[168:171], v[104:107], v[116:119]
	v_mfma_f32_16x16x32_bf16 v[108:111], v[168:171], v[124:127], v[108:111]
	v_mfma_f32_16x16x32_bf16 v[92:95], v[176:179], v[104:107], v[92:95]
	v_mfma_f32_16x16x32_bf16 v[88:91], v[176:179], v[124:127], v[88:91]
	v_mfma_f32_16x16x32_bf16 v[76:79], v[200:203], v[104:107], v[76:79]
	v_mfma_f32_16x16x32_bf16 v[72:75], v[200:203], v[124:127], v[72:75]
	v_mfma_f32_16x16x32_bf16 v[136:139], v[164:167], v[112:115], v[136:139]
	v_mfma_f32_16x16x32_bf16 v[132:135], v[164:167], v[140:143], v[132:135]
	v_mfma_f32_16x16x32_bf16 v[116:119], v[172:175], v[112:115], v[116:119]
	v_mfma_f32_16x16x32_bf16 v[108:111], v[172:175], v[140:143], v[108:111]
	v_mfma_f32_16x16x32_bf16 v[92:95], v[180:183], v[112:115], v[92:95]
	v_mfma_f32_16x16x32_bf16 v[88:91], v[180:183], v[140:143], v[88:91]
	v_mfma_f32_16x16x32_bf16 v[76:79], v[204:207], v[112:115], v[76:79]
	v_mfma_f32_16x16x32_bf16 v[72:75], v[204:207], v[140:143], v[72:75]
	v_mfma_f32_16x16x32_bf16 v[128:131], v[160:163], v[144:147], v[128:131]
	v_mfma_f32_16x16x32_bf16 v[120:123], v[160:163], v[152:155], v[120:123]
	v_mfma_f32_16x16x32_bf16 v[100:103], v[168:171], v[144:147], v[100:103]
	v_mfma_f32_16x16x32_bf16 v[96:99], v[168:171], v[152:155], v[96:99]
	v_mfma_f32_16x16x32_bf16 v[84:87], v[176:179], v[144:147], v[84:87]
	v_mfma_f32_16x16x32_bf16 v[80:83], v[176:179], v[152:155], v[80:83]
	v_mfma_f32_16x16x32_bf16 v[68:71], v[200:203], v[144:147], v[68:71]
	v_mfma_f32_16x16x32_bf16 v[64:67], v[200:203], v[152:155], v[64:67]
	v_mfma_f32_16x16x32_bf16 v[128:131], v[164:167], v[148:151], v[128:131]
	v_mfma_f32_16x16x32_bf16 v[120:123], v[164:167], v[156:159], v[120:123]
	v_mfma_f32_16x16x32_bf16 v[100:103], v[172:175], v[148:151], v[100:103]
	v_mfma_f32_16x16x32_bf16 v[96:99], v[172:175], v[156:159], v[96:99]
	v_mfma_f32_16x16x32_bf16 v[84:87], v[180:183], v[148:151], v[84:87]
	v_mfma_f32_16x16x32_bf16 v[80:83], v[180:183], v[156:159], v[80:83]
	v_mfma_f32_16x16x32_bf16 v[68:71], v[204:207], v[148:151], v[68:71]
	v_mfma_f32_16x16x32_bf16 v[64:67], v[204:207], v[156:159], v[64:67]
	s_setprio 0
	s_barrier
; #define PG8_STAGE(bufoff, gbase, voff) do { _Pragma("unroll") for (int _i = 0; _i < 2; ++_i) \
;         __builtin_amdgcn_global_load_lds((const unsigned*)((const char*)(gbase) + (voff)[_i]), (LAS unsigned*)(lds + (bufoff) + ldsw + _i * 8192), 16, 0, 0); } while (0)
; #define PG8_LDA(dst, b, h) do { _Pragma("unroll") for (int m = 0; m < 4; ++m) _Pragma("unroll") for (int k = 0; k < 2; ++k) dst[m][k] = *(const LAS bf16x8*)(lds + PG8_SA(b, h) + aoff + m * 2048 + k * 1024); } while (0)
; #define PG8_MMA(ai, bj, At, Bt) do { __builtin_amdgcn_s_setprio(1); _Pragma("unroll") for (int m = 0; m < 4; ++m) _Pragma("unroll") for (int n = 0; n < 2; ++n) _Pragma("unroll") for (int k = 0; k < 2; ++k) \
;         acc[ai][bj][m][n] = __builtin_amdgcn_mfma_f32_16x16x32_bf16(Bt[n][k], At[m][k], acc[ai][bj][m][n], 0, 0, 0); __builtin_amdgcn_s_setprio(0); } while (0)
; #define PG8_WAIT_V(n) asm volatile("s_waitcnt vmcnt(" #n ")" ::: "memory")
; #define PG8_WAIT_L(n) asm volatile("s_waitcnt lgkmcnt(" #n ")" ::: "memory")
; #define PG8_BAR __builtin_amdgcn_s_barrier()
; #define PG8_SCHED __builtin_amdgcn_sched_barrier(0)
; template <class Epi, class Sched>
; __device__ __forceinline__ void gemm_phase(LAS unsigned char* lds, const int K, const int lda, const int ldb, const Sched& S, const Epi& E) {
;     ...
;             PG8_LDA(At, 1, 1); PG8_STAGE(PG8_SB(1, 0), b3, voffB); PG8_STAGE(PG8_SB(1, 1), b3 + hB, voffB); PG8_STAGE(PG8_SA(1, 0), a3, voffA);
;             PG8_WAIT_V(8); PG8_WAIT_L(0); PG8_BAR; PG8_MMA(1, 0, At, B0); PG8_MMA(1, 1, At, B1); PG8_BAR; PG8_SCHED;
;         }
;         if (wr == 0) PG8_BAR;
	s_add_i32 s51, s51, s1
	v_lshl_add_u64 v[208:209], v[208:209], 0, s[20:21]
	s_mov_b32 m0, s51
	ds_read_b128 v[160:163], v222 offset:49152
	ds_read_b128 v[164:167], v246 offset:49152
	ds_read_b128 v[168:171], v222 offset:51200
	ds_read_b128 v[172:175], v246 offset:51200
	ds_read_b128 v[176:179], v222 offset:53248
	ds_read_b128 v[180:183], v246 offset:53248
	ds_read_b128 v[200:203], v222 offset:55296
	ds_read_b128 v[204:207], v246 offset:55296
	global_load_lds_dwordx4 v[208:209], off
	s_add_i32 m0, s51, 0x2000
	s_add_u32 s54, s54, 0x80080
	v_lshl_add_u64 v[208:209], v[210:211], 0, s[20:21]
	s_addc_u32 s55, s55, 0
	s_add_i32 s51, s58, s1
	global_load_lds_dwordx4 v[208:209], off
	v_lshl_add_u64 v[208:209], s[54:55], 0, v[186:187]
	s_mov_b32 m0, s51
	s_nop 0
	global_load_lds_dwordx4 v[208:209], off
	v_lshl_add_u64 v[208:209], s[54:55], 0, v[190:191]
	s_add_i32 m0, s51, 0x2000
	s_nop 0
	global_load_lds_dwordx4 v[208:209], off
	v_lshl_add_u64 v[208:209], v[212:213], 0, s[20:21]
	s_mov_b32 m0, s14
	s_nop 0
	global_load_lds_dwordx4 v[208:209], off
	v_lshl_add_u64 v[208:209], v[214:215], 0, s[20:21]
	s_mov_b32 m0, s15
	s_nop 0
	global_load_lds_dwordx4 v[208:209], off
	s_waitcnt vmcnt(8)
	s_waitcnt lgkmcnt(0)
	s_barrier
	s_setprio 1
	s_waitcnt lgkmcnt(0)
	v_mfma_f32_16x16x32_bf16 v[60:63], v[160:163], v[104:107], v[60:63]
	v_mfma_f32_16x16x32_bf16 v[56:59], v[160:163], v[124:127], v[56:59]
	v_mfma_f32_16x16x32_bf16 v[44:47], v[168:171], v[104:107], v[44:47]
	v_mfma_f32_16x16x32_bf16 v[40:43], v[168:171], v[124:127], v[40:43]
	v_mfma_f32_16x16x32_bf16 v[28:31], v[176:179], v[104:107], v[28:31]
	v_mfma_f32_16x16x32_bf16 v[24:27], v[176:179], v[124:127], v[24:27]
	v_mfma_f32_16x16x32_bf16 v[12:15], v[200:203], v[104:107], v[12:15]
	v_mfma_f32_16x16x32_bf16 v[8:11], v[200:203], v[124:127], v[8:11]
	v_mfma_f32_16x16x32_bf16 v[60:63], v[164:167], v[112:115], v[60:63]
	v_mfma_f32_16x16x32_bf16 v[56:59], v[164:167], v[140:143], v[56:59]
	v_mfma_f32_16x16x32_bf16 v[44:47], v[172:175], v[112:115], v[44:47]
	v_mfma_f32_16x16x32_bf16 v[40:43], v[172:175], v[140:143], v[40:43]
	v_mfma_f32_16x16x32_bf16 v[28:31], v[180:183], v[112:115], v[28:31]
	v_mfma_f32_16x16x32_bf16 v[24:27], v[180:183], v[140:143], v[24:27]
	v_mfma_f32_16x16x32_bf16 v[12:15], v[204:207], v[112:115], v[12:15]
	v_mfma_f32_16x16x32_bf16 v[8:11], v[204:207], v[140:143], v[8:11]
	v_mfma_f32_16x16x32_bf16 v[52:55], v[160:163], v[144:147], v[52:55]
	v_mfma_f32_16x16x32_bf16 v[48:51], v[160:163], v[152:155], v[48:51]
	v_mfma_f32_16x16x32_bf16 v[36:39], v[168:171], v[144:147], v[36:39]
	v_mfma_f32_16x16x32_bf16 v[32:35], v[168:171], v[152:155], v[32:35]
	v_mfma_f32_16x16x32_bf16 v[20:23], v[176:179], v[144:147], v[20:23]
	v_mfma_f32_16x16x32_bf16 v[16:19], v[176:179], v[152:155], v[16:19]
	v_mfma_f32_16x16x32_bf16 v[4:7], v[200:203], v[144:147], v[4:7]
	v_mfma_f32_16x16x32_bf16 v[0:3], v[200:203], v[152:155], v[0:3]
	v_mfma_f32_16x16x32_bf16 v[52:55], v[164:167], v[148:151], v[52:55]
	v_mfma_f32_16x16x32_bf16 v[48:51], v[164:167], v[156:159], v[48:51]
	v_mfma_f32_16x16x32_bf16 v[36:39], v[172:175], v[148:151], v[36:39]
	v_mfma_f32_16x16x32_bf16 v[32:35], v[172:175], v[156:159], v[32:35]
	v_mfma_f32_16x16x32_bf16 v[20:23], v[180:183], v[148:151], v[20:23]
	v_mfma_f32_16x16x32_bf16 v[16:19], v[180:183], v[156:159], v[16:19]
	v_mfma_f32_16x16x32_bf16 v[4:7], v[204:207], v[148:151], v[4:7]
	v_mfma_f32_16x16x32_bf16 v[0:3], v[204:207], v[156:159], v[0:3]
	s_setprio 0
	s_barrier
	s_add_i32 s41, s41, 2
	s_add_u32 s38, s38, 0x100
	s_addc_u32 s39, s39, 0
	s_add_u32 s52, s52, 0x100
	s_addc_u32 s53, s53, 0
	s_cmp_gt_u32 s41, 29
	s_cbranch_scc0 .LBB0_1372
	s_and_b64 vcc, exec, s[22:23]
	s_cbranch_vccz .LBB0_1375
	s_barrier

; #define PG8_STAGE(bufoff, gbase, voff) do { _Pragma("unroll") for (int _i = 0; _i < 2; ++_i) \
;         __builtin_amdgcn_global_load_lds((const unsigned*)((const char*)(gbase) + (voff)[_i]), (LAS unsigned*)(lds + (bufoff) + ldsw + _i * 8192), 16, 0, 0); } while (0)
; #define PG8_LDA(dst, b, h) do { _Pragma("unroll") for (int m = 0; m < 4; ++m) _Pragma("unroll") for (int k = 0; k < 2; ++k) dst[m][k] = *(const LAS bf16x8*)(lds + PG8_SA(b, h) + aoff + m * 2048 + k * 1024); } while (0)
; #define PG8_LDB(dst, b, h) do { _Pragma("unroll") for (int n = 0; n < 2; ++n) _Pragma("unroll") for (int k = 0; k < 2; ++k) dst[n][k] = *(const LAS bf16x8*)(lds + PG8_SB(b, h) + boff + n * 2048 + k * 1024); } while (0)
; #define PG8_MMA(ai, bj, At, Bt) do { __builtin_amdgcn_s_setprio(1); _Pragma("unroll") for (int m = 0; m < 4; ++m) _Pragma("unroll") for (int n = 0; n < 2; ++n) _Pragma("unroll") for (int k = 0; k < 2; ++k) \
;         acc[ai][bj][m][n] = __builtin_amdgcn_mfma_f32_16x16x32_bf16(Bt[n][k], At[m][k], acc[ai][bj][m][n], 0, 0, 0); __builtin_amdgcn_s_setprio(0); } while (0)
; #define PG8_WAIT_V(n) asm volatile("s_waitcnt vmcnt(" #n ")" ::: "memory")
; #define PG8_WAIT_L(n) asm volatile("s_waitcnt lgkmcnt(" #n ")" ::: "memory")
; #define PG8_BAR __builtin_amdgcn_s_barrier()
; #define PG8_SCHED __builtin_amdgcn_sched_barrier(0)
; template <class Epi, class Sched>
; __device__ __forceinline__ void gemm_phase(LAS unsigned char* lds, const int K, const int lda, const int ldb, const Sched& S, const Epi& E) {
;     ...
;         for (int t = 0; t < nt; t += 2) {
;             const bool last = (t == nt - 2);
;             const char* a1 = cA + (size_t)(t + 1) * kstep;
;             const char* a2 = last ? nA : cA + (size_t)(t + 2) * kstep; const char* b2 = last ? nB : cB + (size_t)(t + 2) * kstep;
;             const char* a3 = a2 + kstep; const char* b3 = b2 + kstep;
;             PG8_LDB(B0, 0, 0); PG8_LDB(B1, 0, 1); PG8_SCHED; PG8_LDA(At, 0, 0); PG8_STAGE(PG8_SA(1, 1), a1 + hA, voffA);
;             PG8_WAIT_V(8); PG8_WAIT_L(0); PG8_BAR; PG8_MMA(0, 0, At, B0); PG8_MMA(0, 1, At, B1); PG8_BAR; PG8_SCHED;
;             PG8_LDA(At, 0, 1); PG8_STAGE(PG8_SB(0, 0), b2, voffB); PG8_STAGE(PG8_SB(0, 1), b2 + hB, voffB); PG8_STAGE(PG8_SA(0, 0), a2, voffA);
;             PG8_WAIT_V(8); PG8_WAIT_L(0); PG8_BAR; PG8_MMA(1, 0, At, B0); PG8_MMA(1, 1, At, B1); PG8_BAR; PG8_SCHED;
.LBB0_1448:
	s_waitcnt lgkmcnt(0)
	ds_read_b128 v[158:161], v235
	ds_read_b128 v[162:165], v249
	ds_read_b128 v[166:169], v235 offset:2048
	ds_read_b128 v[170:173], v249 offset:2048
	ds_read_b128 v[174:177], v236
	ds_read_b128 v[178:181], v250
	ds_read_b128 v[182:185], v236 offset:2048
	ds_read_b128 v[186:189], v250 offset:2048
	s_add_u32 s56, s52, 0xfff80080
	s_addc_u32 s57, s53, -1
	s_cmp_eq_u32 s55, 28
	s_cselect_b32 s59, s0, s57
	s_cselect_b32 s58, s1, s56
	s_cselect_b32 s57, s11, s47
	s_cselect_b32 s56, s41, s45
	v_lshl_add_u64 v[222:223], s[52:53], 0, v[148:149]
	s_add_i32 m0, s14, 0xc000
	ds_read_b128 v[190:193], v145
	ds_read_b128 v[194:197], v248
	ds_read_b128 v[198:201], v145 offset:2048
	ds_read_b128 v[202:205], v248 offset:2048
	ds_read_b128 v[206:209], v145 offset:4096
	ds_read_b128 v[210:213], v248 offset:4096
	ds_read_b128 v[214:217], v145 offset:6144
	ds_read_b128 v[218:221], v248 offset:6144
	global_load_lds_dwordx4 v[222:223], off
	v_lshl_add_u64 v[222:223], s[52:53], 0, v[146:147]
	s_add_i32 m0, s14, 0xe000
	s_nop 0
	global_load_lds_dwordx4 v[222:223], off
	s_waitcnt vmcnt(8)
	s_waitcnt lgkmcnt(0)
	s_barrier
	s_setprio 1
	s_waitcnt lgkmcnt(0)
	v_mfma_f32_16x16x32_bf16 v[124:127], v[158:161], v[190:193], v[124:127]
	v_mfma_f32_16x16x32_bf16 v[116:119], v[166:169], v[190:193], v[116:119]
	v_mfma_f32_16x16x32_bf16 v[108:111], v[158:161], v[198:201], v[108:111]
	v_mfma_f32_16x16x32_bf16 v[100:103], v[166:169], v[198:201], v[100:103]
	v_mfma_f32_16x16x32_bf16 v[92:95], v[158:161], v[206:209], v[92:95]
	v_mfma_f32_16x16x32_bf16 v[84:87], v[166:169], v[206:209], v[84:87]
	v_mfma_f32_16x16x32_bf16 v[76:79], v[158:161], v[214:217], v[76:79]
	v_mfma_f32_16x16x32_bf16 v[68:71], v[166:169], v[214:217], v[68:71]
	v_mfma_f32_16x16x32_bf16 v[124:127], v[162:165], v[194:197], v[124:127]
	v_mfma_f32_16x16x32_bf16 v[116:119], v[170:173], v[194:197], v[116:119]
	v_mfma_f32_16x16x32_bf16 v[108:111], v[162:165], v[202:205], v[108:111]
	v_mfma_f32_16x16x32_bf16 v[100:103], v[170:173], v[202:205], v[100:103]
	v_mfma_f32_16x16x32_bf16 v[92:95], v[162:165], v[210:213], v[92:95]
	v_mfma_f32_16x16x32_bf16 v[84:87], v[170:173], v[210:213], v[84:87]
	v_mfma_f32_16x16x32_bf16 v[76:79], v[162:165], v[218:221], v[76:79]
	v_mfma_f32_16x16x32_bf16 v[68:71], v[170:173], v[218:221], v[68:71]
	v_mfma_f32_16x16x32_bf16 v[120:123], v[174:177], v[190:193], v[120:123]
	v_mfma_f32_16x16x32_bf16 v[112:115], v[182:185], v[190:193], v[112:115]
	v_mfma_f32_16x16x32_bf16 v[104:107], v[174:177], v[198:201], v[104:107]
	v_mfma_f32_16x16x32_bf16 v[96:99], v[182:185], v[198:201], v[96:99]
	v_mfma_f32_16x16x32_bf16 v[88:91], v[174:177], v[206:209], v[88:91]
	v_mfma_f32_16x16x32_bf16 v[80:83], v[182:185], v[206:209], v[80:83]
	v_mfma_f32_16x16x32_bf16 v[72:75], v[174:177], v[214:217], v[72:75]
	v_mfma_f32_16x16x32_bf16 v[64:67], v[182:185], v[214:217], v[64:67]
	v_mfma_f32_16x16x32_bf16 v[120:123], v[178:181], v[194:197], v[120:123]
	v_mfma_f32_16x16x32_bf16 v[112:115], v[186:189], v[194:197], v[112:115]
	v_mfma_f32_16x16x32_bf16 v[104:107], v[178:181], v[202:205], v[104:107]
	v_mfma_f32_16x16x32_bf16 v[96:99], v[186:189], v[202:205], v[96:99]
	v_mfma_f32_16x16x32_bf16 v[88:91], v[178:181], v[210:213], v[88:91]
	v_mfma_f32_16x16x32_bf16 v[80:83], v[186:189], v[210:213], v[80:83]
	v_mfma_f32_16x16x32_bf16 v[72:75], v[178:181], v[218:221], v[72:75]
	v_mfma_f32_16x16x32_bf16 v[64:67], v[186:189], v[218:221], v[64:67]
	s_setprio 0
	s_barrier
	s_add_i32 s60, s72, s2
	v_lshl_add_u64 v[222:223], s[56:57], 0, v[130:131]
	s_mov_b32 m0, s60
	ds_read_b128 v[190:193], v145 offset:16384
	ds_read_b128 v[194:197], v248 offset:16384
	ds_read_b128 v[198:201], v145 offset:18432
	ds_read_b128 v[202:205], v248 offset:18432
	ds_read_b128 v[206:209], v145 offset:20480
	ds_read_b128 v[210:213], v248 offset:20480
	ds_read_b128 v[214:217], v145 offset:22528
	ds_read_b128 v[218:221], v248 offset:22528
	global_load_lds_dwordx4 v[222:223], off
	s_add_i32 m0, s60, 0x2000
	s_add_u32 s60, s56, 0x80000
	v_lshl_add_u64 v[224:225], s[56:57], 0, v[134:135]
	s_addc_u32 s61, s57, 0
	s_add_i32 s62, s73, s2
	global_load_lds_dwordx4 v[224:225], off
	v_lshl_add_u64 v[226:227], s[60:61], 0, v[130:131]
	s_mov_b32 m0, s62
	v_lshl_add_u64 v[228:229], s[58:59], 0, v[132:133]
	global_load_lds_dwordx4 v[226:227], off
	v_lshl_add_u64 v[226:227], s[60:61], 0, v[134:135]
	s_add_i32 m0, s62, 0x2000
	s_nop 0
	global_load_lds_dwordx4 v[226:227], off
	v_lshl_add_u64 v[226:227], s[58:59], 0, v[128:129]
	s_mov_b32 m0, s14
	s_nop 0
	global_load_lds_dwordx4 v[226:227], off
	s_mov_b32 m0, s15
	s_nop 0
	global_load_lds_dwordx4 v[228:229], off
	s_waitcnt vmcnt(8)
	s_waitcnt lgkmcnt(0)
	s_barrier
; #define PG8_STAGE(bufoff, gbase, voff) do { _Pragma("unroll") for (int _i = 0; _i < 2; ++_i) \
;         __builtin_amdgcn_global_load_lds((const unsigned*)((const char*)(gbase) + (voff)[_i]), (LAS unsigned*)(lds + (bufoff) + ldsw + _i * 8192), 16, 0, 0); } while (0)
; #define PG8_LDA(dst, b, h) do { _Pragma("unroll") for (int m = 0; m < 4; ++m) _Pragma("unroll") for (int k = 0; k < 2; ++k) dst[m][k] = *(const LAS bf16x8*)(lds + PG8_SA(b, h) + aoff + m * 2048 + k * 1024); } while (0)
; #define PG8_LDB(dst, b, h) do { _Pragma("unroll") for (int n = 0; n < 2; ++n) _Pragma("unroll") for (int k = 0; k < 2; ++k) dst[n][k] = *(const LAS bf16x8*)(lds + PG8_SB(b, h) + boff + n * 2048 + k * 1024); } while (0)
; #define PG8_MMA(ai, bj, At, Bt) do { __builtin_amdgcn_s_setprio(1); _Pragma("unroll") for (int m = 0; m < 4; ++m) _Pragma("unroll") for (int n = 0; n < 2; ++n) _Pragma("unroll") for (int k = 0; k < 2; ++k) \
;         acc[ai][bj][m][n] = __builtin_amdgcn_mfma_f32_16x16x32_bf16(Bt[n][k], At[m][k], acc[ai][bj][m][n], 0, 0, 0); __builtin_amdgcn_s_setprio(0); } while (0)
; #define PG8_WAIT_V(n) asm volatile("s_waitcnt vmcnt(" #n ")" ::: "memory")
; #define PG8_WAIT_L(n) asm volatile("s_waitcnt lgkmcnt(" #n ")" ::: "memory")
; #define PG8_BAR __builtin_amdgcn_s_barrier()
; #define PG8_SCHED __builtin_amdgcn_sched_barrier(0)
; template <class Epi, class Sched>
; __device__ __forceinline__ void gemm_phase(LAS unsigned char* lds, const int K, const int lda, const int ldb, const Sched& S, const Epi& E) {
;     ...
;             PG8_WAIT_V(8); PG8_WAIT_L(0); PG8_BAR; PG8_MMA(1, 0, At, B0); PG8_MMA(1, 1, At, B1); PG8_BAR; PG8_SCHED;
;             PG8_LDB(B0, 1, 0); PG8_LDB(B1, 1, 1); PG8_SCHED; PG8_LDA(At, 1, 0); PG8_STAGE(PG8_SA(0, 1), a2 + hA, voffA);
;             PG8_WAIT_V(8); PG8_WAIT_L(0); PG8_BAR; PG8_MMA(0, 0, At, B0); PG8_MMA(0, 1, At, B1); PG8_BAR; PG8_SCHED;
	s_setprio 1
	s_waitcnt lgkmcnt(0)
	v_mfma_f32_16x16x32_bf16 v[60:63], v[158:161], v[190:193], v[60:63]
	v_mfma_f32_16x16x32_bf16 v[52:55], v[166:169], v[190:193], v[52:55]
	v_mfma_f32_16x16x32_bf16 v[44:47], v[158:161], v[198:201], v[44:47]
	v_mfma_f32_16x16x32_bf16 v[36:39], v[166:169], v[198:201], v[36:39]
	v_mfma_f32_16x16x32_bf16 v[28:31], v[158:161], v[206:209], v[28:31]
	v_mfma_f32_16x16x32_bf16 v[20:23], v[166:169], v[206:209], v[20:23]
	v_mfma_f32_16x16x32_bf16 v[12:15], v[158:161], v[214:217], v[12:15]
	v_mfma_f32_16x16x32_bf16 v[4:7], v[166:169], v[214:217], v[4:7]
	v_mfma_f32_16x16x32_bf16 v[60:63], v[162:165], v[194:197], v[60:63]
	v_mfma_f32_16x16x32_bf16 v[52:55], v[170:173], v[194:197], v[52:55]
	v_mfma_f32_16x16x32_bf16 v[44:47], v[162:165], v[202:205], v[44:47]
	v_mfma_f32_16x16x32_bf16 v[36:39], v[170:173], v[202:205], v[36:39]
	v_mfma_f32_16x16x32_bf16 v[28:31], v[162:165], v[210:213], v[28:31]
	v_mfma_f32_16x16x32_bf16 v[20:23], v[170:173], v[210:213], v[20:23]
	v_mfma_f32_16x16x32_bf16 v[12:15], v[162:165], v[218:221], v[12:15]
	v_mfma_f32_16x16x32_bf16 v[4:7], v[170:173], v[218:221], v[4:7]
	v_mfma_f32_16x16x32_bf16 v[56:59], v[174:177], v[190:193], v[56:59]
	v_mfma_f32_16x16x32_bf16 v[48:51], v[182:185], v[190:193], v[48:51]
	v_mfma_f32_16x16x32_bf16 v[40:43], v[174:177], v[198:201], v[40:43]
	v_mfma_f32_16x16x32_bf16 v[32:35], v[182:185], v[198:201], v[32:35]
	v_mfma_f32_16x16x32_bf16 v[24:27], v[174:177], v[206:209], v[24:27]
	v_mfma_f32_16x16x32_bf16 v[16:19], v[182:185], v[206:209], v[16:19]
	v_mfma_f32_16x16x32_bf16 v[8:11], v[174:177], v[214:217], v[8:11]
	v_mfma_f32_16x16x32_bf16 v[0:3], v[182:185], v[214:217], v[0:3]
	v_mfma_f32_16x16x32_bf16 v[56:59], v[178:181], v[194:197], v[56:59]
	v_mfma_f32_16x16x32_bf16 v[48:51], v[186:189], v[194:197], v[48:51]
	v_mfma_f32_16x16x32_bf16 v[40:43], v[178:181], v[202:205], v[40:43]
	v_mfma_f32_16x16x32_bf16 v[32:35], v[186:189], v[202:205], v[32:35]
	v_mfma_f32_16x16x32_bf16 v[24:27], v[178:181], v[210:213], v[24:27]
	v_mfma_f32_16x16x32_bf16 v[16:19], v[186:189], v[210:213], v[16:19]
	v_mfma_f32_16x16x32_bf16 v[8:11], v[178:181], v[218:221], v[8:11]
	v_mfma_f32_16x16x32_bf16 v[0:3], v[186:189], v[218:221], v[0:3]
	s_setprio 0
	s_barrier
	s_add_i32 s60, 0, 0x18000
	v_add_u32_e32 v151, s60, v143
	v_add_u32_e32 v252, s60, v251
	s_add_i32 s61, 0, 0x1c000
	ds_read_b128 v[158:161], v151
	ds_read_b128 v[162:165], v252
	ds_read_b128 v[166:169], v151 offset:2048
	ds_read_b128 v[170:173], v252 offset:2048
	v_add_u32_e32 v151, s61, v143
	v_add_u32_e32 v252, s61, v251
	ds_read_b128 v[174:177], v151
	ds_read_b128 v[178:181], v252
	ds_read_b128 v[182:185], v151 offset:2048
	ds_read_b128 v[186:189], v252 offset:2048
	s_add_u32 s58, s58, 0x80000
	s_addc_u32 s59, s59, 0
	s_mov_b32 m0, s30
	v_lshl_add_u64 v[230:231], s[58:59], 0, v[128:129]
	ds_read_b128 v[190:193], v145 offset:32768
	ds_read_b128 v[194:197], v248 offset:32768
	ds_read_b128 v[198:201], v145 offset:34816
	ds_read_b128 v[202:205], v248 offset:34816
	ds_read_b128 v[206:209], v145 offset:36864
	ds_read_b128 v[210:213], v248 offset:36864
	ds_read_b128 v[214:217], v145 offset:38912
	ds_read_b128 v[218:221], v248 offset:38912
	global_load_lds_dwordx4 v[230:231], off
	v_lshl_add_u64 v[230:231], s[58:59], 0, v[132:133]
	s_mov_b32 m0, s31
	s_nop 0
	global_load_lds_dwordx4 v[230:231], off
	s_waitcnt vmcnt(8)
	s_waitcnt lgkmcnt(0)
	s_barrier
	s_setprio 1
	s_waitcnt lgkmcnt(0)
	v_mfma_f32_16x16x32_bf16 v[124:127], v[158:161], v[190:193], v[124:127]
	v_mfma_f32_16x16x32_bf16 v[116:119], v[166:169], v[190:193], v[116:119]
	v_mfma_f32_16x16x32_bf16 v[108:111], v[158:161], v[198:201], v[108:111]
	v_mfma_f32_16x16x32_bf16 v[100:103], v[166:169], v[198:201], v[100:103]
	v_mfma_f32_16x16x32_bf16 v[92:95], v[158:161], v[206:209], v[92:95]
	v_mfma_f32_16x16x32_bf16 v[84:87], v[166:169], v[206:209], v[84:87]
	v_mfma_f32_16x16x32_bf16 v[76:79], v[158:161], v[214:217], v[76:79]
	v_mfma_f32_16x16x32_bf16 v[68:71], v[166:169], v[214:217], v[68:71]
	v_mfma_f32_16x16x32_bf16 v[124:127], v[162:165], v[194:197], v[124:127]
	v_mfma_f32_16x16x32_bf16 v[116:119], v[170:173], v[194:197], v[116:119]
	v_mfma_f32_16x16x32_bf16 v[108:111], v[162:165], v[202:205], v[108:111]
	v_mfma_f32_16x16x32_bf16 v[100:103], v[170:173], v[202:205], v[100:103]
	v_mfma_f32_16x16x32_bf16 v[92:95], v[162:165], v[210:213], v[92:95]
	v_mfma_f32_16x16x32_bf16 v[84:87], v[170:173], v[210:213], v[84:87]
	v_mfma_f32_16x16x32_bf16 v[76:79], v[162:165], v[218:221], v[76:79]
	v_mfma_f32_16x16x32_bf16 v[68:71], v[170:173], v[218:221], v[68:71]
	v_mfma_f32_16x16x32_bf16 v[120:123], v[174:177], v[190:193], v[120:123]
	v_mfma_f32_16x16x32_bf16 v[112:115], v[182:185], v[190:193], v[112:115]
	v_mfma_f32_16x16x32_bf16 v[104:107], v[174:177], v[198:201], v[104:107]
	v_mfma_f32_16x16x32_bf16 v[96:99], v[182:185], v[198:201], v[96:99]
	v_mfma_f32_16x16x32_bf16 v[88:91], v[174:177], v[206:209], v[88:91]
	v_mfma_f32_16x16x32_bf16 v[80:83], v[182:185], v[206:209], v[80:83]
	v_mfma_f32_16x16x32_bf16 v[72:75], v[174:177], v[214:217], v[72:75]
	v_mfma_f32_16x16x32_bf16 v[64:67], v[182:185], v[214:217], v[64:67]
	v_mfma_f32_16x16x32_bf16 v[120:123], v[178:181], v[194:197], v[120:123]
	v_mfma_f32_16x16x32_bf16 v[112:115], v[186:189], v[194:197], v[112:115]
	v_mfma_f32_16x16x32_bf16 v[104:107], v[178:181], v[202:205], v[104:107]
	v_mfma_f32_16x16x32_bf16 v[96:99], v[186:189], v[202:205], v[96:99]
	v_mfma_f32_16x16x32_bf16 v[88:91], v[178:181], v[210:213], v[88:91]
	v_mfma_f32_16x16x32_bf16 v[80:83], v[186:189], v[210:213], v[80:83]
	v_mfma_f32_16x16x32_bf16 v[72:75], v[178:181], v[218:221], v[72:75]
	v_mfma_f32_16x16x32_bf16 v[64:67], v[186:189], v[218:221], v[64:67]
	s_setprio 0
	s_barrier
; #define PG8_STAGE(bufoff, gbase, voff) do { _Pragma("unroll") for (int _i = 0; _i < 2; ++_i) \
;         __builtin_amdgcn_global_load_lds((const unsigned*)((const char*)(gbase) + (voff)[_i]), (LAS unsigned*)(lds + (bufoff) + ldsw + _i * 8192), 16, 0, 0); } while (0)
; #define PG8_LDA(dst, b, h) do { _Pragma("unroll") for (int m = 0; m < 4; ++m) _Pragma("unroll") for (int k = 0; k < 2; ++k) dst[m][k] = *(const LAS bf16x8*)(lds + PG8_SA(b, h) + aoff + m * 2048 + k * 1024); } while (0)
; #define PG8_MMA(ai, bj, At, Bt) do { __builtin_amdgcn_s_setprio(1); _Pragma("unroll") for (int m = 0; m < 4; ++m) _Pragma("unroll") for (int n = 0; n < 2; ++n) _Pragma("unroll") for (int k = 0; k < 2; ++k) \
;         acc[ai][bj][m][n] = __builtin_amdgcn_mfma_f32_16x16x32_bf16(Bt[n][k], At[m][k], acc[ai][bj][m][n], 0, 0, 0); __builtin_amdgcn_s_setprio(0); } while (0)
; #define PG8_WAIT_V(n) asm volatile("s_waitcnt vmcnt(" #n ")" ::: "memory")
; #define PG8_WAIT_L(n) asm volatile("s_waitcnt lgkmcnt(" #n ")" ::: "memory")
; #define PG8_BAR __builtin_amdgcn_s_barrier()
; #define PG8_SCHED __builtin_amdgcn_sched_barrier(0)
; template <class Epi, class Sched>
; __device__ __forceinline__ void gemm_phase(LAS unsigned char* lds, const int K, const int lda, const int ldb, const Sched& S, const Epi& E) {
;     ...
;             PG8_LDA(At, 1, 1); PG8_STAGE(PG8_SB(1, 0), b3, voffB); PG8_STAGE(PG8_SB(1, 1), b3 + hB, voffB); PG8_STAGE(PG8_SA(1, 0), a3, voffA);
;             PG8_WAIT_V(8); PG8_WAIT_L(0); PG8_BAR; PG8_MMA(1, 0, At, B0); PG8_MMA(1, 1, At, B1); PG8_BAR; PG8_SCHED;
;         }
;         if (wr == 0) PG8_BAR;
	s_add_i32 s58, s60, s2
	v_lshl_add_u64 v[222:223], v[222:223], 0, s[26:27]
	s_mov_b32 m0, s58
	ds_read_b128 v[190:193], v145 offset:49152
	ds_read_b128 v[194:197], v248 offset:49152
	ds_read_b128 v[198:201], v145 offset:51200
	ds_read_b128 v[202:205], v248 offset:51200
	ds_read_b128 v[206:209], v145 offset:53248
	ds_read_b128 v[210:213], v248 offset:53248
	ds_read_b128 v[214:217], v145 offset:55296
	ds_read_b128 v[218:221], v248 offset:55296
	global_load_lds_dwordx4 v[222:223], off
	s_add_i32 m0, s58, 0x2000
	s_add_u32 s56, s56, 0x80080
	v_lshl_add_u64 v[222:223], v[224:225], 0, s[26:27]
	s_addc_u32 s57, s57, 0
	s_add_i32 s58, s61, s2
	global_load_lds_dwordx4 v[222:223], off
	v_lshl_add_u64 v[222:223], s[56:57], 0, v[130:131]
	s_mov_b32 m0, s58
	s_nop 0
	global_load_lds_dwordx4 v[222:223], off
	v_lshl_add_u64 v[222:223], s[56:57], 0, v[134:135]
	s_add_i32 m0, s58, 0x2000
	s_nop 0
	global_load_lds_dwordx4 v[222:223], off
	v_lshl_add_u64 v[222:223], v[226:227], 0, s[26:27]
	s_mov_b32 m0, s35
	s_nop 0
	global_load_lds_dwordx4 v[222:223], off
	v_lshl_add_u64 v[222:223], v[228:229], 0, s[26:27]
	s_mov_b32 m0, s38
	s_nop 0
	global_load_lds_dwordx4 v[222:223], off
	s_waitcnt vmcnt(8)
	s_waitcnt lgkmcnt(0)
	s_barrier
	s_setprio 1
	s_waitcnt lgkmcnt(0)
	v_mfma_f32_16x16x32_bf16 v[60:63], v[158:161], v[190:193], v[60:63]
	v_mfma_f32_16x16x32_bf16 v[52:55], v[166:169], v[190:193], v[52:55]
	v_mfma_f32_16x16x32_bf16 v[44:47], v[158:161], v[198:201], v[44:47]
	v_mfma_f32_16x16x32_bf16 v[36:39], v[166:169], v[198:201], v[36:39]
	v_mfma_f32_16x16x32_bf16 v[28:31], v[158:161], v[206:209], v[28:31]
	v_mfma_f32_16x16x32_bf16 v[20:23], v[166:169], v[206:209], v[20:23]
	v_mfma_f32_16x16x32_bf16 v[12:15], v[158:161], v[214:217], v[12:15]
	v_mfma_f32_16x16x32_bf16 v[4:7], v[166:169], v[214:217], v[4:7]
	v_mfma_f32_16x16x32_bf16 v[60:63], v[162:165], v[194:197], v[60:63]
	v_mfma_f32_16x16x32_bf16 v[52:55], v[170:173], v[194:197], v[52:55]
	v_mfma_f32_16x16x32_bf16 v[44:47], v[162:165], v[202:205], v[44:47]
	v_mfma_f32_16x16x32_bf16 v[36:39], v[170:173], v[202:205], v[36:39]
	v_mfma_f32_16x16x32_bf16 v[28:31], v[162:165], v[210:213], v[28:31]
	v_mfma_f32_16x16x32_bf16 v[20:23], v[170:173], v[210:213], v[20:23]
	v_mfma_f32_16x16x32_bf16 v[12:15], v[162:165], v[218:221], v[12:15]
	v_mfma_f32_16x16x32_bf16 v[4:7], v[170:173], v[218:221], v[4:7]
	v_mfma_f32_16x16x32_bf16 v[56:59], v[174:177], v[190:193], v[56:59]
	v_mfma_f32_16x16x32_bf16 v[48:51], v[182:185], v[190:193], v[48:51]
	v_mfma_f32_16x16x32_bf16 v[40:43], v[174:177], v[198:201], v[40:43]
	v_mfma_f32_16x16x32_bf16 v[32:35], v[182:185], v[198:201], v[32:35]
	v_mfma_f32_16x16x32_bf16 v[24:27], v[174:177], v[206:209], v[24:27]
	v_mfma_f32_16x16x32_bf16 v[16:19], v[182:185], v[206:209], v[16:19]
	v_mfma_f32_16x16x32_bf16 v[8:11], v[174:177], v[214:217], v[8:11]
	v_mfma_f32_16x16x32_bf16 v[0:3], v[182:185], v[214:217], v[0:3]
	v_mfma_f32_16x16x32_bf16 v[56:59], v[178:181], v[194:197], v[56:59]
	v_mfma_f32_16x16x32_bf16 v[48:51], v[186:189], v[194:197], v[48:51]
	v_mfma_f32_16x16x32_bf16 v[40:43], v[178:181], v[202:205], v[40:43]
	v_mfma_f32_16x16x32_bf16 v[32:35], v[186:189], v[202:205], v[32:35]
	v_mfma_f32_16x16x32_bf16 v[24:27], v[178:181], v[210:213], v[24:27]
	v_mfma_f32_16x16x32_bf16 v[16:19], v[186:189], v[210:213], v[16:19]
	v_mfma_f32_16x16x32_bf16 v[8:11], v[178:181], v[218:221], v[8:11]
	v_mfma_f32_16x16x32_bf16 v[0:3], v[186:189], v[218:221], v[0:3]
	s_setprio 0
	s_barrier
	s_add_i32 s55, s55, 2
	s_add_u32 s45, s45, 0x100
	s_addc_u32 s47, s47, 0
	s_add_u32 s52, s52, 0x100
	s_addc_u32 s53, s53, 0
	s_cmp_gt_u32 s55, 29
	s_cbranch_scc0 .LBB0_1448
	s_and_b64 vcc, exec, s[28:29]
	s_cbranch_vccz .LBB0_1451
	s_barrier

; #define PG8_STAGE(bufoff, gbase, voff) do { _Pragma("unroll") for (int _i = 0; _i < 2; ++_i) \
;         __builtin_amdgcn_global_load_lds((const unsigned*)((const char*)(gbase) + (voff)[_i]), (LAS unsigned*)(lds + (bufoff) + ldsw + _i * 8192), 16, 0, 0); } while (0)
; #define PG8_LDA(dst, b, h) do { _Pragma("unroll") for (int m = 0; m < 4; ++m) _Pragma("unroll") for (int k = 0; k < 2; ++k) dst[m][k] = *(const LAS bf16x8*)(lds + PG8_SA(b, h) + aoff + m * 2048 + k * 1024); } while (0)
; #define PG8_LDB(dst, b, h) do { _Pragma("unroll") for (int n = 0; n < 2; ++n) _Pragma("unroll") for (int k = 0; k < 2; ++k) dst[n][k] = *(const LAS bf16x8*)(lds + PG8_SB(b, h) + boff + n * 2048 + k * 1024); } while (0)
; #define PG8_MMA(ai, bj, At, Bt) do { __builtin_amdgcn_s_setprio(1); _Pragma("unroll") for (int m = 0; m < 4; ++m) _Pragma("unroll") for (int n = 0; n < 2; ++n) _Pragma("unroll") for (int k = 0; k < 2; ++k) \
;         acc[ai][bj][m][n] = __builtin_amdgcn_mfma_f32_16x16x32_bf16(Bt[n][k], At[m][k], acc[ai][bj][m][n], 0, 0, 0); __builtin_amdgcn_s_setprio(0); } while (0)
; #define PG8_WAIT_V(n) asm volatile("s_waitcnt vmcnt(" #n ")" ::: "memory")
; #define PG8_WAIT_L(n) asm volatile("s_waitcnt lgkmcnt(" #n ")" ::: "memory")
; #define PG8_BAR __builtin_amdgcn_s_barrier()
; #define PG8_SCHED __builtin_amdgcn_sched_barrier(0)
; template <class Epi, class Sched>
; __device__ __forceinline__ void gemm_phase(LAS unsigned char* lds, const int K, const int lda, const int ldb, const Sched& S, const Epi& E) {
;     ...
;         for (int t = 0; t < nt; t += 2) {
;             const bool last = (t == nt - 2);
;             const char* a1 = cA + (size_t)(t + 1) * kstep;
;             const char* a2 = last ? nA : cA + (size_t)(t + 2) * kstep; const char* b2 = last ? nB : cB + (size_t)(t + 2) * kstep;
;             const char* a3 = a2 + kstep; const char* b3 = b2 + kstep;
;             PG8_LDB(B0, 0, 0); PG8_LDB(B1, 0, 1); PG8_SCHED; PG8_LDA(At, 0, 0); PG8_STAGE(PG8_SA(1, 1), a1 + hA, voffA);
;             PG8_WAIT_V(8); PG8_WAIT_L(0); PG8_BAR; PG8_MMA(0, 0, At, B0); PG8_MMA(0, 1, At, B1); PG8_BAR; PG8_SCHED;
;             PG8_LDA(At, 0, 1); PG8_STAGE(PG8_SB(0, 0), b2, voffB); PG8_STAGE(PG8_SB(0, 1), b2 + hB, voffB); PG8_STAGE(PG8_SA(0, 0), a2, voffA);
.LBB0_1625:
	ds_read_b128 v[128:131], v197
	ds_read_b128 v[132:135], v197 offset:1024
	ds_read_b128 v[136:139], v197 offset:2048
	ds_read_b128 v[140:143], v197 offset:3072
	ds_read_b128 v[144:147], v198
	ds_read_b128 v[148:151], v198 offset:1024
	ds_read_b128 v[152:155], v198 offset:2048
	ds_read_b128 v[156:159], v198 offset:3072
	s_add_u32 s30, s28, 0xfff80080
	s_addc_u32 s31, s29, -1
	s_cmp_eq_u32 s51, 28
	s_cselect_b32 s35, s21, s31
	s_cselect_b32 s34, s47, s30
	s_cselect_b32 s31, s19, s50
	s_cselect_b32 s30, s48, s49
	v_lshl_add_u64 v[192:193], s[28:29], 0, v[174:175]
	s_add_i32 m0, s27, 0xc000
	ds_read_b128 v[160:163], v199
	ds_read_b128 v[180:183], v199 offset:1024
	ds_read_b128 v[184:187], v199 offset:2048
	ds_read_b128 v[188:191], v199 offset:3072
	ds_read_b128 v[200:203], v199 offset:4096
	ds_read_b128 v[204:207], v199 offset:5120
	ds_read_b128 v[208:211], v199 offset:6144
	ds_read_b128 v[212:215], v199 offset:7168
	global_load_lds_dwordx4 v[192:193], off
	v_lshl_add_u64 v[192:193], s[28:29], 0, v[172:173]
	s_add_i32 m0, s27, 0xe000
	s_nop 0
	global_load_lds_dwordx4 v[192:193], off
	s_waitcnt vmcnt(8)
	s_waitcnt lgkmcnt(0)
	s_barrier
	s_setprio 1
	s_waitcnt lgkmcnt(0)
	v_mfma_f32_16x16x32_bf16 v[124:127], v[160:163], v[128:131], v[124:127]
	v_mfma_f32_16x16x32_bf16 v[120:123], v[160:163], v[136:139], v[120:123]
	v_mfma_f32_16x16x32_bf16 v[108:111], v[184:187], v[128:131], v[108:111]
	v_mfma_f32_16x16x32_bf16 v[104:107], v[184:187], v[136:139], v[104:107]
	v_mfma_f32_16x16x32_bf16 v[96:99], v[200:203], v[128:131], v[96:99]
	v_mfma_f32_16x16x32_bf16 v[88:91], v[200:203], v[136:139], v[88:91]
	v_mfma_f32_16x16x32_bf16 v[80:83], v[208:211], v[128:131], v[80:83]
	v_mfma_f32_16x16x32_bf16 v[72:75], v[208:211], v[136:139], v[72:75]
	v_mfma_f32_16x16x32_bf16 v[124:127], v[180:183], v[132:135], v[124:127]
	v_mfma_f32_16x16x32_bf16 v[120:123], v[180:183], v[140:143], v[120:123]
	v_mfma_f32_16x16x32_bf16 v[108:111], v[188:191], v[132:135], v[108:111]
	v_mfma_f32_16x16x32_bf16 v[104:107], v[188:191], v[140:143], v[104:107]
	v_mfma_f32_16x16x32_bf16 v[96:99], v[204:207], v[132:135], v[96:99]
	v_mfma_f32_16x16x32_bf16 v[88:91], v[204:207], v[140:143], v[88:91]
	v_mfma_f32_16x16x32_bf16 v[80:83], v[212:215], v[132:135], v[80:83]
	v_mfma_f32_16x16x32_bf16 v[72:75], v[212:215], v[140:143], v[72:75]
	v_mfma_f32_16x16x32_bf16 v[116:119], v[160:163], v[144:147], v[116:119]
	v_mfma_f32_16x16x32_bf16 v[112:115], v[160:163], v[152:155], v[112:115]
	v_mfma_f32_16x16x32_bf16 v[100:103], v[184:187], v[144:147], v[100:103]
	v_mfma_f32_16x16x32_bf16 v[92:95], v[184:187], v[152:155], v[92:95]
	v_mfma_f32_16x16x32_bf16 v[84:87], v[200:203], v[144:147], v[84:87]
	v_mfma_f32_16x16x32_bf16 v[76:79], v[200:203], v[152:155], v[76:79]
	v_mfma_f32_16x16x32_bf16 v[68:71], v[208:211], v[144:147], v[68:71]
	v_mfma_f32_16x16x32_bf16 v[64:67], v[208:211], v[152:155], v[64:67]
	v_mfma_f32_16x16x32_bf16 v[116:119], v[180:183], v[148:151], v[116:119]
	v_mfma_f32_16x16x32_bf16 v[112:115], v[180:183], v[156:159], v[112:115]
	v_mfma_f32_16x16x32_bf16 v[100:103], v[188:191], v[148:151], v[100:103]
	v_mfma_f32_16x16x32_bf16 v[92:95], v[188:191], v[156:159], v[92:95]
	v_mfma_f32_16x16x32_bf16 v[84:87], v[204:207], v[148:151], v[84:87]
	v_mfma_f32_16x16x32_bf16 v[76:79], v[204:207], v[156:159], v[76:79]
	v_mfma_f32_16x16x32_bf16 v[68:71], v[212:215], v[148:151], v[68:71]
	v_mfma_f32_16x16x32_bf16 v[64:67], v[212:215], v[156:159], v[64:67]
	s_setprio 0
	s_barrier
	s_add_i32 s52, s44, s36
	v_lshl_add_u64 v[192:193], s[30:31], 0, v[166:167]
	s_mov_b32 m0, s52
	ds_read_b128 v[160:163], v199 offset:16384
	ds_read_b128 v[180:183], v199 offset:17408
	ds_read_b128 v[184:187], v199 offset:18432
	ds_read_b128 v[188:191], v199 offset:19456
	ds_read_b128 v[200:203], v199 offset:20480
	ds_read_b128 v[204:207], v199 offset:21504
	ds_read_b128 v[208:211], v199 offset:22528
	ds_read_b128 v[212:215], v199 offset:23552
	global_load_lds_dwordx4 v[192:193], off
	s_add_i32 m0, s52, 0x2000
	s_add_u32 s52, s30, 0x80000
	v_lshl_add_u64 v[216:217], s[30:31], 0, v[170:171]
	s_addc_u32 s53, s31, 0
	s_add_i32 s54, s45, s36
	global_load_lds_dwordx4 v[216:217], off
	v_lshl_add_u64 v[218:219], s[52:53], 0, v[166:167]
	s_mov_b32 m0, s54
	v_lshl_add_u64 v[220:221], s[34:35], 0, v[168:169]
	global_load_lds_dwordx4 v[218:219], off
	v_lshl_add_u64 v[218:219], s[52:53], 0, v[170:171]
	s_add_i32 m0, s54, 0x2000
	s_nop 0
	global_load_lds_dwordx4 v[218:219], off
	v_lshl_add_u64 v[218:219], s[34:35], 0, v[164:165]
	s_mov_b32 m0, s27
	s_nop 0
	global_load_lds_dwordx4 v[218:219], off
	s_mov_b32 m0, s37
	s_nop 0
	global_load_lds_dwordx4 v[220:221], off
	s_waitcnt vmcnt(8)
	s_waitcnt lgkmcnt(0)
	s_barrier
; #define PG8_STAGE(bufoff, gbase, voff) do { _Pragma("unroll") for (int _i = 0; _i < 2; ++_i) \
;         __builtin_amdgcn_global_load_lds((const unsigned*)((const char*)(gbase) + (voff)[_i]), (LAS unsigned*)(lds + (bufoff) + ldsw + _i * 8192), 16, 0, 0); } while (0)
; #define PG8_LDA(dst, b, h) do { _Pragma("unroll") for (int m = 0; m < 4; ++m) _Pragma("unroll") for (int k = 0; k < 2; ++k) dst[m][k] = *(const LAS bf16x8*)(lds + PG8_SA(b, h) + aoff + m * 2048 + k * 1024); } while (0)
; #define PG8_LDB(dst, b, h) do { _Pragma("unroll") for (int n = 0; n < 2; ++n) _Pragma("unroll") for (int k = 0; k < 2; ++k) dst[n][k] = *(const LAS bf16x8*)(lds + PG8_SB(b, h) + boff + n * 2048 + k * 1024); } while (0)
; #define PG8_MMA(ai, bj, At, Bt) do { __builtin_amdgcn_s_setprio(1); _Pragma("unroll") for (int m = 0; m < 4; ++m) _Pragma("unroll") for (int n = 0; n < 2; ++n) _Pragma("unroll") for (int k = 0; k < 2; ++k) \
;         acc[ai][bj][m][n] = __builtin_amdgcn_mfma_f32_16x16x32_bf16(Bt[n][k], At[m][k], acc[ai][bj][m][n], 0, 0, 0); __builtin_amdgcn_s_setprio(0); } while (0)
; #define PG8_WAIT_V(n) asm volatile("s_waitcnt vmcnt(" #n ")" ::: "memory")
; #define PG8_WAIT_L(n) asm volatile("s_waitcnt lgkmcnt(" #n ")" ::: "memory")
; #define PG8_BAR __builtin_amdgcn_s_barrier()
; #define PG8_SCHED __builtin_amdgcn_sched_barrier(0)
; template <class Epi, class Sched>
; __device__ __forceinline__ void gemm_phase(LAS unsigned char* lds, const int K, const int lda, const int ldb, const Sched& S, const Epi& E) {
;     ...
;             PG8_WAIT_V(8); PG8_WAIT_L(0); PG8_BAR; PG8_MMA(1, 0, At, B0); PG8_MMA(1, 1, At, B1); PG8_BAR; PG8_SCHED;
;             PG8_LDB(B0, 1, 0); PG8_LDB(B1, 1, 1); PG8_SCHED; PG8_LDA(At, 1, 0); PG8_STAGE(PG8_SA(0, 1), a2 + hA, voffA);
;             PG8_WAIT_V(8); PG8_WAIT_L(0); PG8_BAR; PG8_MMA(0, 0, At, B0); PG8_MMA(0, 1, At, B1); PG8_BAR; PG8_SCHED;
	s_setprio 1
	s_waitcnt lgkmcnt(0)
	v_mfma_f32_16x16x32_bf16 v[60:63], v[160:163], v[128:131], v[60:63]
	v_mfma_f32_16x16x32_bf16 v[56:59], v[160:163], v[136:139], v[56:59]
	v_mfma_f32_16x16x32_bf16 v[48:51], v[184:187], v[128:131], v[48:51]
	v_mfma_f32_16x16x32_bf16 v[40:43], v[184:187], v[136:139], v[40:43]
	v_mfma_f32_16x16x32_bf16 v[32:35], v[200:203], v[128:131], v[32:35]
	v_mfma_f32_16x16x32_bf16 v[24:27], v[200:203], v[136:139], v[24:27]
	v_mfma_f32_16x16x32_bf16 v[16:19], v[208:211], v[128:131], v[16:19]
	v_mfma_f32_16x16x32_bf16 v[8:11], v[208:211], v[136:139], v[8:11]
	v_mfma_f32_16x16x32_bf16 v[60:63], v[180:183], v[132:135], v[60:63]
	v_mfma_f32_16x16x32_bf16 v[56:59], v[180:183], v[140:143], v[56:59]
	v_mfma_f32_16x16x32_bf16 v[48:51], v[188:191], v[132:135], v[48:51]
	v_mfma_f32_16x16x32_bf16 v[40:43], v[188:191], v[140:143], v[40:43]
	v_mfma_f32_16x16x32_bf16 v[32:35], v[204:207], v[132:135], v[32:35]
	v_mfma_f32_16x16x32_bf16 v[24:27], v[204:207], v[140:143], v[24:27]
	v_mfma_f32_16x16x32_bf16 v[16:19], v[212:215], v[132:135], v[16:19]
	v_mfma_f32_16x16x32_bf16 v[8:11], v[212:215], v[140:143], v[8:11]
	v_mfma_f32_16x16x32_bf16 v[52:55], v[160:163], v[144:147], v[52:55]
	v_mfma_f32_16x16x32_bf16 v[44:47], v[160:163], v[152:155], v[44:47]
	v_mfma_f32_16x16x32_bf16 v[36:39], v[184:187], v[144:147], v[36:39]
	v_mfma_f32_16x16x32_bf16 v[28:31], v[184:187], v[152:155], v[28:31]
	v_mfma_f32_16x16x32_bf16 v[20:23], v[200:203], v[144:147], v[20:23]
	v_mfma_f32_16x16x32_bf16 v[12:15], v[200:203], v[152:155], v[12:15]
	v_mfma_f32_16x16x32_bf16 v[4:7], v[208:211], v[144:147], v[4:7]
	v_mfma_f32_16x16x32_bf16 v[0:3], v[208:211], v[152:155], v[0:3]
	v_mfma_f32_16x16x32_bf16 v[52:55], v[180:183], v[148:151], v[52:55]
	v_mfma_f32_16x16x32_bf16 v[44:47], v[180:183], v[156:159], v[44:47]
	v_mfma_f32_16x16x32_bf16 v[36:39], v[188:191], v[148:151], v[36:39]
	v_mfma_f32_16x16x32_bf16 v[28:31], v[188:191], v[156:159], v[28:31]
	v_mfma_f32_16x16x32_bf16 v[20:23], v[204:207], v[148:151], v[20:23]
	v_mfma_f32_16x16x32_bf16 v[12:15], v[204:207], v[156:159], v[12:15]
	v_mfma_f32_16x16x32_bf16 v[4:7], v[212:215], v[148:151], v[4:7]
	v_mfma_f32_16x16x32_bf16 v[0:3], v[212:215], v[156:159], v[0:3]
	s_setprio 0
	s_barrier
	s_add_i32 s52, 0, 0x18000
	s_add_i32 s53, 0, 0x1c000
	v_add_u32_e32 v140, s52, v195
	v_add_u32_e32 v156, 0x19000, v195
	ds_read_b128 v[128:131], v140
	ds_read_b128 v[132:135], v140 offset:1024
	ds_read_b128 v[136:139], v140 offset:2048
	ds_read_b128 v[140:143], v140 offset:3072
	ds_read_b128 v[144:147], v156
	ds_read_b128 v[148:151], v156 offset:1024
	ds_read_b128 v[152:155], v156 offset:2048
	ds_read_b128 v[156:159], v156 offset:3072
	s_add_u32 s34, s34, 0x80000
	s_addc_u32 s35, s35, 0
	s_mov_b32 m0, s38
	v_lshl_add_u64 v[222:223], s[34:35], 0, v[164:165]
	ds_read_b128 v[160:163], v199 offset:32768
	ds_read_b128 v[180:183], v199 offset:33792
	ds_read_b128 v[184:187], v199 offset:34816
	ds_read_b128 v[188:191], v199 offset:35840
	ds_read_b128 v[200:203], v199 offset:36864
	ds_read_b128 v[204:207], v199 offset:37888
	ds_read_b128 v[208:211], v199 offset:38912
	ds_read_b128 v[212:215], v199 offset:39936
	global_load_lds_dwordx4 v[222:223], off
	v_lshl_add_u64 v[222:223], s[34:35], 0, v[168:169]
	s_mov_b32 m0, s39
	s_nop 0
	global_load_lds_dwordx4 v[222:223], off
	s_waitcnt vmcnt(8)
	s_waitcnt lgkmcnt(0)
	s_barrier
	s_setprio 1
	s_waitcnt lgkmcnt(0)
	v_mfma_f32_16x16x32_bf16 v[124:127], v[160:163], v[128:131], v[124:127]
	v_mfma_f32_16x16x32_bf16 v[120:123], v[160:163], v[136:139], v[120:123]
	v_mfma_f32_16x16x32_bf16 v[108:111], v[184:187], v[128:131], v[108:111]
	v_mfma_f32_16x16x32_bf16 v[104:107], v[184:187], v[136:139], v[104:107]
	v_mfma_f32_16x16x32_bf16 v[96:99], v[200:203], v[128:131], v[96:99]
	v_mfma_f32_16x16x32_bf16 v[88:91], v[200:203], v[136:139], v[88:91]
	v_mfma_f32_16x16x32_bf16 v[80:83], v[208:211], v[128:131], v[80:83]
	v_mfma_f32_16x16x32_bf16 v[72:75], v[208:211], v[136:139], v[72:75]
	v_mfma_f32_16x16x32_bf16 v[124:127], v[180:183], v[132:135], v[124:127]
	v_mfma_f32_16x16x32_bf16 v[120:123], v[180:183], v[140:143], v[120:123]
	v_mfma_f32_16x16x32_bf16 v[108:111], v[188:191], v[132:135], v[108:111]
	v_mfma_f32_16x16x32_bf16 v[104:107], v[188:191], v[140:143], v[104:107]
	v_mfma_f32_16x16x32_bf16 v[96:99], v[204:207], v[132:135], v[96:99]
	v_mfma_f32_16x16x32_bf16 v[88:91], v[204:207], v[140:143], v[88:91]
	v_mfma_f32_16x16x32_bf16 v[80:83], v[212:215], v[132:135], v[80:83]
	v_mfma_f32_16x16x32_bf16 v[72:75], v[212:215], v[140:143], v[72:75]
	v_mfma_f32_16x16x32_bf16 v[116:119], v[160:163], v[144:147], v[116:119]
	v_mfma_f32_16x16x32_bf16 v[112:115], v[160:163], v[152:155], v[112:115]
	v_mfma_f32_16x16x32_bf16 v[100:103], v[184:187], v[144:147], v[100:103]
	v_mfma_f32_16x16x32_bf16 v[92:95], v[184:187], v[152:155], v[92:95]
	v_mfma_f32_16x16x32_bf16 v[84:87], v[200:203], v[144:147], v[84:87]
	v_mfma_f32_16x16x32_bf16 v[76:79], v[200:203], v[152:155], v[76:79]
	v_mfma_f32_16x16x32_bf16 v[68:71], v[208:211], v[144:147], v[68:71]
	v_mfma_f32_16x16x32_bf16 v[64:67], v[208:211], v[152:155], v[64:67]
	v_mfma_f32_16x16x32_bf16 v[116:119], v[180:183], v[148:151], v[116:119]
	v_mfma_f32_16x16x32_bf16 v[112:115], v[180:183], v[156:159], v[112:115]
	v_mfma_f32_16x16x32_bf16 v[100:103], v[188:191], v[148:151], v[100:103]
	v_mfma_f32_16x16x32_bf16 v[92:95], v[188:191], v[156:159], v[92:95]
	v_mfma_f32_16x16x32_bf16 v[84:87], v[204:207], v[148:151], v[84:87]
	v_mfma_f32_16x16x32_bf16 v[76:79], v[204:207], v[156:159], v[76:79]
	v_mfma_f32_16x16x32_bf16 v[68:71], v[212:215], v[148:151], v[68:71]
	v_mfma_f32_16x16x32_bf16 v[64:67], v[212:215], v[156:159], v[64:67]
	s_setprio 0
	s_barrier
; #define PG8_STAGE(bufoff, gbase, voff) do { _Pragma("unroll") for (int _i = 0; _i < 2; ++_i) \
;         __builtin_amdgcn_global_load_lds((const unsigned*)((const char*)(gbase) + (voff)[_i]), (LAS unsigned*)(lds + (bufoff) + ldsw + _i * 8192), 16, 0, 0); } while (0)
; #define PG8_LDA(dst, b, h) do { _Pragma("unroll") for (int m = 0; m < 4; ++m) _Pragma("unroll") for (int k = 0; k < 2; ++k) dst[m][k] = *(const LAS bf16x8*)(lds + PG8_SA(b, h) + aoff + m * 2048 + k * 1024); } while (0)
; #define PG8_MMA(ai, bj, At, Bt) do { __builtin_amdgcn_s_setprio(1); _Pragma("unroll") for (int m = 0; m < 4; ++m) _Pragma("unroll") for (int n = 0; n < 2; ++n) _Pragma("unroll") for (int k = 0; k < 2; ++k) \
;         acc[ai][bj][m][n] = __builtin_amdgcn_mfma_f32_16x16x32_bf16(Bt[n][k], At[m][k], acc[ai][bj][m][n], 0, 0, 0); __builtin_amdgcn_s_setprio(0); } while (0)
; #define PG8_WAIT_V(n) asm volatile("s_waitcnt vmcnt(" #n ")" ::: "memory")
; #define PG8_WAIT_L(n) asm volatile("s_waitcnt lgkmcnt(" #n ")" ::: "memory")
; #define PG8_BAR __builtin_amdgcn_s_barrier()
; #define PG8_SCHED __builtin_amdgcn_sched_barrier(0)
; template <class Epi, class Sched>
; __device__ __forceinline__ void gemm_phase(LAS unsigned char* lds, const int K, const int lda, const int ldb, const Sched& S, const Epi& E) {
;     ...
;             PG8_LDA(At, 1, 1); PG8_STAGE(PG8_SB(1, 0), b3, voffB); PG8_STAGE(PG8_SB(1, 1), b3 + hB, voffB); PG8_STAGE(PG8_SA(1, 0), a3, voffA);
;             PG8_WAIT_V(8); PG8_WAIT_L(0); PG8_BAR; PG8_MMA(1, 0, At, B0); PG8_MMA(1, 1, At, B1); PG8_BAR; PG8_SCHED;
;         }
;         if (wr == 0) PG8_BAR;
	s_add_i32 s34, s52, s36
	v_lshl_add_u64 v[192:193], v[192:193], 0, s[10:11]
	s_mov_b32 m0, s34
	ds_read_b128 v[160:163], v199 offset:49152
	ds_read_b128 v[180:183], v199 offset:50176
	ds_read_b128 v[184:187], v199 offset:51200
	ds_read_b128 v[188:191], v199 offset:52224
	ds_read_b128 v[200:203], v199 offset:53248
	ds_read_b128 v[204:207], v199 offset:54272
	ds_read_b128 v[208:211], v199 offset:55296
	ds_read_b128 v[212:215], v199 offset:56320
	global_load_lds_dwordx4 v[192:193], off
	s_add_i32 m0, s34, 0x2000
	s_add_u32 s30, s30, 0x80080
	v_lshl_add_u64 v[192:193], v[216:217], 0, s[10:11]
	s_addc_u32 s31, s31, 0
	s_add_i32 s34, s53, s36
	global_load_lds_dwordx4 v[192:193], off
	v_lshl_add_u64 v[192:193], s[30:31], 0, v[166:167]
	s_mov_b32 m0, s34
	s_nop 0
	global_load_lds_dwordx4 v[192:193], off
	v_lshl_add_u64 v[192:193], s[30:31], 0, v[170:171]
	s_add_i32 m0, s34, 0x2000
	s_nop 0
	global_load_lds_dwordx4 v[192:193], off
	v_lshl_add_u64 v[192:193], v[218:219], 0, s[10:11]
	s_mov_b32 m0, s41
	s_nop 0
	global_load_lds_dwordx4 v[192:193], off
	v_lshl_add_u64 v[192:193], v[220:221], 0, s[10:11]
	s_mov_b32 m0, s42
	s_nop 0
	global_load_lds_dwordx4 v[192:193], off
	s_waitcnt vmcnt(8)
	s_waitcnt lgkmcnt(0)
	s_barrier
	s_setprio 1
	s_waitcnt lgkmcnt(0)
	v_mfma_f32_16x16x32_bf16 v[60:63], v[160:163], v[128:131], v[60:63]
	v_mfma_f32_16x16x32_bf16 v[56:59], v[160:163], v[136:139], v[56:59]
	v_mfma_f32_16x16x32_bf16 v[48:51], v[184:187], v[128:131], v[48:51]
	v_mfma_f32_16x16x32_bf16 v[40:43], v[184:187], v[136:139], v[40:43]
	v_mfma_f32_16x16x32_bf16 v[32:35], v[200:203], v[128:131], v[32:35]
	v_mfma_f32_16x16x32_bf16 v[24:27], v[200:203], v[136:139], v[24:27]
	v_mfma_f32_16x16x32_bf16 v[16:19], v[208:211], v[128:131], v[16:19]
	v_mfma_f32_16x16x32_bf16 v[8:11], v[208:211], v[136:139], v[8:11]
	v_mfma_f32_16x16x32_bf16 v[60:63], v[180:183], v[132:135], v[60:63]
	v_mfma_f32_16x16x32_bf16 v[56:59], v[180:183], v[140:143], v[56:59]
	v_mfma_f32_16x16x32_bf16 v[48:51], v[188:191], v[132:135], v[48:51]
	v_mfma_f32_16x16x32_bf16 v[40:43], v[188:191], v[140:143], v[40:43]
	v_mfma_f32_16x16x32_bf16 v[32:35], v[204:207], v[132:135], v[32:35]
	v_mfma_f32_16x16x32_bf16 v[24:27], v[204:207], v[140:143], v[24:27]
	v_mfma_f32_16x16x32_bf16 v[16:19], v[212:215], v[132:135], v[16:19]
	v_mfma_f32_16x16x32_bf16 v[8:11], v[212:215], v[140:143], v[8:11]
	v_mfma_f32_16x16x32_bf16 v[52:55], v[160:163], v[144:147], v[52:55]
	v_mfma_f32_16x16x32_bf16 v[44:47], v[160:163], v[152:155], v[44:47]
	v_mfma_f32_16x16x32_bf16 v[36:39], v[184:187], v[144:147], v[36:39]
	v_mfma_f32_16x16x32_bf16 v[28:31], v[184:187], v[152:155], v[28:31]
	v_mfma_f32_16x16x32_bf16 v[20:23], v[200:203], v[144:147], v[20:23]
	v_mfma_f32_16x16x32_bf16 v[12:15], v[200:203], v[152:155], v[12:15]
	v_mfma_f32_16x16x32_bf16 v[4:7], v[208:211], v[144:147], v[4:7]
	v_mfma_f32_16x16x32_bf16 v[0:3], v[208:211], v[152:155], v[0:3]
	v_mfma_f32_16x16x32_bf16 v[52:55], v[180:183], v[148:151], v[52:55]
	v_mfma_f32_16x16x32_bf16 v[44:47], v[180:183], v[156:159], v[44:47]
	v_mfma_f32_16x16x32_bf16 v[36:39], v[188:191], v[148:151], v[36:39]
	v_mfma_f32_16x16x32_bf16 v[28:31], v[188:191], v[156:159], v[28:31]
	v_mfma_f32_16x16x32_bf16 v[20:23], v[204:207], v[148:151], v[20:23]
	v_mfma_f32_16x16x32_bf16 v[12:15], v[204:207], v[156:159], v[12:15]
	v_mfma_f32_16x16x32_bf16 v[4:7], v[212:215], v[148:151], v[4:7]
	v_mfma_f32_16x16x32_bf16 v[0:3], v[212:215], v[156:159], v[0:3]
	s_setprio 0
	s_barrier
	s_add_i32 s51, s51, 2
	s_add_u32 s49, s49, 0x100
	s_addc_u32 s50, s50, 0
	s_add_u32 s28, s28, 0x100
	s_addc_u32 s29, s29, 0
	s_cmp_gt_u32 s51, 29
	s_cbranch_scc0 .LBB0_1625
	s_and_b64 vcc, exec, s[14:15]
	s_cbranch_vccz .LBB0_1628
	s_barrier
